# window units process two adjacent query tiles per wave; retention intra units: both tiles of a wave share one staged K image and the per-pass state and value pieces (half the staging and barriers)
# speedup vs baseline: 1.2345x; 1.0095x over previous
.Lw_lut:
	v_max_i32_e32 v41, 0, v40
	v_min_i32_e32 v41, 0x3ff, v41
	v_cvt_f32_u32_e32 v42, v41
	v_mul_f32_e32 v42, 0x3d800000, v42
	v_log_f32_e32 v42, v42
	s_nop 0
	v_mul_f32_e32 v42, 0x40124925, v42
	v_cvt_i32_f32_e32 v42, v42
	v_med3_i32 v42, v42, 0, 15
	v_add_u32_e32 v42, 16, v42
	v_cmp_gt_u32_e32 vcc, 16, v41
	s_nop 1
	v_cndmask_b32_e32 v42, v42, v41, vcc
	v_lshl_add_u32 v42, v42, 4, s20
	v_lshl_add_u32 v42, v42, 2, s57
	ds_read_b32 v42, v42
	v_cmp_gt_u32_e32 vcc, 0x200, v40
	s_waitcnt lgkmcnt(0)
	v_mul_f32_e32 v42, 0x3fb8aa3b, v42
	v_cndmask_b32_e32 v42, v46, v42, vcc
	ds_write_b32 v47, v42
	v_add_u32_e32 v40, 64, v40
	v_add_u32_e32 v47, 0x100, v47
	s_add_i32 s0, s0, -1
	s_cmp_lg_u32 s0, 0
	s_cbranch_scc1 .Lw_lut
	s_waitcnt lgkmcnt(0)
	s_mov_b32 s6, 0
	s_lshl_b32 s8, s7, 4
	s_add_i32 s0, s8, 0xfffffe01
	s_max_i32 s0, s0, 0
	s_lshr_b32 s0, s0, 4
	s_and_b32 s11, s0, -2
	s_sub_i32 s0, s7, s11
	s_lshr_b32 s0, s0, 1
	s_add_i32 s9, s0, 1
	s_mov_b32 s10, 0
	s_mov_b32 s3, s7
	s_mov_b32 s29, s9
	s_mov_b32 s21, 0
	s_mov_b32 s38, 0
	s_lshl_b32 s0, s8, 11
	s_add_u32 s62, s34, s0
	s_addc_u32 s63, s35, 0
	v_lshlrev_b32_e32 v40, 11, v53
	v_lshl_add_u32 v40, v55, 1, v40
	v_add_u32_e32 v40, s39, v40
	global_load_dwordx4 v[16:19], v40, s[62:63]
	global_load_dwordx4 v[20:23], v40, s[62:63] offset:64
	s_add_u32 s62, s62, 0x8000
	s_addc_u32 s63, s63, 0
	global_load_dwordx4 v[120:123], v40, s[62:63]
	global_load_dwordx4 v[124:127], v40, s[62:63] offset:64
	s_lshl_b32 s0, s11, 4
	s_sub_i32 s0, s8, s0
	s_add_i32 s0, s0, 13
	s_lshl_b32 s0, s0, 2
	s_add_i32 s0, s0, s28
	v_sub_u32_e32 v50, v53, v54
	v_lshl_add_u32 v50, v50, 2, s0
	v_readfirstlane_b32 s1, v143
	s_and_b32 s0, s1, 3
	s_lshl_b32 s0, s0, 10
	s_cmp_lt_u32 s1, 4
	s_cselect_b32 s2, s12, s14
	s_cselect_b32 s16, s13, s15
	s_add_u32 s12, s2, s0
	s_addc_u32 s13, s16, 0
	s_lshl_b32 s23, s1, 10
	s_add_i32 s23, s23, 0x8000
	v_and_b32_e32 v96, 63, v208
	v_lshlrev_b32_e32 v96, 4, v96
	v_add_u32_e32 v97, 0x8000, v96
	s_barrier
	s_mov_b32 s18, 0
	s_mov_b32 s2, 0
	s_lshl_b32 s0, s2, 13
	s_add_i32 m0, s0, s23
	s_lshl_b32 s0, s11, 11
	s_add_u32 s16, s12, s0
	s_addc_u32 s17, s13, 0
	global_load_lds_dwordx4 v96, s[16:17]
	s_add_i32 s0, s21, 1
	s_cmp_lt_i32 s0, s29
	s_cbranch_scc1 .Lw_pfsamee1
	s_cmp_ge_i32 s38, 3
	s_cbranch_scc1 .Lw_pfgoe1
	s_add_i32 s38, s38, 1
	s_add_i32 s3, s3, 2
	s_lshl_b32 s1, s3, 4
	s_add_i32 s0, s1, 0xfffffe01
	s_max_i32 s0, s0, 0
	s_lshr_b32 s0, s0, 4
	s_and_b32 s11, s0, -2
	s_sub_i32 s0, s3, s11
	s_lshr_b32 s0, s0, 1
	s_add_i32 s29, s0, 1
	s_mov_b32 s21, 0
	s_branch .Lw_pfgoe1

.Lw_pfgoe1:
	s_mov_b32 s2, 1
	s_lshl_b32 s0, s2, 13
	s_add_i32 m0, s0, s23
	s_lshl_b32 s0, s11, 11
	s_add_u32 s16, s12, s0
	s_addc_u32 s17, s13, 0
	global_load_lds_dwordx4 v96, s[16:17]
	s_add_i32 s0, s21, 1
	s_cmp_lt_i32 s0, s29
	s_cbranch_scc1 .Lw_pfsamee2
	s_cmp_ge_i32 s38, 3
	s_cbranch_scc1 .Lw_pfgoe2
	s_add_i32 s38, s38, 1
	s_add_i32 s3, s3, 2
	s_lshl_b32 s1, s3, 4
	s_add_i32 s0, s1, 0xfffffe01
	s_max_i32 s0, s0, 0
	s_lshr_b32 s0, s0, 4
	s_and_b32 s11, s0, -2
	s_sub_i32 s0, s3, s11
	s_lshr_b32 s0, s0, 1
	s_add_i32 s29, s0, 1
	s_mov_b32 s21, 0
	s_branch .Lw_pfgoe2

.Lw_pfgoe2:
	s_mov_b32 s2, 2
	s_lshl_b32 s0, s2, 13
	s_add_i32 m0, s0, s23
	s_lshl_b32 s0, s11, 11
	s_add_u32 s16, s12, s0
	s_addc_u32 s17, s13, 0
	global_load_lds_dwordx4 v96, s[16:17]
	s_add_i32 s0, s21, 1
	s_cmp_lt_i32 s0, s29
	s_cbranch_scc1 .Lw_pfsamee3
	s_cmp_ge_i32 s38, 3
	s_cbranch_scc1 .Lw_pfgoe3
	s_add_i32 s38, s38, 1
	s_add_i32 s3, s3, 2
	s_lshl_b32 s1, s3, 4
	s_add_i32 s0, s1, 0xfffffe01
	s_max_i32 s0, s0, 0
	s_lshr_b32 s0, s0, 4
	s_and_b32 s11, s0, -2
	s_sub_i32 s0, s3, s11
	s_lshr_b32 s0, s0, 1
	s_add_i32 s29, s0, 1
	s_mov_b32 s21, 0
	s_branch .Lw_pfgoe3

.Lw_pfgoe3:
	s_mov_b32 s2, 3
	s_lshl_b32 s0, s2, 13
	s_add_i32 m0, s0, s23
	s_lshl_b32 s0, s11, 11
	s_add_u32 s16, s12, s0
	s_addc_u32 s17, s13, 0
	global_load_lds_dwordx4 v96, s[16:17]
	s_add_i32 s0, s21, 1
	s_cmp_lt_i32 s0, s29
	s_cbranch_scc1 .Lw_pfsamee4
	s_cmp_ge_i32 s38, 3
	s_cbranch_scc1 .Lw_pfgoe4
	s_add_i32 s38, s38, 1
	s_add_i32 s3, s3, 2
	s_lshl_b32 s1, s3, 4
	s_add_i32 s0, s1, 0xfffffe01
	s_max_i32 s0, s0, 0
	s_lshr_b32 s0, s0, 4
	s_and_b32 s11, s0, -2
	s_sub_i32 s0, s3, s11
	s_lshr_b32 s0, s0, 1
	s_add_i32 s29, s0, 1
	s_mov_b32 s21, 0
	s_branch .Lw_pfgoe4

.Lw_pfgoe4:
	s_mov_b32 s2, 4
	s_lshl_b32 s0, s2, 13
	s_add_i32 m0, s0, s23
	s_lshl_b32 s0, s11, 11
	s_add_u32 s16, s12, s0
	s_addc_u32 s17, s13, 0
	global_load_lds_dwordx4 v96, s[16:17]
	s_add_i32 s0, s21, 1
	s_cmp_lt_i32 s0, s29
	s_cbranch_scc1 .Lw_pfsamee5
	s_cmp_ge_i32 s38, 3
	s_cbranch_scc1 .Lw_pfgoe5
	s_add_i32 s38, s38, 1
	s_add_i32 s3, s3, 2
	s_lshl_b32 s1, s3, 4
	s_add_i32 s0, s1, 0xfffffe01
	s_max_i32 s0, s0, 0
	s_lshr_b32 s0, s0, 4
	s_and_b32 s11, s0, -2
	s_sub_i32 s0, s3, s11
	s_lshr_b32 s0, s0, 1
	s_add_i32 s29, s0, 1
	s_mov_b32 s21, 0
	s_branch .Lw_pfgoe5

.Lw_pfgoe5:
	s_mov_b32 s2, 5
	s_lshl_b32 s0, s2, 13
	s_add_i32 m0, s0, s23
	s_lshl_b32 s0, s11, 11
	s_add_u32 s16, s12, s0
	s_addc_u32 s17, s13, 0
	global_load_lds_dwordx4 v96, s[16:17]
	s_add_i32 s0, s21, 1
	s_cmp_lt_i32 s0, s29
	s_cbranch_scc1 .Lw_pfsamee6
	s_cmp_ge_i32 s38, 3
	s_cbranch_scc1 .Lw_pfgoe6
	s_add_i32 s38, s38, 1
	s_add_i32 s3, s3, 2
	s_lshl_b32 s1, s3, 4
	s_add_i32 s0, s1, 0xfffffe01
	s_max_i32 s0, s0, 0
	s_lshr_b32 s0, s0, 4
	s_and_b32 s11, s0, -2
	s_sub_i32 s0, s3, s11
	s_lshr_b32 s0, s0, 1
	s_add_i32 s29, s0, 1
	s_mov_b32 s21, 0
	s_branch .Lw_pfgoe6

.Lw_pfgoe6:
	s_mov_b32 s2, 6
	s_lshl_b32 s0, s2, 13
	s_add_i32 m0, s0, s23
	s_lshl_b32 s0, s11, 11
	s_add_u32 s16, s12, s0
	s_addc_u32 s17, s13, 0
	global_load_lds_dwordx4 v96, s[16:17]
	v_mov_b32_e32 v48, 0xefa18f08
	v_mov_b32_e32 v49, 0
	v_mov_b32_e32 v160, 0xefa18f08
	v_mov_b32_e32 v161, 0
	v_mov_b32_e32 v0, 0
	v_mov_b32_e32 v1, 0
	v_mov_b32_e32 v2, 0
	v_mov_b32_e32 v3, 0
	v_mov_b32_e32 v4, 0
	v_mov_b32_e32 v5, 0
	v_mov_b32_e32 v6, 0
	v_mov_b32_e32 v7, 0
	v_mov_b32_e32 v8, 0
	v_mov_b32_e32 v9, 0
	v_mov_b32_e32 v10, 0
	v_mov_b32_e32 v11, 0
	v_mov_b32_e32 v12, 0
	v_mov_b32_e32 v13, 0
	v_mov_b32_e32 v14, 0
	v_mov_b32_e32 v15, 0
	v_mov_b32_e32 v104, 0
	v_mov_b32_e32 v105, 0
	v_mov_b32_e32 v106, 0
	v_mov_b32_e32 v107, 0
	v_mov_b32_e32 v108, 0
	v_mov_b32_e32 v109, 0
	v_mov_b32_e32 v110, 0
	v_mov_b32_e32 v111, 0
	v_mov_b32_e32 v112, 0
	v_mov_b32_e32 v113, 0
	v_mov_b32_e32 v114, 0
	v_mov_b32_e32 v115, 0
	v_mov_b32_e32 v116, 0
	v_mov_b32_e32 v117, 0
	v_mov_b32_e32 v118, 0
	v_mov_b32_e32 v119, 0
.Lw_step:
	s_cmp_lg_u32 s10, 0
	s_cbranch_scc1 .Lw_nofirst
	s_lshl_b32 s0, s8, 7
	s_add_u32 s24, s36, s0
	s_addc_u32 s25, s37, 0
	v_lshlrev_b32_e32 v40, 7, v53
	v_add_u32_e32 v40, s56, v40
	global_load_ushort v52, v40, s[24:25]
	global_load_ushort v162, v40, s[24:25] offset:2048
	s_add_i32 s0, s6, 1
	s_cmp_lt_i32 s0, 4
	s_cselect_b32 s0, 32, 0
	s_add_i32 s0, s8, s0
	s_lshl_b32 s0, s0, 11
	s_add_u32 s62, s34, s0
	s_addc_u32 s63, s35, 0
	v_lshlrev_b32_e32 v40, 11, v53
	v_lshl_add_u32 v40, v55, 1, v40
	v_add_u32_e32 v40, s39, v40
	global_load_dwordx4 v[24:27], v40, s[62:63]
	global_load_dwordx4 v[28:31], v40, s[62:63] offset:64
	s_add_u32 s62, s62, 0x8000
	s_addc_u32 s63, s63, 0
	global_load_dwordx4 v[128:131], v40, s[62:63]
	global_load_dwordx4 v[132:135], v40, s[62:63] offset:64
.Lw_nofirst:
	s_waitcnt vmcnt(6) lgkmcnt(0)
	s_barrier
	s_add_i32 s0, s21, 1
	s_cmp_lt_i32 s0, s29
	s_cbranch_scc1 .Lw_pfsames
	s_cmp_ge_i32 s38, 3
	s_cbranch_scc1 .Lw_pfgos
	s_add_i32 s38, s38, 1
	s_add_i32 s3, s3, 2
	s_lshl_b32 s1, s3, 4
	s_add_i32 s0, s1, 0xfffffe01
	s_max_i32 s0, s0, 0
	s_lshr_b32 s0, s0, 4
	s_and_b32 s11, s0, -2
	s_sub_i32 s0, s3, s11
	s_lshr_b32 s0, s0, 1
	s_add_i32 s29, s0, 1
	s_mov_b32 s21, 0
	s_branch .Lw_pfgos

.Lw_pfgos:
	s_add_i32 s2, s18, 7
	s_and_b32 s2, s2, 7
	s_lshl_b32 s0, s2, 13
	s_add_i32 m0, s0, s23
	s_lshl_b32 s0, s11, 11
	s_add_u32 s16, s12, s0
	s_addc_u32 s17, s13, 0
	global_load_lds_dwordx4 v96, s[16:17]
	s_lshl_b32 s0, s18, 13
	v_add_u32_e32 v40, s0, v97
	ds_read_b128 v[56:59], v40 offset:0
	ds_read_b128 v[60:63], v40 offset:1024
	ds_read_b128 v[68:71], v40 offset:2048
	ds_read_b128 v[72:75], v40 offset:3072
	ds_read_b128 v[76:79], v40 offset:4096
	ds_read_b128 v[80:83], v40 offset:5120
	ds_read_b128 v[84:87], v40 offset:6144
	ds_read_b128 v[92:95], v40 offset:7168
	s_add_i32 s18, s18, 1
	s_and_b32 s18, s18, 7
	s_waitcnt lgkmcnt(4)
	v_mfma_f32_16x16x32_bf16 v[32:35], v[56:59], v[16:19], 0
	v_mfma_f32_16x16x32_bf16 v[36:39], v[68:71], v[16:19], 0
	v_mfma_f32_16x16x32_bf16 v[32:35], v[60:63], v[20:23], v[32:35]
	v_mfma_f32_16x16x32_bf16 v[36:39], v[72:75], v[20:23], v[36:39]
	v_mfma_f32_16x16x32_bf16 v[144:147], v[56:59], v[120:123], 0
	v_mfma_f32_16x16x32_bf16 v[148:151], v[68:71], v[120:123], 0
	v_mfma_f32_16x16x32_bf16 v[144:147], v[60:63], v[124:127], v[144:147]
	v_mfma_f32_16x16x32_bf16 v[148:151], v[72:75], v[124:127], v[148:151]
	ds_read_b32 v40, v50 offset:76
	ds_read_b32 v41, v50 offset:72
	ds_read_b32 v42, v50 offset:68
	ds_read_b32 v43, v50 offset:64
	ds_read_b32 v44, v50 offset:12
	ds_read_b32 v45, v50 offset:8
	ds_read_b32 v46, v50 offset:4
	ds_read_b32 v47, v50 offset:0
	ds_read_b32 v152, v50 offset:140
	ds_read_b32 v153, v50 offset:136
	ds_read_b32 v154, v50 offset:132
	ds_read_b32 v155, v50 offset:128
	ds_read_b32 v156, v50 offset:76
	ds_read_b32 v157, v50 offset:72
	ds_read_b32 v158, v50 offset:68
	ds_read_b32 v159, v50 offset:64
	v_add_u32_e32 v50, 0xffffff80, v50
	s_waitcnt lgkmcnt(0)
	v_pk_fma_f32 v[32:33], v[32:33], s[40:41], v[40:41] op_sel_hi:[1,0,1]
	v_pk_fma_f32 v[34:35], v[34:35], s[40:41], v[42:43] op_sel_hi:[1,0,1]
	v_pk_fma_f32 v[36:37], v[36:37], s[40:41], v[44:45] op_sel_hi:[1,0,1]
	v_pk_fma_f32 v[38:39], v[38:39], s[40:41], v[46:47] op_sel_hi:[1,0,1]
	v_max3_f32 v40, v32, v33, v34
	v_max3_f32 v41, v35, v36, v37
	v_max3_f32 v40, v40, v38, v39
	v_max_f32_e32 v40, v40, v41
	v_mov_b32_e32 v41, v40
	s_nop 1
	v_permlane16_swap_b32_e32 v41, v40
	v_max_f32_e32 v40, v40, v41
	v_mov_b32_e32 v41, v40
	s_nop 1
	v_permlane32_swap_b32_e32 v41, v40
	v_max_f32_e32 v42, v40, v41
	v_cmp_gt_f32_e32 vcc, v42, v48
	s_cbranch_vccz .Lw_norescA
	v_max_f32_e32 v42, v48, v42
	v_sub_f32_e32 v40, v48, v42
	v_exp_f32_e32 v40, v40
	v_mov_b32_e32 v48, v42
	s_nop 0
	v_pk_mul_f32 v[0:1], v[0:1], v[40:41] op_sel_hi:[1,0]
	v_pk_mul_f32 v[2:3], v[2:3], v[40:41] op_sel_hi:[1,0]
	v_pk_mul_f32 v[4:5], v[4:5], v[40:41] op_sel_hi:[1,0]
	v_pk_mul_f32 v[6:7], v[6:7], v[40:41] op_sel_hi:[1,0]
	v_pk_mul_f32 v[8:9], v[8:9], v[40:41] op_sel_hi:[1,0]
	v_pk_mul_f32 v[10:11], v[10:11], v[40:41] op_sel_hi:[1,0]
	v_pk_mul_f32 v[12:13], v[12:13], v[40:41] op_sel_hi:[1,0]
	v_pk_mul_f32 v[14:15], v[14:15], v[40:41] op_sel_hi:[1,0]
	v_mul_f32_e32 v49, v49, v40
.Lw_norescA:
	v_pk_add_f32 v[32:33], v[32:33], v[48:49] op_sel_hi:[1,0] neg_lo:[0,1] neg_hi:[0,1]
	v_pk_add_f32 v[34:35], v[34:35], v[48:49] op_sel_hi:[1,0] neg_lo:[0,1] neg_hi:[0,1]
	v_pk_add_f32 v[36:37], v[36:37], v[48:49] op_sel_hi:[1,0] neg_lo:[0,1] neg_hi:[0,1]
	v_pk_add_f32 v[38:39], v[38:39], v[48:49] op_sel_hi:[1,0] neg_lo:[0,1] neg_hi:[0,1]
	v_exp_f32_e32 v32, v32
	v_exp_f32_e32 v33, v33
	v_exp_f32_e32 v34, v34
	v_exp_f32_e32 v35, v35
	v_exp_f32_e32 v36, v36
	v_exp_f32_e32 v37, v37
	v_exp_f32_e32 v38, v38
	v_exp_f32_e32 v39, v39
	s_nop 0
	v_pk_add_f32 v[40:41], v[32:33], v[34:35]
	v_pk_add_f32 v[40:41], v[40:41], v[36:37]
	v_pk_add_f32 v[40:41], v[40:41], v[38:39]
	v_add_f32_e32 v40, v40, v41
	v_add_f32_e32 v49, v49, v40
	v_cvt_pk_bf16_f32 v32, v32, v33
	v_cvt_pk_bf16_f32 v33, v34, v35
	v_cvt_pk_bf16_f32 v34, v36, v37
	v_cvt_pk_bf16_f32 v35, v38, v39
	s_nop 1
	v_mfma_f32_16x16x32_bf16 v[0:3], v[76:79], v[32:35], v[0:3]
	v_mfma_f32_16x16x32_bf16 v[4:7], v[80:83], v[32:35], v[4:7]
	v_mfma_f32_16x16x32_bf16 v[8:11], v[84:87], v[32:35], v[8:11]
	v_mfma_f32_16x16x32_bf16 v[12:15], v[92:95], v[32:35], v[12:15]
	v_pk_fma_f32 v[144:145], v[144:145], s[40:41], v[152:153] op_sel_hi:[1,0,1]
	v_pk_fma_f32 v[146:147], v[146:147], s[40:41], v[154:155] op_sel_hi:[1,0,1]
	v_pk_fma_f32 v[148:149], v[148:149], s[40:41], v[156:157] op_sel_hi:[1,0,1]
	v_pk_fma_f32 v[150:151], v[150:151], s[40:41], v[158:159] op_sel_hi:[1,0,1]
	v_max3_f32 v152, v144, v145, v146
	v_max3_f32 v153, v147, v148, v149
	v_max3_f32 v152, v152, v150, v151
	v_max_f32_e32 v152, v152, v153
	v_mov_b32_e32 v153, v152
	s_nop 1
	v_permlane16_swap_b32_e32 v153, v152
	v_max_f32_e32 v152, v152, v153
	v_mov_b32_e32 v153, v152
	s_nop 1
	v_permlane32_swap_b32_e32 v153, v152
	v_max_f32_e32 v154, v152, v153
	v_cmp_gt_f32_e32 vcc, v154, v160
	s_cbranch_vccz .Lw_norescB
	v_max_f32_e32 v154, v160, v154
	v_sub_f32_e32 v152, v160, v154
	v_exp_f32_e32 v152, v152
	v_mov_b32_e32 v160, v154
	s_nop 0
	v_pk_mul_f32 v[104:105], v[104:105], v[152:153] op_sel_hi:[1,0]
	v_pk_mul_f32 v[106:107], v[106:107], v[152:153] op_sel_hi:[1,0]
	v_pk_mul_f32 v[108:109], v[108:109], v[152:153] op_sel_hi:[1,0]
	v_pk_mul_f32 v[110:111], v[110:111], v[152:153] op_sel_hi:[1,0]
	v_pk_mul_f32 v[112:113], v[112:113], v[152:153] op_sel_hi:[1,0]
	v_pk_mul_f32 v[114:115], v[114:115], v[152:153] op_sel_hi:[1,0]
	v_pk_mul_f32 v[116:117], v[116:117], v[152:153] op_sel_hi:[1,0]
	v_pk_mul_f32 v[118:119], v[118:119], v[152:153] op_sel_hi:[1,0]
	v_mul_f32_e32 v161, v161, v152
.Lw_norescB:
	v_pk_add_f32 v[144:145], v[144:145], v[160:161] op_sel_hi:[1,0] neg_lo:[0,1] neg_hi:[0,1]
	v_pk_add_f32 v[146:147], v[146:147], v[160:161] op_sel_hi:[1,0] neg_lo:[0,1] neg_hi:[0,1]
	v_pk_add_f32 v[148:149], v[148:149], v[160:161] op_sel_hi:[1,0] neg_lo:[0,1] neg_hi:[0,1]
	v_pk_add_f32 v[150:151], v[150:151], v[160:161] op_sel_hi:[1,0] neg_lo:[0,1] neg_hi:[0,1]
	v_exp_f32_e32 v144, v144
	v_exp_f32_e32 v145, v145
	v_exp_f32_e32 v146, v146
	v_exp_f32_e32 v147, v147
	v_exp_f32_e32 v148, v148
	v_exp_f32_e32 v149, v149
	v_exp_f32_e32 v150, v150
	v_exp_f32_e32 v151, v151
	s_nop 0
	v_pk_add_f32 v[152:153], v[144:145], v[146:147]
	v_pk_add_f32 v[152:153], v[152:153], v[148:149]
	v_pk_add_f32 v[152:153], v[152:153], v[150:151]
	v_add_f32_e32 v152, v152, v153
	v_add_f32_e32 v161, v161, v152
	v_cvt_pk_bf16_f32 v144, v144, v145
	v_cvt_pk_bf16_f32 v145, v146, v147
	v_cvt_pk_bf16_f32 v146, v148, v149
	v_cvt_pk_bf16_f32 v147, v150, v151
	s_nop 1
	v_mfma_f32_16x16x32_bf16 v[104:107], v[76:79], v[144:147], v[104:107]
	v_mfma_f32_16x16x32_bf16 v[108:111], v[80:83], v[144:147], v[108:111]
	v_mfma_f32_16x16x32_bf16 v[112:115], v[84:87], v[144:147], v[112:115]
	v_mfma_f32_16x16x32_bf16 v[116:119], v[92:95], v[144:147], v[116:119]
	s_add_i32 s10, s10, 1
	s_cmp_ge_i32 s10, s9
	s_cbranch_scc0 .Lw_step
	s_cmp_ge_i32 s9, 8
	s_cbranch_scc1 .Lw_ep_go
	s_waitcnt vmcnt(0)
.Lw_ep_go:
	s_nop 7
	ds_bpermute_b32 v40, v64, v49
	s_waitcnt lgkmcnt(0)
	v_add_f32_e32 v49, v49, v40
	ds_bpermute_b32 v40, v66, v49
	v_lshlrev_b32_e32 v42, 16, v52
	v_mul_f32_e32 v42, 0xbfb8aa3b, v42
	v_exp_f32_e32 v42, v42
	s_waitcnt lgkmcnt(0)
	v_add_f32_e32 v49, v49, v40
	v_add_f32_e32 v42, 1.0, v42
	v_mul_f32_e32 v42, v42, v49
	v_rcp_f32_e32 v42, v42
	s_nop 0
	v_pk_mul_f32 v[0:1], v[0:1], v[42:43] op_sel_hi:[1,0]
	v_pk_mul_f32 v[2:3], v[2:3], v[42:43] op_sel_hi:[1,0]
	v_pk_mul_f32 v[4:5], v[4:5], v[42:43] op_sel_hi:[1,0]
	v_pk_mul_f32 v[6:7], v[6:7], v[42:43] op_sel_hi:[1,0]
	v_pk_mul_f32 v[8:9], v[8:9], v[42:43] op_sel_hi:[1,0]
	v_pk_mul_f32 v[10:11], v[10:11], v[42:43] op_sel_hi:[1,0]
	v_pk_mul_f32 v[12:13], v[12:13], v[42:43] op_sel_hi:[1,0]
	v_pk_mul_f32 v[14:15], v[14:15], v[42:43] op_sel_hi:[1,0]
	s_add_i32 s0, s8, 0
	s_mul_i32 s0, s0, 0x1800
	s_add_i32 s0, s0, 0x1000
	s_add_u32 s24, s30, s0
	s_addc_u32 s25, s31, 0
	v_mul_u32_u24_e32 v44, 0x1800, v53
	v_add_u32_e32 v44, v44, v55
	v_add_u32_e32 v44, s39, v44
	v_cvt_pk_bf16_f32 v0, v0, v1
	v_cvt_pk_bf16_f32 v1, v2, v3
	global_store_dwordx2 v44, v[0:1], s[24:25] offset:0
	v_cvt_pk_bf16_f32 v4, v4, v5
	v_cvt_pk_bf16_f32 v5, v6, v7
	global_store_dwordx2 v44, v[4:5], s[24:25] offset:32
	v_cvt_pk_bf16_f32 v8, v8, v9
	v_cvt_pk_bf16_f32 v9, v10, v11
	global_store_dwordx2 v44, v[8:9], s[24:25] offset:64
	v_cvt_pk_bf16_f32 v12, v12, v13
	v_cvt_pk_bf16_f32 v13, v14, v15
	global_store_dwordx2 v44, v[12:13], s[24:25] offset:96
	ds_bpermute_b32 v40, v64, v161
	s_waitcnt lgkmcnt(0)
	v_add_f32_e32 v161, v161, v40
	ds_bpermute_b32 v40, v66, v161
	v_lshlrev_b32_e32 v42, 16, v162
	v_mul_f32_e32 v42, 0xbfb8aa3b, v42
	v_exp_f32_e32 v42, v42
	s_waitcnt lgkmcnt(0)
	v_add_f32_e32 v161, v161, v40
	v_add_f32_e32 v42, 1.0, v42
	v_mul_f32_e32 v42, v42, v161
	v_rcp_f32_e32 v42, v42
	s_nop 0
	v_pk_mul_f32 v[104:105], v[104:105], v[42:43] op_sel_hi:[1,0]
	v_pk_mul_f32 v[106:107], v[106:107], v[42:43] op_sel_hi:[1,0]
	v_pk_mul_f32 v[108:109], v[108:109], v[42:43] op_sel_hi:[1,0]
	v_pk_mul_f32 v[110:111], v[110:111], v[42:43] op_sel_hi:[1,0]
	v_pk_mul_f32 v[112:113], v[112:113], v[42:43] op_sel_hi:[1,0]
	v_pk_mul_f32 v[114:115], v[114:115], v[42:43] op_sel_hi:[1,0]
	v_pk_mul_f32 v[116:117], v[116:117], v[42:43] op_sel_hi:[1,0]
	v_pk_mul_f32 v[118:119], v[118:119], v[42:43] op_sel_hi:[1,0]
	s_add_i32 s0, s8, 16
	s_mul_i32 s0, s0, 0x1800
	s_add_i32 s0, s0, 0x1000
	s_add_u32 s24, s30, s0
	s_addc_u32 s25, s31, 0
	v_mul_u32_u24_e32 v44, 0x1800, v53
	v_add_u32_e32 v44, v44, v55
	v_add_u32_e32 v44, s39, v44
	v_cvt_pk_bf16_f32 v104, v104, v105
	v_cvt_pk_bf16_f32 v105, v106, v107
	global_store_dwordx2 v44, v[104:105], s[24:25] offset:0
	v_cvt_pk_bf16_f32 v108, v108, v109
	v_cvt_pk_bf16_f32 v109, v110, v111
	global_store_dwordx2 v44, v[108:109], s[24:25] offset:32
	v_cvt_pk_bf16_f32 v112, v112, v113
	v_cvt_pk_bf16_f32 v113, v114, v115
	global_store_dwordx2 v44, v[112:113], s[24:25] offset:64
	v_cvt_pk_bf16_f32 v116, v116, v117
	v_cvt_pk_bf16_f32 v117, v118, v119
	global_store_dwordx2 v44, v[116:117], s[24:25] offset:96
	s_add_i32 s6, s6, 1
	s_cmp_ge_i32 s6, 4
	s_cbranch_scc1 .Lw_exit
	s_add_i32 s7, s7, 2
	s_lshl_b32 s8, s7, 4
	s_add_i32 s0, s8, 0xfffffe01
	s_max_i32 s0, s0, 0
	s_lshr_b32 s0, s0, 4
	s_and_b32 s1, s0, -2
	s_sub_i32 s0, s7, s1
	s_lshr_b32 s0, s0, 1
	s_add_i32 s9, s0, 1
	s_mov_b32 s10, 0
	s_lshl_b32 s0, s1, 4
	s_sub_i32 s0, s8, s0
	s_add_i32 s0, s0, 13
	s_lshl_b32 s0, s0, 2
	s_add_i32 s0, s0, s28
	v_sub_u32_e32 v50, v53, v54
	v_lshl_add_u32 v50, v50, 2, s0
	v_mov_b32_e32 v16, v24
	v_mov_b32_e32 v20, v28
	v_mov_b32_e32 v120, v128
	v_mov_b32_e32 v124, v132
	v_mov_b32_e32 v17, v25
	v_mov_b32_e32 v21, v29
	v_mov_b32_e32 v121, v129
	v_mov_b32_e32 v125, v133
	v_mov_b32_e32 v18, v26
	v_mov_b32_e32 v22, v30
	v_mov_b32_e32 v122, v130
	v_mov_b32_e32 v126, v134
	v_mov_b32_e32 v19, v27
	v_mov_b32_e32 v23, v31
	v_mov_b32_e32 v123, v131
	v_mov_b32_e32 v127, v135
	v_mov_b32_e32 v48, 0xefa18f08
	v_mov_b32_e32 v49, 0
	v_mov_b32_e32 v160, 0xefa18f08
	v_mov_b32_e32 v161, 0
	v_mov_b32_e32 v0, 0
	v_mov_b32_e32 v1, 0
	v_mov_b32_e32 v2, 0
	v_mov_b32_e32 v3, 0
	v_mov_b32_e32 v4, 0
	v_mov_b32_e32 v5, 0
	v_mov_b32_e32 v6, 0
	v_mov_b32_e32 v7, 0
	v_mov_b32_e32 v8, 0
	v_mov_b32_e32 v9, 0
	v_mov_b32_e32 v10, 0
	v_mov_b32_e32 v11, 0
	v_mov_b32_e32 v12, 0
	v_mov_b32_e32 v13, 0
	v_mov_b32_e32 v14, 0
	v_mov_b32_e32 v15, 0
	v_mov_b32_e32 v104, 0
	v_mov_b32_e32 v105, 0
	v_mov_b32_e32 v106, 0
	v_mov_b32_e32 v107, 0
	v_mov_b32_e32 v108, 0
	v_mov_b32_e32 v109, 0
	v_mov_b32_e32 v110, 0
	v_mov_b32_e32 v111, 0
	v_mov_b32_e32 v112, 0
	v_mov_b32_e32 v113, 0
	v_mov_b32_e32 v114, 0
	v_mov_b32_e32 v115, 0
	v_mov_b32_e32 v116, 0
	v_mov_b32_e32 v117, 0
	v_mov_b32_e32 v118, 0
	v_mov_b32_e32 v119, 0
	s_branch .Lw_step

.LBB0_698:
	s_andn2_b64 vcc, exec, s[0:1]
	s_cbranch_vccnz .LBB0_992
	v_readlane_b32 s0, v254, 5
	v_readlane_b32 s1, v254, 6
	s_load_dwordx4 s[40:43], s[0:1], 0xa0
	s_load_dword s2, s[0:1], 0xb0
	v_mov_b32_e32 v0, v208
	s_waitcnt lgkmcnt(0)
	s_mov_b64 s[26:27], s[42:43]
	v_writelane_b32 v254, s2, 46
	v_ashrrev_i32_e32 v220, 6, v0
	v_readlane_b32 s2, v254, 0
	s_add_u32 s24, s26, 0x6d00000
	s_addc_u32 s25, s27, 0
	v_mov_b32_e32 v0, v208
	s_cmpk_gt_i32 s2, 0xff
	v_writelane_b32 v254, s2, 47
	s_cbranch_scc1 .LBB0_748
	s_cmpk_lg_i32 s46, 0x100
	s_cbranch_scc1 .Lintra_orig
	v_readlane_b32 s2, v254, 47
	v_readfirstlane_b32 s3, v220
	s_load_dwordx2 s[28:29], s[0:1], 0x48
	v_readlane_b32 s6, v254, 39
	v_readlane_b32 s7, v254, 40
	s_lshr_b32 s4, s2, 6
	s_and_b32 s5, s2, 63
	v_and_b32_e32 v221, 15, v208
	v_bfe_u32 v222, v208, 4, 2
	v_lshlrev_b32_e32 v200, 6, v221
	v_lshl_add_u32 v200, v222, 4, v200
	v_mul_u32_u24_e32 v204, 0x1800, v221
	v_lshl_add_u32 v204, v222, 3, v204
	v_lshlrev_b32_e32 v205, 12, v221
	v_lshl_add_u32 v205, v222, 3, v205
	v_lshlrev_b32_e32 v206, 4, v222
	v_lshlrev_b32_e32 v223, 2, v222
	v_sub_u32_e32 v201, v221, v223
	v_mov_b32_e32 v231, v201
	v_and_b32_e32 v207, 63, v208
	v_lshlrev_b32_e32 v207, 4, v207
	v_add_u32_e32 v230, 0x10000, v207
	s_lshl_b32 s11, s3, 13
	s_lshl_b32 s0, s4, 23
	s_add_i32 s1, s0, 0xcd00000
	s_add_u32 s12, s26, s1
	s_addc_u32 s13, s27, 0
	s_add_i32 s1, s0, 0xed00000
	s_add_u32 s14, s26, s1
	s_addc_u32 s15, s27, 0
	s_lshl_b32 s0, s5, 17
	s_add_u32 s14, s14, s0
	s_addc_u32 s15, s15, 0
	s_lshl_b32 s0, s4, 24
	s_lshl_b32 s1, s5, 18
	s_add_i32 s0, s0, s1
	s_add_i32 s0, s0, 0x12d00000
	s_add_u32 s16, s26, s0
	s_addc_u32 s17, s27, 0
	s_lshl_b32 s0, s4, 6
	s_add_i32 s0, s0, s5
	s_lshl_b32 s0, s0, 18
	s_add_i32 s0, s0, 0x2d00000
	s_add_u32 s18, s26, s0
	s_addc_u32 s19, s27, 0
	s_lshl_b32 s0, s4, 10
	s_add_u32 s20, s24, s0
	s_addc_u32 s21, s25, 0
	s_add_i32 s1, s0, 0x16d00000
	s_add_u32 s22, s26, s1
	s_addc_u32 s23, s27, 0
	s_waitcnt lgkmcnt(0)
	s_add_u32 s28, s28, s6
	s_addc_u32 s29, s29, s7
	s_lshl_b32 s0, s4, 11
	s_add_u32 s28, s28, s0
	s_addc_u32 s29, s29, 0
	s_sub_i32 s1, 15, s3
	s_lshl_b32 s0, s5, 4
	s_add_i32 s8, s0, s3
	s_add_i32 s9, s0, s1
	s_lshr_b32 s6, s3, 1
	s_add_i32 s6, s6, 1
	s_lshr_b32 s7, s1, 1
	s_add_i32 s7, s7, 1
	s_lshl_b32 s0, s3, 4
	v_add_u32_e32 v201, s0, v231
	s_lshl_b32 s0, s1, 4
	v_add_u32_e32 v244, s0, v231
	s_lshl_b32 s0, s8, 13
	s_add_u32 s30, s12, s0
	s_addc_u32 s31, s13, 0
	global_load_dwordx4 v[0:3], v200, s[30:31] offset:0
	global_load_dwordx4 v[4:7], v200, s[30:31] offset:1024
	global_load_dwordx4 v[8:11], v200, s[30:31] offset:2048
	global_load_dwordx4 v[12:15], v200, s[30:31] offset:3072
	s_add_u32 s30, s30, 0x1000
	s_addc_u32 s31, s31, 0
	global_load_dwordx4 v[16:19], v200, s[30:31] offset:0
	global_load_dwordx4 v[20:23], v200, s[30:31] offset:1024
	global_load_dwordx4 v[24:27], v200, s[30:31] offset:2048
	global_load_dwordx4 v[28:31], v200, s[30:31] offset:3072
	s_lshl_b32 s0, s9, 13
	s_add_u32 s30, s12, s0
	s_addc_u32 s31, s13, 0
	global_load_dwordx4 v[168:171], v200, s[30:31] offset:0
	global_load_dwordx4 v[172:175], v200, s[30:31] offset:1024
	global_load_dwordx4 v[176:179], v200, s[30:31] offset:2048
	global_load_dwordx4 v[180:183], v200, s[30:31] offset:3072
	s_add_u32 s30, s30, 0x1000
	s_addc_u32 s31, s31, 0
	global_load_dwordx4 v[184:187], v200, s[30:31] offset:0
	global_load_dwordx4 v[188:191], v200, s[30:31] offset:1024
	global_load_dwordx4 v[192:195], v200, s[30:31] offset:2048
	global_load_dwordx4 v[196:199], v200, s[30:31] offset:3072
	s_lshl_b32 s8, s8, 4
	s_lshl_b32 s9, s9, 4
	s_lshl_b32 s0, s3, 14
	s_add_u32 s34, s14, s0
	s_addc_u32 s35, s15, 0
	s_add_i32 m0, s0, 0
	s_nop 0
	global_load_lds_dwordx4 v200, s[34:35]
	s_add_i32 m0, s0, 1024
	s_add_u32 s34, s34, 0x400
	s_addc_u32 s35, s35, 0
	global_load_lds_dwordx4 v200, s[34:35]
	s_add_i32 m0, s0, 2048
	s_add_u32 s34, s34, 0x400
	s_addc_u32 s35, s35, 0
	global_load_lds_dwordx4 v200, s[34:35]
	s_add_i32 m0, s0, 3072
	s_add_u32 s34, s34, 0x400
	s_addc_u32 s35, s35, 0
	global_load_lds_dwordx4 v200, s[34:35]
	s_add_i32 m0, s0, 4096
	s_add_u32 s34, s34, 0x400
	s_addc_u32 s35, s35, 0
	global_load_lds_dwordx4 v200, s[34:35]
	s_add_i32 m0, s0, 5120
	s_add_u32 s34, s34, 0x400
	s_addc_u32 s35, s35, 0
	global_load_lds_dwordx4 v200, s[34:35]
	s_add_i32 m0, s0, 6144
	s_add_u32 s34, s34, 0x400
	s_addc_u32 s35, s35, 0
	global_load_lds_dwordx4 v200, s[34:35]
	s_add_i32 m0, s0, 7168
	s_add_u32 s34, s34, 0x400
	s_addc_u32 s35, s35, 0
	global_load_lds_dwordx4 v200, s[34:35]
	s_add_i32 m0, s0, 8192
	s_add_u32 s34, s34, 0x400
	s_addc_u32 s35, s35, 0
	global_load_lds_dwordx4 v200, s[34:35]
	s_add_i32 m0, s0, 9216
	s_add_u32 s34, s34, 0x400
	s_addc_u32 s35, s35, 0
	global_load_lds_dwordx4 v200, s[34:35]
	s_add_i32 m0, s0, 10240
	s_add_u32 s34, s34, 0x400
	s_addc_u32 s35, s35, 0
	global_load_lds_dwordx4 v200, s[34:35]
	s_add_i32 m0, s0, 11264
	s_add_u32 s34, s34, 0x400
	s_addc_u32 s35, s35, 0
	global_load_lds_dwordx4 v200, s[34:35]
	s_add_i32 m0, s0, 12288
	s_add_u32 s34, s34, 0x400
	s_addc_u32 s35, s35, 0
	global_load_lds_dwordx4 v200, s[34:35]
	s_add_i32 m0, s0, 13312
	s_add_u32 s34, s34, 0x400
	s_addc_u32 s35, s35, 0
	global_load_lds_dwordx4 v200, s[34:35]
	s_add_i32 m0, s0, 14336
	s_add_u32 s34, s34, 0x400
	s_addc_u32 s35, s35, 0
	global_load_lds_dwordx4 v200, s[34:35]
	s_add_i32 m0, s0, 15360
	s_add_u32 s34, s34, 0x400
	s_addc_u32 s35, s35, 0
	global_load_lds_dwordx4 v200, s[34:35]
	s_waitcnt vmcnt(0)
	s_barrier
	ds_read_b128 v[100:103], v207 offset:0
	ds_read_b128 v[104:107], v207 offset:1024
	ds_read_b128 v[108:111], v207 offset:2048
	ds_read_b128 v[112:115], v207 offset:3072
	ds_read_b128 v[116:119], v207 offset:4096
	ds_read_b128 v[120:123], v207 offset:5120
	ds_read_b128 v[124:127], v207 offset:6144
	ds_read_b128 v[128:131], v207 offset:7168
	ds_read_b128 v[132:135], v207 offset:8192
	ds_read_b128 v[136:139], v207 offset:9216
	ds_read_b128 v[144:147], v207 offset:10240
	ds_read_b128 v[148:151], v207 offset:11264
	ds_read_b128 v[152:155], v207 offset:12288
	ds_read_b128 v[156:159], v207 offset:13312
	ds_read_b128 v[160:163], v207 offset:14336
	ds_read_b128 v[164:167], v207 offset:15360
	s_waitcnt lgkmcnt(8)
	v_mfma_f32_16x16x32_bf16 v[232:235], v[100:103], v[0:3], 0
	v_mfma_f32_16x16x32_bf16 v[232:235], v[104:107], v[4:7], v[232:235]
	v_mfma_f32_16x16x32_bf16 v[232:235], v[108:111], v[8:11], v[232:235]
	v_mfma_f32_16x16x32_bf16 v[232:235], v[112:115], v[12:15], v[232:235]
	v_mfma_f32_16x16x32_bf16 v[232:235], v[116:119], v[16:19], v[232:235]
	v_mfma_f32_16x16x32_bf16 v[232:235], v[120:123], v[20:23], v[232:235]
	v_mfma_f32_16x16x32_bf16 v[232:235], v[124:127], v[24:27], v[232:235]
	v_mfma_f32_16x16x32_bf16 v[232:235], v[128:131], v[28:31], v[232:235]
	s_waitcnt lgkmcnt(0)
	v_mfma_f32_16x16x32_bf16 v[236:239], v[132:135], v[0:3], 0
	v_mfma_f32_16x16x32_bf16 v[236:239], v[136:139], v[4:7], v[236:239]
	v_mfma_f32_16x16x32_bf16 v[236:239], v[144:147], v[8:11], v[236:239]
	v_mfma_f32_16x16x32_bf16 v[236:239], v[148:151], v[12:15], v[236:239]
	v_mfma_f32_16x16x32_bf16 v[236:239], v[152:155], v[16:19], v[236:239]
	v_mfma_f32_16x16x32_bf16 v[236:239], v[156:159], v[20:23], v[236:239]
	v_mfma_f32_16x16x32_bf16 v[236:239], v[160:163], v[24:27], v[236:239]
	v_mfma_f32_16x16x32_bf16 v[236:239], v[164:167], v[28:31], v[236:239]
	s_nop 7
	s_nop 3
	v_cmp_le_i32_e32 vcc, 0, v201
	s_nop 1
	v_cndmask_b32_e32 v232, 0, v232, vcc
	v_cmp_le_i32_e32 vcc, 1, v201
	s_nop 1
	v_cndmask_b32_e32 v233, 0, v233, vcc
	v_cmp_le_i32_e32 vcc, 2, v201
	s_nop 1
	v_cndmask_b32_e32 v234, 0, v234, vcc
	v_cmp_le_i32_e32 vcc, 3, v201
	s_nop 1
	v_cndmask_b32_e32 v235, 0, v235, vcc
	v_cmp_le_i32_e32 vcc, 16, v201
	s_nop 1
	v_cndmask_b32_e32 v236, 0, v236, vcc
	v_cmp_le_i32_e32 vcc, 17, v201
	s_nop 1
	v_cndmask_b32_e32 v237, 0, v237, vcc
	v_cmp_le_i32_e32 vcc, 18, v201
	s_nop 1
	v_cndmask_b32_e32 v238, 0, v238, vcc
	v_cmp_le_i32_e32 vcc, 19, v201
	s_nop 1
	v_cndmask_b32_e32 v239, 0, v239, vcc
	v_cvt_pk_bf16_f32 v32, v232, v233
	v_cvt_pk_bf16_f32 v33, v234, v235
	v_cvt_pk_bf16_f32 v34, v236, v237
	v_cvt_pk_bf16_f32 v35, v238, v239
	s_cmp_ge_i32 s6, 2
	s_cbranch_scc0 .Lintra_a0_done
	ds_read_b128 v[100:103], v207 offset:16384
	ds_read_b128 v[104:107], v207 offset:17408
	ds_read_b128 v[108:111], v207 offset:18432
	ds_read_b128 v[112:115], v207 offset:19456
	ds_read_b128 v[116:119], v207 offset:20480
	ds_read_b128 v[120:123], v207 offset:21504
	ds_read_b128 v[124:127], v207 offset:22528
	ds_read_b128 v[128:131], v207 offset:23552
	ds_read_b128 v[132:135], v207 offset:24576
	ds_read_b128 v[136:139], v207 offset:25600
	ds_read_b128 v[144:147], v207 offset:26624
	ds_read_b128 v[148:151], v207 offset:27648
	ds_read_b128 v[152:155], v207 offset:28672
	ds_read_b128 v[156:159], v207 offset:29696
	ds_read_b128 v[160:163], v207 offset:30720
	ds_read_b128 v[164:167], v207 offset:31744
	s_waitcnt lgkmcnt(8)
	v_mfma_f32_16x16x32_bf16 v[232:235], v[100:103], v[0:3], 0
	v_mfma_f32_16x16x32_bf16 v[232:235], v[104:107], v[4:7], v[232:235]
	v_mfma_f32_16x16x32_bf16 v[232:235], v[108:111], v[8:11], v[232:235]
	v_mfma_f32_16x16x32_bf16 v[232:235], v[112:115], v[12:15], v[232:235]
	v_mfma_f32_16x16x32_bf16 v[232:235], v[116:119], v[16:19], v[232:235]
	v_mfma_f32_16x16x32_bf16 v[232:235], v[120:123], v[20:23], v[232:235]
	v_mfma_f32_16x16x32_bf16 v[232:235], v[124:127], v[24:27], v[232:235]
	v_mfma_f32_16x16x32_bf16 v[232:235], v[128:131], v[28:31], v[232:235]
	s_waitcnt lgkmcnt(0)
	v_mfma_f32_16x16x32_bf16 v[236:239], v[132:135], v[0:3], 0
	v_mfma_f32_16x16x32_bf16 v[236:239], v[136:139], v[4:7], v[236:239]
	v_mfma_f32_16x16x32_bf16 v[236:239], v[144:147], v[8:11], v[236:239]
	v_mfma_f32_16x16x32_bf16 v[236:239], v[148:151], v[12:15], v[236:239]
	v_mfma_f32_16x16x32_bf16 v[236:239], v[152:155], v[16:19], v[236:239]
	v_mfma_f32_16x16x32_bf16 v[236:239], v[156:159], v[20:23], v[236:239]
	v_mfma_f32_16x16x32_bf16 v[236:239], v[160:163], v[24:27], v[236:239]
	v_mfma_f32_16x16x32_bf16 v[236:239], v[164:167], v[28:31], v[236:239]
	s_nop 7
	s_nop 3
	v_cmp_le_i32_e32 vcc, 32, v201
	s_nop 1
	v_cndmask_b32_e32 v232, 0, v232, vcc
	v_cmp_le_i32_e32 vcc, 33, v201
	s_nop 1
	v_cndmask_b32_e32 v233, 0, v233, vcc
	v_cmp_le_i32_e32 vcc, 34, v201
	s_nop 1
	v_cndmask_b32_e32 v234, 0, v234, vcc
	v_cmp_le_i32_e32 vcc, 35, v201
	s_nop 1
	v_cndmask_b32_e32 v235, 0, v235, vcc
	v_cmp_le_i32_e32 vcc, 48, v201
	s_nop 1
	v_cndmask_b32_e32 v236, 0, v236, vcc
	v_cmp_le_i32_e32 vcc, 49, v201
	s_nop 1
	v_cndmask_b32_e32 v237, 0, v237, vcc
	v_cmp_le_i32_e32 vcc, 50, v201
	s_nop 1
	v_cndmask_b32_e32 v238, 0, v238, vcc
	v_cmp_le_i32_e32 vcc, 51, v201
	s_nop 1
	v_cndmask_b32_e32 v239, 0, v239, vcc
	v_cvt_pk_bf16_f32 v36, v232, v233
	v_cvt_pk_bf16_f32 v37, v234, v235
	v_cvt_pk_bf16_f32 v38, v236, v237
	v_cvt_pk_bf16_f32 v39, v238, v239
	s_cmp_ge_i32 s6, 3
	s_cbranch_scc0 .Lintra_a0_done
	ds_read_b128 v[100:103], v207 offset:32768
	ds_read_b128 v[104:107], v207 offset:33792
	ds_read_b128 v[108:111], v207 offset:34816
	ds_read_b128 v[112:115], v207 offset:35840
	ds_read_b128 v[116:119], v207 offset:36864
	ds_read_b128 v[120:123], v207 offset:37888
	ds_read_b128 v[124:127], v207 offset:38912
	ds_read_b128 v[128:131], v207 offset:39936
	ds_read_b128 v[132:135], v207 offset:40960
	ds_read_b128 v[136:139], v207 offset:41984
	ds_read_b128 v[144:147], v207 offset:43008
	ds_read_b128 v[148:151], v207 offset:44032
	ds_read_b128 v[152:155], v207 offset:45056
	ds_read_b128 v[156:159], v207 offset:46080
	ds_read_b128 v[160:163], v207 offset:47104
	ds_read_b128 v[164:167], v207 offset:48128
	s_waitcnt lgkmcnt(8)
	v_mfma_f32_16x16x32_bf16 v[232:235], v[100:103], v[0:3], 0
	v_mfma_f32_16x16x32_bf16 v[232:235], v[104:107], v[4:7], v[232:235]
	v_mfma_f32_16x16x32_bf16 v[232:235], v[108:111], v[8:11], v[232:235]
	v_mfma_f32_16x16x32_bf16 v[232:235], v[112:115], v[12:15], v[232:235]
	v_mfma_f32_16x16x32_bf16 v[232:235], v[116:119], v[16:19], v[232:235]
	v_mfma_f32_16x16x32_bf16 v[232:235], v[120:123], v[20:23], v[232:235]
	v_mfma_f32_16x16x32_bf16 v[232:235], v[124:127], v[24:27], v[232:235]
	v_mfma_f32_16x16x32_bf16 v[232:235], v[128:131], v[28:31], v[232:235]
	s_waitcnt lgkmcnt(0)
	v_mfma_f32_16x16x32_bf16 v[236:239], v[132:135], v[0:3], 0
	v_mfma_f32_16x16x32_bf16 v[236:239], v[136:139], v[4:7], v[236:239]
	v_mfma_f32_16x16x32_bf16 v[236:239], v[144:147], v[8:11], v[236:239]
	v_mfma_f32_16x16x32_bf16 v[236:239], v[148:151], v[12:15], v[236:239]
	v_mfma_f32_16x16x32_bf16 v[236:239], v[152:155], v[16:19], v[236:239]
	v_mfma_f32_16x16x32_bf16 v[236:239], v[156:159], v[20:23], v[236:239]
	v_mfma_f32_16x16x32_bf16 v[236:239], v[160:163], v[24:27], v[236:239]
	v_mfma_f32_16x16x32_bf16 v[236:239], v[164:167], v[28:31], v[236:239]
	s_nop 7
	s_nop 3
	v_cmp_le_i32_e32 vcc, 64, v201
	s_nop 1
	v_cndmask_b32_e32 v232, 0, v232, vcc
	v_cmp_le_i32_e32 vcc, 65, v201
	s_nop 1
	v_cndmask_b32_e32 v233, 0, v233, vcc
	v_cmp_le_i32_e32 vcc, 66, v201
	s_nop 1
	v_cndmask_b32_e32 v234, 0, v234, vcc
	v_cmp_le_i32_e32 vcc, 67, v201
	s_nop 1
	v_cndmask_b32_e32 v235, 0, v235, vcc
	v_cmp_le_i32_e32 vcc, 80, v201
	s_nop 1
	v_cndmask_b32_e32 v236, 0, v236, vcc
	v_cmp_le_i32_e32 vcc, 81, v201
	s_nop 1
	v_cndmask_b32_e32 v237, 0, v237, vcc
	v_cmp_le_i32_e32 vcc, 82, v201
	s_nop 1
	v_cndmask_b32_e32 v238, 0, v238, vcc
	v_cmp_le_i32_e32 vcc, 83, v201
	s_nop 1
	v_cndmask_b32_e32 v239, 0, v239, vcc
	v_cvt_pk_bf16_f32 v40, v232, v233
	v_cvt_pk_bf16_f32 v41, v234, v235
	v_cvt_pk_bf16_f32 v42, v236, v237
	v_cvt_pk_bf16_f32 v43, v238, v239
	s_cmp_ge_i32 s6, 4
	s_cbranch_scc0 .Lintra_a0_done
	ds_read_b128 v[100:103], v207 offset:49152
	ds_read_b128 v[104:107], v207 offset:50176
	ds_read_b128 v[108:111], v207 offset:51200
	ds_read_b128 v[112:115], v207 offset:52224
	ds_read_b128 v[116:119], v207 offset:53248
	ds_read_b128 v[120:123], v207 offset:54272
	ds_read_b128 v[124:127], v207 offset:55296
	ds_read_b128 v[128:131], v207 offset:56320
	ds_read_b128 v[132:135], v207 offset:57344
	ds_read_b128 v[136:139], v207 offset:58368
	ds_read_b128 v[144:147], v207 offset:59392
	ds_read_b128 v[148:151], v207 offset:60416
	ds_read_b128 v[152:155], v207 offset:61440
	ds_read_b128 v[156:159], v207 offset:62464
	ds_read_b128 v[160:163], v207 offset:63488
	ds_read_b128 v[164:167], v207 offset:64512
	s_waitcnt lgkmcnt(8)
	v_mfma_f32_16x16x32_bf16 v[232:235], v[100:103], v[0:3], 0
	v_mfma_f32_16x16x32_bf16 v[232:235], v[104:107], v[4:7], v[232:235]
	v_mfma_f32_16x16x32_bf16 v[232:235], v[108:111], v[8:11], v[232:235]
	v_mfma_f32_16x16x32_bf16 v[232:235], v[112:115], v[12:15], v[232:235]
	v_mfma_f32_16x16x32_bf16 v[232:235], v[116:119], v[16:19], v[232:235]
	v_mfma_f32_16x16x32_bf16 v[232:235], v[120:123], v[20:23], v[232:235]
	v_mfma_f32_16x16x32_bf16 v[232:235], v[124:127], v[24:27], v[232:235]
	v_mfma_f32_16x16x32_bf16 v[232:235], v[128:131], v[28:31], v[232:235]
	s_waitcnt lgkmcnt(0)
	v_mfma_f32_16x16x32_bf16 v[236:239], v[132:135], v[0:3], 0
	v_mfma_f32_16x16x32_bf16 v[236:239], v[136:139], v[4:7], v[236:239]
	v_mfma_f32_16x16x32_bf16 v[236:239], v[144:147], v[8:11], v[236:239]
	v_mfma_f32_16x16x32_bf16 v[236:239], v[148:151], v[12:15], v[236:239]
	v_mfma_f32_16x16x32_bf16 v[236:239], v[152:155], v[16:19], v[236:239]
	v_mfma_f32_16x16x32_bf16 v[236:239], v[156:159], v[20:23], v[236:239]
	v_mfma_f32_16x16x32_bf16 v[236:239], v[160:163], v[24:27], v[236:239]
	v_mfma_f32_16x16x32_bf16 v[236:239], v[164:167], v[28:31], v[236:239]
	s_nop 7
	s_nop 3
	v_cmp_le_i32_e32 vcc, 96, v201
	s_nop 1
	v_cndmask_b32_e32 v232, 0, v232, vcc
	v_cmp_le_i32_e32 vcc, 97, v201
	s_nop 1
	v_cndmask_b32_e32 v233, 0, v233, vcc
	v_cmp_le_i32_e32 vcc, 98, v201
	s_nop 1
	v_cndmask_b32_e32 v234, 0, v234, vcc
	v_cmp_le_i32_e32 vcc, 99, v201
	s_nop 1
	v_cndmask_b32_e32 v235, 0, v235, vcc
	v_cmp_le_i32_e32 vcc, 112, v201
	s_nop 1
	v_cndmask_b32_e32 v236, 0, v236, vcc
	v_cmp_le_i32_e32 vcc, 113, v201
	s_nop 1
	v_cndmask_b32_e32 v237, 0, v237, vcc
	v_cmp_le_i32_e32 vcc, 114, v201
	s_nop 1
	v_cndmask_b32_e32 v238, 0, v238, vcc
	v_cmp_le_i32_e32 vcc, 115, v201
	s_nop 1
	v_cndmask_b32_e32 v239, 0, v239, vcc
	v_cvt_pk_bf16_f32 v44, v232, v233
	v_cvt_pk_bf16_f32 v45, v234, v235
	v_cvt_pk_bf16_f32 v46, v236, v237
	v_cvt_pk_bf16_f32 v47, v238, v239
	s_cmp_ge_i32 s6, 5
	s_cbranch_scc0 .Lintra_a0_done
	ds_read_b128 v[100:103], v230 offset:0
	ds_read_b128 v[104:107], v230 offset:1024
	ds_read_b128 v[108:111], v230 offset:2048
	ds_read_b128 v[112:115], v230 offset:3072
	ds_read_b128 v[116:119], v230 offset:4096
	ds_read_b128 v[120:123], v230 offset:5120
	ds_read_b128 v[124:127], v230 offset:6144
	ds_read_b128 v[128:131], v230 offset:7168
	ds_read_b128 v[132:135], v230 offset:8192
	ds_read_b128 v[136:139], v230 offset:9216
	ds_read_b128 v[144:147], v230 offset:10240
	ds_read_b128 v[148:151], v230 offset:11264
	ds_read_b128 v[152:155], v230 offset:12288
	ds_read_b128 v[156:159], v230 offset:13312
	ds_read_b128 v[160:163], v230 offset:14336
	ds_read_b128 v[164:167], v230 offset:15360
	s_waitcnt lgkmcnt(8)
	v_mfma_f32_16x16x32_bf16 v[232:235], v[100:103], v[0:3], 0
	v_mfma_f32_16x16x32_bf16 v[232:235], v[104:107], v[4:7], v[232:235]
	v_mfma_f32_16x16x32_bf16 v[232:235], v[108:111], v[8:11], v[232:235]
	v_mfma_f32_16x16x32_bf16 v[232:235], v[112:115], v[12:15], v[232:235]
	v_mfma_f32_16x16x32_bf16 v[232:235], v[116:119], v[16:19], v[232:235]
	v_mfma_f32_16x16x32_bf16 v[232:235], v[120:123], v[20:23], v[232:235]
	v_mfma_f32_16x16x32_bf16 v[232:235], v[124:127], v[24:27], v[232:235]
	v_mfma_f32_16x16x32_bf16 v[232:235], v[128:131], v[28:31], v[232:235]
	s_waitcnt lgkmcnt(0)
	v_mfma_f32_16x16x32_bf16 v[236:239], v[132:135], v[0:3], 0
	v_mfma_f32_16x16x32_bf16 v[236:239], v[136:139], v[4:7], v[236:239]
	v_mfma_f32_16x16x32_bf16 v[236:239], v[144:147], v[8:11], v[236:239]
	v_mfma_f32_16x16x32_bf16 v[236:239], v[148:151], v[12:15], v[236:239]
	v_mfma_f32_16x16x32_bf16 v[236:239], v[152:155], v[16:19], v[236:239]
	v_mfma_f32_16x16x32_bf16 v[236:239], v[156:159], v[20:23], v[236:239]
	v_mfma_f32_16x16x32_bf16 v[236:239], v[160:163], v[24:27], v[236:239]
	v_mfma_f32_16x16x32_bf16 v[236:239], v[164:167], v[28:31], v[236:239]
	s_nop 7
	s_nop 3
	v_cmp_le_i32_e32 vcc, 128, v201
	s_nop 1
	v_cndmask_b32_e32 v232, 0, v232, vcc
	v_cmp_le_i32_e32 vcc, 129, v201
	s_nop 1
	v_cndmask_b32_e32 v233, 0, v233, vcc
	v_cmp_le_i32_e32 vcc, 130, v201
	s_nop 1
	v_cndmask_b32_e32 v234, 0, v234, vcc
	v_cmp_le_i32_e32 vcc, 131, v201
	s_nop 1
	v_cndmask_b32_e32 v235, 0, v235, vcc
	v_cmp_le_i32_e32 vcc, 144, v201
	s_nop 1
	v_cndmask_b32_e32 v236, 0, v236, vcc
	v_cmp_le_i32_e32 vcc, 145, v201
	s_nop 1
	v_cndmask_b32_e32 v237, 0, v237, vcc
	v_cmp_le_i32_e32 vcc, 146, v201
	s_nop 1
	v_cndmask_b32_e32 v238, 0, v238, vcc
	v_cmp_le_i32_e32 vcc, 147, v201
	s_nop 1
	v_cndmask_b32_e32 v239, 0, v239, vcc
	v_cvt_pk_bf16_f32 v48, v232, v233
	v_cvt_pk_bf16_f32 v49, v234, v235
	v_cvt_pk_bf16_f32 v50, v236, v237
	v_cvt_pk_bf16_f32 v51, v238, v239
	s_cmp_ge_i32 s6, 6
	s_cbranch_scc0 .Lintra_a0_done
	ds_read_b128 v[100:103], v230 offset:16384
	ds_read_b128 v[104:107], v230 offset:17408
	ds_read_b128 v[108:111], v230 offset:18432
	ds_read_b128 v[112:115], v230 offset:19456
	ds_read_b128 v[116:119], v230 offset:20480
	ds_read_b128 v[120:123], v230 offset:21504
	ds_read_b128 v[124:127], v230 offset:22528
	ds_read_b128 v[128:131], v230 offset:23552
	ds_read_b128 v[132:135], v230 offset:24576
	ds_read_b128 v[136:139], v230 offset:25600
	ds_read_b128 v[144:147], v230 offset:26624
	ds_read_b128 v[148:151], v230 offset:27648
	ds_read_b128 v[152:155], v230 offset:28672
	ds_read_b128 v[156:159], v230 offset:29696
	ds_read_b128 v[160:163], v230 offset:30720
	ds_read_b128 v[164:167], v230 offset:31744
	s_waitcnt lgkmcnt(8)
	v_mfma_f32_16x16x32_bf16 v[232:235], v[100:103], v[0:3], 0
	v_mfma_f32_16x16x32_bf16 v[232:235], v[104:107], v[4:7], v[232:235]
	v_mfma_f32_16x16x32_bf16 v[232:235], v[108:111], v[8:11], v[232:235]
	v_mfma_f32_16x16x32_bf16 v[232:235], v[112:115], v[12:15], v[232:235]
	v_mfma_f32_16x16x32_bf16 v[232:235], v[116:119], v[16:19], v[232:235]
	v_mfma_f32_16x16x32_bf16 v[232:235], v[120:123], v[20:23], v[232:235]
	v_mfma_f32_16x16x32_bf16 v[232:235], v[124:127], v[24:27], v[232:235]
	v_mfma_f32_16x16x32_bf16 v[232:235], v[128:131], v[28:31], v[232:235]
	s_waitcnt lgkmcnt(0)
	v_mfma_f32_16x16x32_bf16 v[236:239], v[132:135], v[0:3], 0
	v_mfma_f32_16x16x32_bf16 v[236:239], v[136:139], v[4:7], v[236:239]
	v_mfma_f32_16x16x32_bf16 v[236:239], v[144:147], v[8:11], v[236:239]
	v_mfma_f32_16x16x32_bf16 v[236:239], v[148:151], v[12:15], v[236:239]
	v_mfma_f32_16x16x32_bf16 v[236:239], v[152:155], v[16:19], v[236:239]
	v_mfma_f32_16x16x32_bf16 v[236:239], v[156:159], v[20:23], v[236:239]
	v_mfma_f32_16x16x32_bf16 v[236:239], v[160:163], v[24:27], v[236:239]
	v_mfma_f32_16x16x32_bf16 v[236:239], v[164:167], v[28:31], v[236:239]
	s_nop 7
	s_nop 3
	v_cmp_le_i32_e32 vcc, 160, v201
	s_nop 1
	v_cndmask_b32_e32 v232, 0, v232, vcc
	v_cmp_le_i32_e32 vcc, 161, v201
	s_nop 1
	v_cndmask_b32_e32 v233, 0, v233, vcc
	v_cmp_le_i32_e32 vcc, 162, v201
	s_nop 1
	v_cndmask_b32_e32 v234, 0, v234, vcc
	v_cmp_le_i32_e32 vcc, 163, v201
	s_nop 1
	v_cndmask_b32_e32 v235, 0, v235, vcc
	v_cmp_le_i32_e32 vcc, 176, v201
	s_nop 1
	v_cndmask_b32_e32 v236, 0, v236, vcc
	v_cmp_le_i32_e32 vcc, 177, v201
	s_nop 1
	v_cndmask_b32_e32 v237, 0, v237, vcc
	v_cmp_le_i32_e32 vcc, 178, v201
	s_nop 1
	v_cndmask_b32_e32 v238, 0, v238, vcc
	v_cmp_le_i32_e32 vcc, 179, v201
	s_nop 1
	v_cndmask_b32_e32 v239, 0, v239, vcc
	v_cvt_pk_bf16_f32 v52, v232, v233
	v_cvt_pk_bf16_f32 v53, v234, v235
	v_cvt_pk_bf16_f32 v54, v236, v237
	v_cvt_pk_bf16_f32 v55, v238, v239
	s_cmp_ge_i32 s6, 7
	s_cbranch_scc0 .Lintra_a0_done
	ds_read_b128 v[100:103], v230 offset:32768
	ds_read_b128 v[104:107], v230 offset:33792
	ds_read_b128 v[108:111], v230 offset:34816
	ds_read_b128 v[112:115], v230 offset:35840
	ds_read_b128 v[116:119], v230 offset:36864
	ds_read_b128 v[120:123], v230 offset:37888
	ds_read_b128 v[124:127], v230 offset:38912
	ds_read_b128 v[128:131], v230 offset:39936
	ds_read_b128 v[132:135], v230 offset:40960
	ds_read_b128 v[136:139], v230 offset:41984
	ds_read_b128 v[144:147], v230 offset:43008
	ds_read_b128 v[148:151], v230 offset:44032
	ds_read_b128 v[152:155], v230 offset:45056
	ds_read_b128 v[156:159], v230 offset:46080
	ds_read_b128 v[160:163], v230 offset:47104
	ds_read_b128 v[164:167], v230 offset:48128
	s_waitcnt lgkmcnt(8)
	v_mfma_f32_16x16x32_bf16 v[232:235], v[100:103], v[0:3], 0
	v_mfma_f32_16x16x32_bf16 v[232:235], v[104:107], v[4:7], v[232:235]
	v_mfma_f32_16x16x32_bf16 v[232:235], v[108:111], v[8:11], v[232:235]
	v_mfma_f32_16x16x32_bf16 v[232:235], v[112:115], v[12:15], v[232:235]
	v_mfma_f32_16x16x32_bf16 v[232:235], v[116:119], v[16:19], v[232:235]
	v_mfma_f32_16x16x32_bf16 v[232:235], v[120:123], v[20:23], v[232:235]
	v_mfma_f32_16x16x32_bf16 v[232:235], v[124:127], v[24:27], v[232:235]
	v_mfma_f32_16x16x32_bf16 v[232:235], v[128:131], v[28:31], v[232:235]
	s_waitcnt lgkmcnt(0)
	v_mfma_f32_16x16x32_bf16 v[236:239], v[132:135], v[0:3], 0
	v_mfma_f32_16x16x32_bf16 v[236:239], v[136:139], v[4:7], v[236:239]
	v_mfma_f32_16x16x32_bf16 v[236:239], v[144:147], v[8:11], v[236:239]
	v_mfma_f32_16x16x32_bf16 v[236:239], v[148:151], v[12:15], v[236:239]
	v_mfma_f32_16x16x32_bf16 v[236:239], v[152:155], v[16:19], v[236:239]
	v_mfma_f32_16x16x32_bf16 v[236:239], v[156:159], v[20:23], v[236:239]
	v_mfma_f32_16x16x32_bf16 v[236:239], v[160:163], v[24:27], v[236:239]
	v_mfma_f32_16x16x32_bf16 v[236:239], v[164:167], v[28:31], v[236:239]
	s_nop 7
	s_nop 3
	v_cmp_le_i32_e32 vcc, 192, v201
	s_nop 1
	v_cndmask_b32_e32 v232, 0, v232, vcc
	v_cmp_le_i32_e32 vcc, 193, v201
	s_nop 1
	v_cndmask_b32_e32 v233, 0, v233, vcc
	v_cmp_le_i32_e32 vcc, 194, v201
	s_nop 1
	v_cndmask_b32_e32 v234, 0, v234, vcc
	v_cmp_le_i32_e32 vcc, 195, v201
	s_nop 1
	v_cndmask_b32_e32 v235, 0, v235, vcc
	v_cmp_le_i32_e32 vcc, 208, v201
	s_nop 1
	v_cndmask_b32_e32 v236, 0, v236, vcc
	v_cmp_le_i32_e32 vcc, 209, v201
	s_nop 1
	v_cndmask_b32_e32 v237, 0, v237, vcc
	v_cmp_le_i32_e32 vcc, 210, v201
	s_nop 1
	v_cndmask_b32_e32 v238, 0, v238, vcc
	v_cmp_le_i32_e32 vcc, 211, v201
	s_nop 1
	v_cndmask_b32_e32 v239, 0, v239, vcc
	v_cvt_pk_bf16_f32 v56, v232, v233
	v_cvt_pk_bf16_f32 v57, v234, v235
	v_cvt_pk_bf16_f32 v58, v236, v237
	v_cvt_pk_bf16_f32 v59, v238, v239
	s_cmp_ge_i32 s6, 8
	s_cbranch_scc0 .Lintra_a0_done
	ds_read_b128 v[100:103], v230 offset:49152
	ds_read_b128 v[104:107], v230 offset:50176
	ds_read_b128 v[108:111], v230 offset:51200
	ds_read_b128 v[112:115], v230 offset:52224
	ds_read_b128 v[116:119], v230 offset:53248
	ds_read_b128 v[120:123], v230 offset:54272
	ds_read_b128 v[124:127], v230 offset:55296
	ds_read_b128 v[128:131], v230 offset:56320
	ds_read_b128 v[132:135], v230 offset:57344
	ds_read_b128 v[136:139], v230 offset:58368
	ds_read_b128 v[144:147], v230 offset:59392
	ds_read_b128 v[148:151], v230 offset:60416
	ds_read_b128 v[152:155], v230 offset:61440
	ds_read_b128 v[156:159], v230 offset:62464
	ds_read_b128 v[160:163], v230 offset:63488
	ds_read_b128 v[164:167], v230 offset:64512
	s_waitcnt lgkmcnt(8)
	v_mfma_f32_16x16x32_bf16 v[232:235], v[100:103], v[0:3], 0
	v_mfma_f32_16x16x32_bf16 v[232:235], v[104:107], v[4:7], v[232:235]
	v_mfma_f32_16x16x32_bf16 v[232:235], v[108:111], v[8:11], v[232:235]
	v_mfma_f32_16x16x32_bf16 v[232:235], v[112:115], v[12:15], v[232:235]
	v_mfma_f32_16x16x32_bf16 v[232:235], v[116:119], v[16:19], v[232:235]
	v_mfma_f32_16x16x32_bf16 v[232:235], v[120:123], v[20:23], v[232:235]
	v_mfma_f32_16x16x32_bf16 v[232:235], v[124:127], v[24:27], v[232:235]
	v_mfma_f32_16x16x32_bf16 v[232:235], v[128:131], v[28:31], v[232:235]
	s_waitcnt lgkmcnt(0)
	v_mfma_f32_16x16x32_bf16 v[236:239], v[132:135], v[0:3], 0
	v_mfma_f32_16x16x32_bf16 v[236:239], v[136:139], v[4:7], v[236:239]
	v_mfma_f32_16x16x32_bf16 v[236:239], v[144:147], v[8:11], v[236:239]
	v_mfma_f32_16x16x32_bf16 v[236:239], v[148:151], v[12:15], v[236:239]
	v_mfma_f32_16x16x32_bf16 v[236:239], v[152:155], v[16:19], v[236:239]
	v_mfma_f32_16x16x32_bf16 v[236:239], v[156:159], v[20:23], v[236:239]
	v_mfma_f32_16x16x32_bf16 v[236:239], v[160:163], v[24:27], v[236:239]
	v_mfma_f32_16x16x32_bf16 v[236:239], v[164:167], v[28:31], v[236:239]
	s_nop 7
	s_nop 3
	v_cmp_le_i32_e32 vcc, 224, v201
	s_nop 1
	v_cndmask_b32_e32 v232, 0, v232, vcc
	v_cmp_le_i32_e32 vcc, 225, v201
	s_nop 1
	v_cndmask_b32_e32 v233, 0, v233, vcc
	v_cmp_le_i32_e32 vcc, 226, v201
	s_nop 1
	v_cndmask_b32_e32 v234, 0, v234, vcc
	v_cmp_le_i32_e32 vcc, 227, v201
	s_nop 1
	v_cndmask_b32_e32 v235, 0, v235, vcc
	v_cmp_le_i32_e32 vcc, 240, v201
	s_nop 1
	v_cndmask_b32_e32 v236, 0, v236, vcc
	v_cmp_le_i32_e32 vcc, 241, v201
	s_nop 1
	v_cndmask_b32_e32 v237, 0, v237, vcc
	v_cmp_le_i32_e32 vcc, 242, v201
	s_nop 1
	v_cndmask_b32_e32 v238, 0, v238, vcc
	v_cmp_le_i32_e32 vcc, 243, v201
	s_nop 1
	v_cndmask_b32_e32 v239, 0, v239, vcc
	v_cvt_pk_bf16_f32 v60, v232, v233
	v_cvt_pk_bf16_f32 v61, v234, v235
	v_cvt_pk_bf16_f32 v62, v236, v237
	v_cvt_pk_bf16_f32 v63, v238, v239
.Lintra_a0_done:
	ds_read_b128 v[100:103], v207 offset:0
	ds_read_b128 v[104:107], v207 offset:1024
	ds_read_b128 v[108:111], v207 offset:2048
	ds_read_b128 v[112:115], v207 offset:3072
	ds_read_b128 v[116:119], v207 offset:4096
	ds_read_b128 v[120:123], v207 offset:5120
	ds_read_b128 v[124:127], v207 offset:6144
	ds_read_b128 v[128:131], v207 offset:7168
	ds_read_b128 v[132:135], v207 offset:8192
	ds_read_b128 v[136:139], v207 offset:9216
	ds_read_b128 v[144:147], v207 offset:10240
	ds_read_b128 v[148:151], v207 offset:11264
	ds_read_b128 v[152:155], v207 offset:12288
	ds_read_b128 v[156:159], v207 offset:13312
	ds_read_b128 v[160:163], v207 offset:14336
	ds_read_b128 v[164:167], v207 offset:15360
	s_waitcnt lgkmcnt(8)
	v_mfma_f32_16x16x32_bf16 v[232:235], v[100:103], v[168:171], 0
	v_mfma_f32_16x16x32_bf16 v[232:235], v[104:107], v[172:175], v[232:235]
	v_mfma_f32_16x16x32_bf16 v[232:235], v[108:111], v[176:179], v[232:235]
	v_mfma_f32_16x16x32_bf16 v[232:235], v[112:115], v[180:183], v[232:235]
	v_mfma_f32_16x16x32_bf16 v[232:235], v[116:119], v[184:187], v[232:235]
	v_mfma_f32_16x16x32_bf16 v[232:235], v[120:123], v[188:191], v[232:235]
	v_mfma_f32_16x16x32_bf16 v[232:235], v[124:127], v[192:195], v[232:235]
	v_mfma_f32_16x16x32_bf16 v[232:235], v[128:131], v[196:199], v[232:235]
	s_waitcnt lgkmcnt(0)
	v_mfma_f32_16x16x32_bf16 v[236:239], v[132:135], v[168:171], 0
	v_mfma_f32_16x16x32_bf16 v[236:239], v[136:139], v[172:175], v[236:239]
	v_mfma_f32_16x16x32_bf16 v[236:239], v[144:147], v[176:179], v[236:239]
	v_mfma_f32_16x16x32_bf16 v[236:239], v[148:151], v[180:183], v[236:239]
	v_mfma_f32_16x16x32_bf16 v[236:239], v[152:155], v[184:187], v[236:239]
	v_mfma_f32_16x16x32_bf16 v[236:239], v[156:159], v[188:191], v[236:239]
	v_mfma_f32_16x16x32_bf16 v[236:239], v[160:163], v[192:195], v[236:239]
	v_mfma_f32_16x16x32_bf16 v[236:239], v[164:167], v[196:199], v[236:239]
	s_nop 7
	s_nop 3
	v_cmp_le_i32_e32 vcc, 0, v244
	s_nop 1
	v_cndmask_b32_e32 v232, 0, v232, vcc
	v_cmp_le_i32_e32 vcc, 1, v244
	s_nop 1
	v_cndmask_b32_e32 v233, 0, v233, vcc
	v_cmp_le_i32_e32 vcc, 2, v244
	s_nop 1
	v_cndmask_b32_e32 v234, 0, v234, vcc
	v_cmp_le_i32_e32 vcc, 3, v244
	s_nop 1
	v_cndmask_b32_e32 v235, 0, v235, vcc
	v_cmp_le_i32_e32 vcc, 16, v244
	s_nop 1
	v_cndmask_b32_e32 v236, 0, v236, vcc
	v_cmp_le_i32_e32 vcc, 17, v244
	s_nop 1
	v_cndmask_b32_e32 v237, 0, v237, vcc
	v_cmp_le_i32_e32 vcc, 18, v244
	s_nop 1
	v_cndmask_b32_e32 v238, 0, v238, vcc
	v_cmp_le_i32_e32 vcc, 19, v244
	s_nop 1
	v_cndmask_b32_e32 v239, 0, v239, vcc
	v_cvt_pk_bf16_f32 v240, v232, v233
	v_cvt_pk_bf16_f32 v241, v234, v235
	v_cvt_pk_bf16_f32 v242, v236, v237
	v_cvt_pk_bf16_f32 v243, v238, v239
	s_cmp_ge_i32 s7, 2
	s_cbranch_scc0 .Lintra_a1_done
	ds_read_b128 v[100:103], v207 offset:16384
	ds_read_b128 v[104:107], v207 offset:17408
	ds_read_b128 v[108:111], v207 offset:18432
	ds_read_b128 v[112:115], v207 offset:19456
	ds_read_b128 v[116:119], v207 offset:20480
	ds_read_b128 v[120:123], v207 offset:21504
	ds_read_b128 v[124:127], v207 offset:22528
	ds_read_b128 v[128:131], v207 offset:23552
	ds_read_b128 v[132:135], v207 offset:24576
	ds_read_b128 v[136:139], v207 offset:25600
	ds_read_b128 v[144:147], v207 offset:26624
	ds_read_b128 v[148:151], v207 offset:27648
	ds_read_b128 v[152:155], v207 offset:28672
	ds_read_b128 v[156:159], v207 offset:29696
	ds_read_b128 v[160:163], v207 offset:30720
	ds_read_b128 v[164:167], v207 offset:31744
	s_waitcnt lgkmcnt(8)
	v_mfma_f32_16x16x32_bf16 v[232:235], v[100:103], v[168:171], 0
	v_mfma_f32_16x16x32_bf16 v[232:235], v[104:107], v[172:175], v[232:235]
	v_mfma_f32_16x16x32_bf16 v[232:235], v[108:111], v[176:179], v[232:235]
	v_mfma_f32_16x16x32_bf16 v[232:235], v[112:115], v[180:183], v[232:235]
	v_mfma_f32_16x16x32_bf16 v[232:235], v[116:119], v[184:187], v[232:235]
	v_mfma_f32_16x16x32_bf16 v[232:235], v[120:123], v[188:191], v[232:235]
	v_mfma_f32_16x16x32_bf16 v[232:235], v[124:127], v[192:195], v[232:235]
	v_mfma_f32_16x16x32_bf16 v[232:235], v[128:131], v[196:199], v[232:235]
	s_waitcnt lgkmcnt(0)
	v_mfma_f32_16x16x32_bf16 v[236:239], v[132:135], v[168:171], 0
	v_mfma_f32_16x16x32_bf16 v[236:239], v[136:139], v[172:175], v[236:239]
	v_mfma_f32_16x16x32_bf16 v[236:239], v[144:147], v[176:179], v[236:239]
	v_mfma_f32_16x16x32_bf16 v[236:239], v[148:151], v[180:183], v[236:239]
	v_mfma_f32_16x16x32_bf16 v[236:239], v[152:155], v[184:187], v[236:239]
	v_mfma_f32_16x16x32_bf16 v[236:239], v[156:159], v[188:191], v[236:239]
	v_mfma_f32_16x16x32_bf16 v[236:239], v[160:163], v[192:195], v[236:239]
	v_mfma_f32_16x16x32_bf16 v[236:239], v[164:167], v[196:199], v[236:239]
	s_nop 7
	s_nop 3
	v_cmp_le_i32_e32 vcc, 32, v244
	s_nop 1
	v_cndmask_b32_e32 v232, 0, v232, vcc
	v_cmp_le_i32_e32 vcc, 33, v244
	s_nop 1
	v_cndmask_b32_e32 v233, 0, v233, vcc
	v_cmp_le_i32_e32 vcc, 34, v244
	s_nop 1
	v_cndmask_b32_e32 v234, 0, v234, vcc
	v_cmp_le_i32_e32 vcc, 35, v244
	s_nop 1
	v_cndmask_b32_e32 v235, 0, v235, vcc
	v_cmp_le_i32_e32 vcc, 48, v244
	s_nop 1
	v_cndmask_b32_e32 v236, 0, v236, vcc
	v_cmp_le_i32_e32 vcc, 49, v244
	s_nop 1
	v_cndmask_b32_e32 v237, 0, v237, vcc
	v_cmp_le_i32_e32 vcc, 50, v244
	s_nop 1
	v_cndmask_b32_e32 v238, 0, v238, vcc
	v_cmp_le_i32_e32 vcc, 51, v244
	s_nop 1
	v_cndmask_b32_e32 v239, 0, v239, vcc
	v_cvt_pk_bf16_f32 v60, v232, v233
	v_cvt_pk_bf16_f32 v61, v234, v235
	v_cvt_pk_bf16_f32 v62, v236, v237
	v_cvt_pk_bf16_f32 v63, v238, v239
	s_cmp_ge_i32 s7, 3
	s_cbranch_scc0 .Lintra_a1_done
	ds_read_b128 v[100:103], v207 offset:32768
	ds_read_b128 v[104:107], v207 offset:33792
	ds_read_b128 v[108:111], v207 offset:34816
	ds_read_b128 v[112:115], v207 offset:35840
	ds_read_b128 v[116:119], v207 offset:36864
	ds_read_b128 v[120:123], v207 offset:37888
	ds_read_b128 v[124:127], v207 offset:38912
	ds_read_b128 v[128:131], v207 offset:39936
	ds_read_b128 v[132:135], v207 offset:40960
	ds_read_b128 v[136:139], v207 offset:41984
	ds_read_b128 v[144:147], v207 offset:43008
	ds_read_b128 v[148:151], v207 offset:44032
	ds_read_b128 v[152:155], v207 offset:45056
	ds_read_b128 v[156:159], v207 offset:46080
	ds_read_b128 v[160:163], v207 offset:47104
	ds_read_b128 v[164:167], v207 offset:48128
	s_waitcnt lgkmcnt(8)
	v_mfma_f32_16x16x32_bf16 v[232:235], v[100:103], v[168:171], 0
	v_mfma_f32_16x16x32_bf16 v[232:235], v[104:107], v[172:175], v[232:235]
	v_mfma_f32_16x16x32_bf16 v[232:235], v[108:111], v[176:179], v[232:235]
	v_mfma_f32_16x16x32_bf16 v[232:235], v[112:115], v[180:183], v[232:235]
	v_mfma_f32_16x16x32_bf16 v[232:235], v[116:119], v[184:187], v[232:235]
	v_mfma_f32_16x16x32_bf16 v[232:235], v[120:123], v[188:191], v[232:235]
	v_mfma_f32_16x16x32_bf16 v[232:235], v[124:127], v[192:195], v[232:235]
	v_mfma_f32_16x16x32_bf16 v[232:235], v[128:131], v[196:199], v[232:235]
	s_waitcnt lgkmcnt(0)
	v_mfma_f32_16x16x32_bf16 v[236:239], v[132:135], v[168:171], 0
	v_mfma_f32_16x16x32_bf16 v[236:239], v[136:139], v[172:175], v[236:239]
	v_mfma_f32_16x16x32_bf16 v[236:239], v[144:147], v[176:179], v[236:239]
	v_mfma_f32_16x16x32_bf16 v[236:239], v[148:151], v[180:183], v[236:239]
	v_mfma_f32_16x16x32_bf16 v[236:239], v[152:155], v[184:187], v[236:239]
	v_mfma_f32_16x16x32_bf16 v[236:239], v[156:159], v[188:191], v[236:239]
	v_mfma_f32_16x16x32_bf16 v[236:239], v[160:163], v[192:195], v[236:239]
	v_mfma_f32_16x16x32_bf16 v[236:239], v[164:167], v[196:199], v[236:239]
	s_nop 7
	s_nop 3
	v_cmp_le_i32_e32 vcc, 64, v244
	s_nop 1
	v_cndmask_b32_e32 v232, 0, v232, vcc
	v_cmp_le_i32_e32 vcc, 65, v244
	s_nop 1
	v_cndmask_b32_e32 v233, 0, v233, vcc
	v_cmp_le_i32_e32 vcc, 66, v244
	s_nop 1
	v_cndmask_b32_e32 v234, 0, v234, vcc
	v_cmp_le_i32_e32 vcc, 67, v244
	s_nop 1
	v_cndmask_b32_e32 v235, 0, v235, vcc
	v_cmp_le_i32_e32 vcc, 80, v244
	s_nop 1
	v_cndmask_b32_e32 v236, 0, v236, vcc
	v_cmp_le_i32_e32 vcc, 81, v244
	s_nop 1
	v_cndmask_b32_e32 v237, 0, v237, vcc
	v_cmp_le_i32_e32 vcc, 82, v244
	s_nop 1
	v_cndmask_b32_e32 v238, 0, v238, vcc
	v_cmp_le_i32_e32 vcc, 83, v244
	s_nop 1
	v_cndmask_b32_e32 v239, 0, v239, vcc
	v_cvt_pk_bf16_f32 v56, v232, v233
	v_cvt_pk_bf16_f32 v57, v234, v235
	v_cvt_pk_bf16_f32 v58, v236, v237
	v_cvt_pk_bf16_f32 v59, v238, v239
	s_cmp_ge_i32 s7, 4
	s_cbranch_scc0 .Lintra_a1_done
	ds_read_b128 v[100:103], v207 offset:49152
	ds_read_b128 v[104:107], v207 offset:50176
	ds_read_b128 v[108:111], v207 offset:51200
	ds_read_b128 v[112:115], v207 offset:52224
	ds_read_b128 v[116:119], v207 offset:53248
	ds_read_b128 v[120:123], v207 offset:54272
	ds_read_b128 v[124:127], v207 offset:55296
	ds_read_b128 v[128:131], v207 offset:56320
	ds_read_b128 v[132:135], v207 offset:57344
	ds_read_b128 v[136:139], v207 offset:58368
	ds_read_b128 v[144:147], v207 offset:59392
	ds_read_b128 v[148:151], v207 offset:60416
	ds_read_b128 v[152:155], v207 offset:61440
	ds_read_b128 v[156:159], v207 offset:62464
	ds_read_b128 v[160:163], v207 offset:63488
	ds_read_b128 v[164:167], v207 offset:64512
	s_waitcnt lgkmcnt(8)
	v_mfma_f32_16x16x32_bf16 v[232:235], v[100:103], v[168:171], 0
	v_mfma_f32_16x16x32_bf16 v[232:235], v[104:107], v[172:175], v[232:235]
	v_mfma_f32_16x16x32_bf16 v[232:235], v[108:111], v[176:179], v[232:235]
	v_mfma_f32_16x16x32_bf16 v[232:235], v[112:115], v[180:183], v[232:235]
	v_mfma_f32_16x16x32_bf16 v[232:235], v[116:119], v[184:187], v[232:235]
	v_mfma_f32_16x16x32_bf16 v[232:235], v[120:123], v[188:191], v[232:235]
	v_mfma_f32_16x16x32_bf16 v[232:235], v[124:127], v[192:195], v[232:235]
	v_mfma_f32_16x16x32_bf16 v[232:235], v[128:131], v[196:199], v[232:235]
	s_waitcnt lgkmcnt(0)
	v_mfma_f32_16x16x32_bf16 v[236:239], v[132:135], v[168:171], 0
	v_mfma_f32_16x16x32_bf16 v[236:239], v[136:139], v[172:175], v[236:239]
	v_mfma_f32_16x16x32_bf16 v[236:239], v[144:147], v[176:179], v[236:239]
	v_mfma_f32_16x16x32_bf16 v[236:239], v[148:151], v[180:183], v[236:239]
	v_mfma_f32_16x16x32_bf16 v[236:239], v[152:155], v[184:187], v[236:239]
	v_mfma_f32_16x16x32_bf16 v[236:239], v[156:159], v[188:191], v[236:239]
	v_mfma_f32_16x16x32_bf16 v[236:239], v[160:163], v[192:195], v[236:239]
	v_mfma_f32_16x16x32_bf16 v[236:239], v[164:167], v[196:199], v[236:239]
	s_nop 7
	s_nop 3
	v_cmp_le_i32_e32 vcc, 96, v244
	s_nop 1
	v_cndmask_b32_e32 v232, 0, v232, vcc
	v_cmp_le_i32_e32 vcc, 97, v244
	s_nop 1
	v_cndmask_b32_e32 v233, 0, v233, vcc
	v_cmp_le_i32_e32 vcc, 98, v244
	s_nop 1
	v_cndmask_b32_e32 v234, 0, v234, vcc
	v_cmp_le_i32_e32 vcc, 99, v244
	s_nop 1
	v_cndmask_b32_e32 v235, 0, v235, vcc
	v_cmp_le_i32_e32 vcc, 112, v244
	s_nop 1
	v_cndmask_b32_e32 v236, 0, v236, vcc
	v_cmp_le_i32_e32 vcc, 113, v244
	s_nop 1
	v_cndmask_b32_e32 v237, 0, v237, vcc
	v_cmp_le_i32_e32 vcc, 114, v244
	s_nop 1
	v_cndmask_b32_e32 v238, 0, v238, vcc
	v_cmp_le_i32_e32 vcc, 115, v244
	s_nop 1
	v_cndmask_b32_e32 v239, 0, v239, vcc
	v_cvt_pk_bf16_f32 v52, v232, v233
	v_cvt_pk_bf16_f32 v53, v234, v235
	v_cvt_pk_bf16_f32 v54, v236, v237
	v_cvt_pk_bf16_f32 v55, v238, v239
	s_cmp_ge_i32 s7, 5
	s_cbranch_scc0 .Lintra_a1_done
	ds_read_b128 v[100:103], v230 offset:0
	ds_read_b128 v[104:107], v230 offset:1024
	ds_read_b128 v[108:111], v230 offset:2048
	ds_read_b128 v[112:115], v230 offset:3072
	ds_read_b128 v[116:119], v230 offset:4096
	ds_read_b128 v[120:123], v230 offset:5120
	ds_read_b128 v[124:127], v230 offset:6144
	ds_read_b128 v[128:131], v230 offset:7168
	ds_read_b128 v[132:135], v230 offset:8192
	ds_read_b128 v[136:139], v230 offset:9216
	ds_read_b128 v[144:147], v230 offset:10240
	ds_read_b128 v[148:151], v230 offset:11264
	ds_read_b128 v[152:155], v230 offset:12288
	ds_read_b128 v[156:159], v230 offset:13312
	ds_read_b128 v[160:163], v230 offset:14336
	ds_read_b128 v[164:167], v230 offset:15360
	s_waitcnt lgkmcnt(8)
	v_mfma_f32_16x16x32_bf16 v[232:235], v[100:103], v[168:171], 0
	v_mfma_f32_16x16x32_bf16 v[232:235], v[104:107], v[172:175], v[232:235]
	v_mfma_f32_16x16x32_bf16 v[232:235], v[108:111], v[176:179], v[232:235]
	v_mfma_f32_16x16x32_bf16 v[232:235], v[112:115], v[180:183], v[232:235]
	v_mfma_f32_16x16x32_bf16 v[232:235], v[116:119], v[184:187], v[232:235]
	v_mfma_f32_16x16x32_bf16 v[232:235], v[120:123], v[188:191], v[232:235]
	v_mfma_f32_16x16x32_bf16 v[232:235], v[124:127], v[192:195], v[232:235]
	v_mfma_f32_16x16x32_bf16 v[232:235], v[128:131], v[196:199], v[232:235]
	s_waitcnt lgkmcnt(0)
	v_mfma_f32_16x16x32_bf16 v[236:239], v[132:135], v[168:171], 0
	v_mfma_f32_16x16x32_bf16 v[236:239], v[136:139], v[172:175], v[236:239]
	v_mfma_f32_16x16x32_bf16 v[236:239], v[144:147], v[176:179], v[236:239]
	v_mfma_f32_16x16x32_bf16 v[236:239], v[148:151], v[180:183], v[236:239]
	v_mfma_f32_16x16x32_bf16 v[236:239], v[152:155], v[184:187], v[236:239]
	v_mfma_f32_16x16x32_bf16 v[236:239], v[156:159], v[188:191], v[236:239]
	v_mfma_f32_16x16x32_bf16 v[236:239], v[160:163], v[192:195], v[236:239]
	v_mfma_f32_16x16x32_bf16 v[236:239], v[164:167], v[196:199], v[236:239]
	s_nop 7
	s_nop 3
	v_cmp_le_i32_e32 vcc, 128, v244
	s_nop 1
	v_cndmask_b32_e32 v232, 0, v232, vcc
	v_cmp_le_i32_e32 vcc, 129, v244
	s_nop 1
	v_cndmask_b32_e32 v233, 0, v233, vcc
	v_cmp_le_i32_e32 vcc, 130, v244
	s_nop 1
	v_cndmask_b32_e32 v234, 0, v234, vcc
	v_cmp_le_i32_e32 vcc, 131, v244
	s_nop 1
	v_cndmask_b32_e32 v235, 0, v235, vcc
	v_cmp_le_i32_e32 vcc, 144, v244
	s_nop 1
	v_cndmask_b32_e32 v236, 0, v236, vcc
	v_cmp_le_i32_e32 vcc, 145, v244
	s_nop 1
	v_cndmask_b32_e32 v237, 0, v237, vcc
	v_cmp_le_i32_e32 vcc, 146, v244
	s_nop 1
	v_cndmask_b32_e32 v238, 0, v238, vcc
	v_cmp_le_i32_e32 vcc, 147, v244
	s_nop 1
	v_cndmask_b32_e32 v239, 0, v239, vcc
	v_cvt_pk_bf16_f32 v48, v232, v233
	v_cvt_pk_bf16_f32 v49, v234, v235
	v_cvt_pk_bf16_f32 v50, v236, v237
	v_cvt_pk_bf16_f32 v51, v238, v239
	s_cmp_ge_i32 s7, 6
	s_cbranch_scc0 .Lintra_a1_done
	ds_read_b128 v[100:103], v230 offset:16384
	ds_read_b128 v[104:107], v230 offset:17408
	ds_read_b128 v[108:111], v230 offset:18432
	ds_read_b128 v[112:115], v230 offset:19456
	ds_read_b128 v[116:119], v230 offset:20480
	ds_read_b128 v[120:123], v230 offset:21504
	ds_read_b128 v[124:127], v230 offset:22528
	ds_read_b128 v[128:131], v230 offset:23552
	ds_read_b128 v[132:135], v230 offset:24576
	ds_read_b128 v[136:139], v230 offset:25600
	ds_read_b128 v[144:147], v230 offset:26624
	ds_read_b128 v[148:151], v230 offset:27648
	ds_read_b128 v[152:155], v230 offset:28672
	ds_read_b128 v[156:159], v230 offset:29696
	ds_read_b128 v[160:163], v230 offset:30720
	ds_read_b128 v[164:167], v230 offset:31744
	s_waitcnt lgkmcnt(8)
	v_mfma_f32_16x16x32_bf16 v[232:235], v[100:103], v[168:171], 0
	v_mfma_f32_16x16x32_bf16 v[232:235], v[104:107], v[172:175], v[232:235]
	v_mfma_f32_16x16x32_bf16 v[232:235], v[108:111], v[176:179], v[232:235]
	v_mfma_f32_16x16x32_bf16 v[232:235], v[112:115], v[180:183], v[232:235]
	v_mfma_f32_16x16x32_bf16 v[232:235], v[116:119], v[184:187], v[232:235]
	v_mfma_f32_16x16x32_bf16 v[232:235], v[120:123], v[188:191], v[232:235]
	v_mfma_f32_16x16x32_bf16 v[232:235], v[124:127], v[192:195], v[232:235]
	v_mfma_f32_16x16x32_bf16 v[232:235], v[128:131], v[196:199], v[232:235]
	s_waitcnt lgkmcnt(0)
	v_mfma_f32_16x16x32_bf16 v[236:239], v[132:135], v[168:171], 0
	v_mfma_f32_16x16x32_bf16 v[236:239], v[136:139], v[172:175], v[236:239]
	v_mfma_f32_16x16x32_bf16 v[236:239], v[144:147], v[176:179], v[236:239]
	v_mfma_f32_16x16x32_bf16 v[236:239], v[148:151], v[180:183], v[236:239]
	v_mfma_f32_16x16x32_bf16 v[236:239], v[152:155], v[184:187], v[236:239]
	v_mfma_f32_16x16x32_bf16 v[236:239], v[156:159], v[188:191], v[236:239]
	v_mfma_f32_16x16x32_bf16 v[236:239], v[160:163], v[192:195], v[236:239]
	v_mfma_f32_16x16x32_bf16 v[236:239], v[164:167], v[196:199], v[236:239]
	s_nop 7
	s_nop 3
	v_cmp_le_i32_e32 vcc, 160, v244
	s_nop 1
	v_cndmask_b32_e32 v232, 0, v232, vcc
	v_cmp_le_i32_e32 vcc, 161, v244
	s_nop 1
	v_cndmask_b32_e32 v233, 0, v233, vcc
	v_cmp_le_i32_e32 vcc, 162, v244
	s_nop 1
	v_cndmask_b32_e32 v234, 0, v234, vcc
	v_cmp_le_i32_e32 vcc, 163, v244
	s_nop 1
	v_cndmask_b32_e32 v235, 0, v235, vcc
	v_cmp_le_i32_e32 vcc, 176, v244
	s_nop 1
	v_cndmask_b32_e32 v236, 0, v236, vcc
	v_cmp_le_i32_e32 vcc, 177, v244
	s_nop 1
	v_cndmask_b32_e32 v237, 0, v237, vcc
	v_cmp_le_i32_e32 vcc, 178, v244
	s_nop 1
	v_cndmask_b32_e32 v238, 0, v238, vcc
	v_cmp_le_i32_e32 vcc, 179, v244
	s_nop 1
	v_cndmask_b32_e32 v239, 0, v239, vcc
	v_cvt_pk_bf16_f32 v44, v232, v233
	v_cvt_pk_bf16_f32 v45, v234, v235
	v_cvt_pk_bf16_f32 v46, v236, v237
	v_cvt_pk_bf16_f32 v47, v238, v239
	s_cmp_ge_i32 s7, 7
	s_cbranch_scc0 .Lintra_a1_done
	ds_read_b128 v[100:103], v230 offset:32768
	ds_read_b128 v[104:107], v230 offset:33792
	ds_read_b128 v[108:111], v230 offset:34816
	ds_read_b128 v[112:115], v230 offset:35840
	ds_read_b128 v[116:119], v230 offset:36864
	ds_read_b128 v[120:123], v230 offset:37888
	ds_read_b128 v[124:127], v230 offset:38912
	ds_read_b128 v[128:131], v230 offset:39936
	ds_read_b128 v[132:135], v230 offset:40960
	ds_read_b128 v[136:139], v230 offset:41984
	ds_read_b128 v[144:147], v230 offset:43008
	ds_read_b128 v[148:151], v230 offset:44032
	ds_read_b128 v[152:155], v230 offset:45056
	ds_read_b128 v[156:159], v230 offset:46080
	ds_read_b128 v[160:163], v230 offset:47104
	ds_read_b128 v[164:167], v230 offset:48128
	s_waitcnt lgkmcnt(8)
	v_mfma_f32_16x16x32_bf16 v[232:235], v[100:103], v[168:171], 0
	v_mfma_f32_16x16x32_bf16 v[232:235], v[104:107], v[172:175], v[232:235]
	v_mfma_f32_16x16x32_bf16 v[232:235], v[108:111], v[176:179], v[232:235]
	v_mfma_f32_16x16x32_bf16 v[232:235], v[112:115], v[180:183], v[232:235]
	v_mfma_f32_16x16x32_bf16 v[232:235], v[116:119], v[184:187], v[232:235]
	v_mfma_f32_16x16x32_bf16 v[232:235], v[120:123], v[188:191], v[232:235]
	v_mfma_f32_16x16x32_bf16 v[232:235], v[124:127], v[192:195], v[232:235]
	v_mfma_f32_16x16x32_bf16 v[232:235], v[128:131], v[196:199], v[232:235]
	s_waitcnt lgkmcnt(0)
	v_mfma_f32_16x16x32_bf16 v[236:239], v[132:135], v[168:171], 0
	v_mfma_f32_16x16x32_bf16 v[236:239], v[136:139], v[172:175], v[236:239]
	v_mfma_f32_16x16x32_bf16 v[236:239], v[144:147], v[176:179], v[236:239]
	v_mfma_f32_16x16x32_bf16 v[236:239], v[148:151], v[180:183], v[236:239]
	v_mfma_f32_16x16x32_bf16 v[236:239], v[152:155], v[184:187], v[236:239]
	v_mfma_f32_16x16x32_bf16 v[236:239], v[156:159], v[188:191], v[236:239]
	v_mfma_f32_16x16x32_bf16 v[236:239], v[160:163], v[192:195], v[236:239]
	v_mfma_f32_16x16x32_bf16 v[236:239], v[164:167], v[196:199], v[236:239]
	s_nop 7
	s_nop 3
	v_cmp_le_i32_e32 vcc, 192, v244
	s_nop 1
	v_cndmask_b32_e32 v232, 0, v232, vcc
	v_cmp_le_i32_e32 vcc, 193, v244
	s_nop 1
	v_cndmask_b32_e32 v233, 0, v233, vcc
	v_cmp_le_i32_e32 vcc, 194, v244
	s_nop 1
	v_cndmask_b32_e32 v234, 0, v234, vcc
	v_cmp_le_i32_e32 vcc, 195, v244
	s_nop 1
	v_cndmask_b32_e32 v235, 0, v235, vcc
	v_cmp_le_i32_e32 vcc, 208, v244
	s_nop 1
	v_cndmask_b32_e32 v236, 0, v236, vcc
	v_cmp_le_i32_e32 vcc, 209, v244
	s_nop 1
	v_cndmask_b32_e32 v237, 0, v237, vcc
	v_cmp_le_i32_e32 vcc, 210, v244
	s_nop 1
	v_cndmask_b32_e32 v238, 0, v238, vcc
	v_cmp_le_i32_e32 vcc, 211, v244
	s_nop 1
	v_cndmask_b32_e32 v239, 0, v239, vcc
	v_cvt_pk_bf16_f32 v40, v232, v233
	v_cvt_pk_bf16_f32 v41, v234, v235
	v_cvt_pk_bf16_f32 v42, v236, v237
	v_cvt_pk_bf16_f32 v43, v238, v239
	s_cmp_ge_i32 s7, 8
	s_cbranch_scc0 .Lintra_a1_done
	ds_read_b128 v[100:103], v230 offset:49152
	ds_read_b128 v[104:107], v230 offset:50176
	ds_read_b128 v[108:111], v230 offset:51200
	ds_read_b128 v[112:115], v230 offset:52224
	ds_read_b128 v[116:119], v230 offset:53248
	ds_read_b128 v[120:123], v230 offset:54272
	ds_read_b128 v[124:127], v230 offset:55296
	ds_read_b128 v[128:131], v230 offset:56320
	ds_read_b128 v[132:135], v230 offset:57344
	ds_read_b128 v[136:139], v230 offset:58368
	ds_read_b128 v[144:147], v230 offset:59392
	ds_read_b128 v[148:151], v230 offset:60416
	ds_read_b128 v[152:155], v230 offset:61440
	ds_read_b128 v[156:159], v230 offset:62464
	ds_read_b128 v[160:163], v230 offset:63488
	ds_read_b128 v[164:167], v230 offset:64512
	s_waitcnt lgkmcnt(8)
	v_mfma_f32_16x16x32_bf16 v[232:235], v[100:103], v[168:171], 0
	v_mfma_f32_16x16x32_bf16 v[232:235], v[104:107], v[172:175], v[232:235]
	v_mfma_f32_16x16x32_bf16 v[232:235], v[108:111], v[176:179], v[232:235]
	v_mfma_f32_16x16x32_bf16 v[232:235], v[112:115], v[180:183], v[232:235]
	v_mfma_f32_16x16x32_bf16 v[232:235], v[116:119], v[184:187], v[232:235]
	v_mfma_f32_16x16x32_bf16 v[232:235], v[120:123], v[188:191], v[232:235]
	v_mfma_f32_16x16x32_bf16 v[232:235], v[124:127], v[192:195], v[232:235]
	v_mfma_f32_16x16x32_bf16 v[232:235], v[128:131], v[196:199], v[232:235]
	s_waitcnt lgkmcnt(0)
	v_mfma_f32_16x16x32_bf16 v[236:239], v[132:135], v[168:171], 0
	v_mfma_f32_16x16x32_bf16 v[236:239], v[136:139], v[172:175], v[236:239]
	v_mfma_f32_16x16x32_bf16 v[236:239], v[144:147], v[176:179], v[236:239]
	v_mfma_f32_16x16x32_bf16 v[236:239], v[148:151], v[180:183], v[236:239]
	v_mfma_f32_16x16x32_bf16 v[236:239], v[152:155], v[184:187], v[236:239]
	v_mfma_f32_16x16x32_bf16 v[236:239], v[156:159], v[188:191], v[236:239]
	v_mfma_f32_16x16x32_bf16 v[236:239], v[160:163], v[192:195], v[236:239]
	v_mfma_f32_16x16x32_bf16 v[236:239], v[164:167], v[196:199], v[236:239]
	s_nop 7
	s_nop 3
	v_cmp_le_i32_e32 vcc, 224, v244
	s_nop 1
	v_cndmask_b32_e32 v232, 0, v232, vcc
	v_cmp_le_i32_e32 vcc, 225, v244
	s_nop 1
	v_cndmask_b32_e32 v233, 0, v233, vcc
	v_cmp_le_i32_e32 vcc, 226, v244
	s_nop 1
	v_cndmask_b32_e32 v234, 0, v234, vcc
	v_cmp_le_i32_e32 vcc, 227, v244
	s_nop 1
	v_cndmask_b32_e32 v235, 0, v235, vcc
	v_cmp_le_i32_e32 vcc, 240, v244
	s_nop 1
	v_cndmask_b32_e32 v236, 0, v236, vcc
	v_cmp_le_i32_e32 vcc, 241, v244
	s_nop 1
	v_cndmask_b32_e32 v237, 0, v237, vcc
	v_cmp_le_i32_e32 vcc, 242, v244
	s_nop 1
	v_cndmask_b32_e32 v238, 0, v238, vcc
	v_cmp_le_i32_e32 vcc, 243, v244
	s_nop 1
	v_cndmask_b32_e32 v239, 0, v239, vcc
	v_cvt_pk_bf16_f32 v36, v232, v233
	v_cvt_pk_bf16_f32 v37, v234, v235
	v_cvt_pk_bf16_f32 v38, v236, v237
	v_cvt_pk_bf16_f32 v39, v238, v239
.Lintra_a1_done:
	s_waitcnt lgkmcnt(0)
	s_barrier
	s_mov_b32 s0, 0
	s_mov_b32 s1, 0
	s_add_u32 s34, s18, s0
	s_addc_u32 s35, s19, 0
	s_add_u32 s34, s34, s11
	s_addc_u32 s35, s35, 0
	s_add_i32 s1, s1, s11
	s_add_i32 m0, s1, 0
	s_nop 0
	global_load_lds_dwordx4 v200, s[34:35]
	s_add_i32 m0, s1, 1024
	s_add_u32 s34, s34, 0x400
	s_addc_u32 s35, s35, 0
	global_load_lds_dwordx4 v200, s[34:35]
	s_add_i32 m0, s1, 2048
	s_add_u32 s34, s34, 0x400
	s_addc_u32 s35, s35, 0
	global_load_lds_dwordx4 v200, s[34:35]
	s_add_i32 m0, s1, 3072
	s_add_u32 s34, s34, 0x400
	s_addc_u32 s35, s35, 0
	global_load_lds_dwordx4 v200, s[34:35]
	s_add_i32 m0, s1, 4096
	s_add_u32 s34, s34, 0x400
	s_addc_u32 s35, s35, 0
	global_load_lds_dwordx4 v200, s[34:35]
	s_add_i32 m0, s1, 5120
	s_add_u32 s34, s34, 0x400
	s_addc_u32 s35, s35, 0
	global_load_lds_dwordx4 v200, s[34:35]
	s_add_i32 m0, s1, 6144
	s_add_u32 s34, s34, 0x400
	s_addc_u32 s35, s35, 0
	global_load_lds_dwordx4 v200, s[34:35]
	s_add_i32 m0, s1, 7168
	s_add_u32 s34, s34, 0x400
	s_addc_u32 s35, s35, 0
	global_load_lds_dwordx4 v200, s[34:35]
	v_mov_b32_e32 v202, 0
	v_mov_b32_e32 v203, 0
	v_mov_b32_e32 v245, 0
	v_mov_b32_e32 v246, 0
	s_mov_b32 s10, 0
.Lintra_hf:
	s_waitcnt vmcnt(0) lgkmcnt(0)
	s_barrier
	s_lshl_b32 s0, s3, 15
	s_lshl_b32 s1, s10, 13
	s_add_i32 s0, s0, s1
	s_add_u32 s34, s16, s0
	s_addc_u32 s35, s17, 0
	s_add_i32 s1, s11, 0x10000
	s_add_i32 m0, s1, 0
	s_nop 0
	global_load_lds_dwordx4 v200, s[34:35]
	s_add_i32 m0, s1, 1024
	s_add_u32 s34, s34, 0x400
	s_addc_u32 s35, s35, 0
	global_load_lds_dwordx4 v200, s[34:35]
	s_add_i32 m0, s1, 2048
	s_add_u32 s34, s34, 0x400
	s_addc_u32 s35, s35, 0
	global_load_lds_dwordx4 v200, s[34:35]
	s_add_i32 m0, s1, 3072
	s_add_u32 s34, s34, 0x400
	s_addc_u32 s35, s35, 0
	global_load_lds_dwordx4 v200, s[34:35]
	s_add_i32 m0, s1, 4096
	s_add_u32 s34, s34, 0x400
	s_addc_u32 s35, s35, 0
	global_load_lds_dwordx4 v200, s[34:35]
	s_add_i32 m0, s1, 5120
	s_add_u32 s34, s34, 0x400
	s_addc_u32 s35, s35, 0
	global_load_lds_dwordx4 v200, s[34:35]
	s_add_i32 m0, s1, 6144
	s_add_u32 s34, s34, 0x400
	s_addc_u32 s35, s35, 0
	global_load_lds_dwordx4 v200, s[34:35]
	s_add_i32 m0, s1, 7168
	s_add_u32 s34, s34, 0x400
	s_addc_u32 s35, s35, 0
	global_load_lds_dwordx4 v200, s[34:35]
	ds_read_b128 v[100:103], v207 offset:0
	ds_read_b128 v[104:107], v207 offset:8192
	ds_read_b128 v[108:111], v207 offset:16384
	ds_read_b128 v[112:115], v207 offset:24576
	ds_read_b128 v[116:119], v207 offset:32768
	ds_read_b128 v[120:123], v207 offset:40960
	ds_read_b128 v[124:127], v207 offset:49152
	ds_read_b128 v[128:131], v207 offset:57344
	s_waitcnt lgkmcnt(4)
	v_mfma_f32_16x16x32_bf16 v[68:71], v[100:103], v[0:3], 0
	v_mfma_f32_16x16x32_bf16 v[132:135], v[100:103], v[168:171], 0
	v_mfma_f32_16x16x32_bf16 v[72:75], v[104:107], v[0:3], 0
	v_mfma_f32_16x16x32_bf16 v[136:139], v[104:107], v[168:171], 0
	v_mfma_f32_16x16x32_bf16 v[76:79], v[108:111], v[0:3], 0
	v_mfma_f32_16x16x32_bf16 v[144:147], v[108:111], v[168:171], 0
	v_mfma_f32_16x16x32_bf16 v[80:83], v[112:115], v[0:3], 0
	v_mfma_f32_16x16x32_bf16 v[148:151], v[112:115], v[168:171], 0
	s_waitcnt lgkmcnt(0)
	v_mfma_f32_16x16x32_bf16 v[84:87], v[116:119], v[0:3], 0
	v_mfma_f32_16x16x32_bf16 v[152:155], v[116:119], v[168:171], 0
	v_mfma_f32_16x16x32_bf16 v[88:91], v[120:123], v[0:3], 0
	v_mfma_f32_16x16x32_bf16 v[156:159], v[120:123], v[168:171], 0
	v_mfma_f32_16x16x32_bf16 v[92:95], v[124:127], v[0:3], 0
	v_mfma_f32_16x16x32_bf16 v[160:163], v[124:127], v[168:171], 0
	v_mfma_f32_16x16x32_bf16 v[96:99], v[128:131], v[0:3], 0
	v_mfma_f32_16x16x32_bf16 v[164:167], v[128:131], v[168:171], 0
	ds_read_b128 v[100:103], v207 offset:1024
	ds_read_b128 v[104:107], v207 offset:9216
	ds_read_b128 v[108:111], v207 offset:17408
	ds_read_b128 v[112:115], v207 offset:25600
	ds_read_b128 v[116:119], v207 offset:33792
	ds_read_b128 v[120:123], v207 offset:41984
	ds_read_b128 v[124:127], v207 offset:50176
	ds_read_b128 v[128:131], v207 offset:58368
	s_waitcnt lgkmcnt(4)
	v_mfma_f32_16x16x32_bf16 v[68:71], v[100:103], v[4:7], v[68:71]
	v_mfma_f32_16x16x32_bf16 v[132:135], v[100:103], v[172:175], v[132:135]
	v_mfma_f32_16x16x32_bf16 v[72:75], v[104:107], v[4:7], v[72:75]
	v_mfma_f32_16x16x32_bf16 v[136:139], v[104:107], v[172:175], v[136:139]
	v_mfma_f32_16x16x32_bf16 v[76:79], v[108:111], v[4:7], v[76:79]
	v_mfma_f32_16x16x32_bf16 v[144:147], v[108:111], v[172:175], v[144:147]
	v_mfma_f32_16x16x32_bf16 v[80:83], v[112:115], v[4:7], v[80:83]
	v_mfma_f32_16x16x32_bf16 v[148:151], v[112:115], v[172:175], v[148:151]
	s_waitcnt lgkmcnt(0)
	v_mfma_f32_16x16x32_bf16 v[84:87], v[116:119], v[4:7], v[84:87]
	v_mfma_f32_16x16x32_bf16 v[152:155], v[116:119], v[172:175], v[152:155]
	v_mfma_f32_16x16x32_bf16 v[88:91], v[120:123], v[4:7], v[88:91]
	v_mfma_f32_16x16x32_bf16 v[156:159], v[120:123], v[172:175], v[156:159]
	v_mfma_f32_16x16x32_bf16 v[92:95], v[124:127], v[4:7], v[92:95]
	v_mfma_f32_16x16x32_bf16 v[160:163], v[124:127], v[172:175], v[160:163]
	v_mfma_f32_16x16x32_bf16 v[96:99], v[128:131], v[4:7], v[96:99]
	v_mfma_f32_16x16x32_bf16 v[164:167], v[128:131], v[172:175], v[164:167]
	ds_read_b128 v[100:103], v207 offset:2048
	ds_read_b128 v[104:107], v207 offset:10240
	ds_read_b128 v[108:111], v207 offset:18432
	ds_read_b128 v[112:115], v207 offset:26624
	ds_read_b128 v[116:119], v207 offset:34816
	ds_read_b128 v[120:123], v207 offset:43008
	ds_read_b128 v[124:127], v207 offset:51200
	ds_read_b128 v[128:131], v207 offset:59392
	s_waitcnt lgkmcnt(4)
	v_mfma_f32_16x16x32_bf16 v[68:71], v[100:103], v[8:11], v[68:71]
	v_mfma_f32_16x16x32_bf16 v[132:135], v[100:103], v[176:179], v[132:135]
	v_mfma_f32_16x16x32_bf16 v[72:75], v[104:107], v[8:11], v[72:75]
	v_mfma_f32_16x16x32_bf16 v[136:139], v[104:107], v[176:179], v[136:139]
	v_mfma_f32_16x16x32_bf16 v[76:79], v[108:111], v[8:11], v[76:79]
	v_mfma_f32_16x16x32_bf16 v[144:147], v[108:111], v[176:179], v[144:147]
	v_mfma_f32_16x16x32_bf16 v[80:83], v[112:115], v[8:11], v[80:83]
	v_mfma_f32_16x16x32_bf16 v[148:151], v[112:115], v[176:179], v[148:151]
	s_waitcnt lgkmcnt(0)
	v_mfma_f32_16x16x32_bf16 v[84:87], v[116:119], v[8:11], v[84:87]
	v_mfma_f32_16x16x32_bf16 v[152:155], v[116:119], v[176:179], v[152:155]
	v_mfma_f32_16x16x32_bf16 v[88:91], v[120:123], v[8:11], v[88:91]
	v_mfma_f32_16x16x32_bf16 v[156:159], v[120:123], v[176:179], v[156:159]
	v_mfma_f32_16x16x32_bf16 v[92:95], v[124:127], v[8:11], v[92:95]
	v_mfma_f32_16x16x32_bf16 v[160:163], v[124:127], v[176:179], v[160:163]
	v_mfma_f32_16x16x32_bf16 v[96:99], v[128:131], v[8:11], v[96:99]
	v_mfma_f32_16x16x32_bf16 v[164:167], v[128:131], v[176:179], v[164:167]
	ds_read_b128 v[100:103], v207 offset:3072
	ds_read_b128 v[104:107], v207 offset:11264
	ds_read_b128 v[108:111], v207 offset:19456
	ds_read_b128 v[112:115], v207 offset:27648
	ds_read_b128 v[116:119], v207 offset:35840
	ds_read_b128 v[120:123], v207 offset:44032
	ds_read_b128 v[124:127], v207 offset:52224
	ds_read_b128 v[128:131], v207 offset:60416
	s_waitcnt lgkmcnt(4)
	v_mfma_f32_16x16x32_bf16 v[68:71], v[100:103], v[12:15], v[68:71]
	v_mfma_f32_16x16x32_bf16 v[132:135], v[100:103], v[180:183], v[132:135]
	v_mfma_f32_16x16x32_bf16 v[72:75], v[104:107], v[12:15], v[72:75]
	v_mfma_f32_16x16x32_bf16 v[136:139], v[104:107], v[180:183], v[136:139]
	v_mfma_f32_16x16x32_bf16 v[76:79], v[108:111], v[12:15], v[76:79]
	v_mfma_f32_16x16x32_bf16 v[144:147], v[108:111], v[180:183], v[144:147]
	v_mfma_f32_16x16x32_bf16 v[80:83], v[112:115], v[12:15], v[80:83]
	v_mfma_f32_16x16x32_bf16 v[148:151], v[112:115], v[180:183], v[148:151]
	s_waitcnt lgkmcnt(0)
	v_mfma_f32_16x16x32_bf16 v[84:87], v[116:119], v[12:15], v[84:87]
	v_mfma_f32_16x16x32_bf16 v[152:155], v[116:119], v[180:183], v[152:155]
	v_mfma_f32_16x16x32_bf16 v[88:91], v[120:123], v[12:15], v[88:91]
	v_mfma_f32_16x16x32_bf16 v[156:159], v[120:123], v[180:183], v[156:159]
	v_mfma_f32_16x16x32_bf16 v[92:95], v[124:127], v[12:15], v[92:95]
	v_mfma_f32_16x16x32_bf16 v[160:163], v[124:127], v[180:183], v[160:163]
	v_mfma_f32_16x16x32_bf16 v[96:99], v[128:131], v[12:15], v[96:99]
	v_mfma_f32_16x16x32_bf16 v[164:167], v[128:131], v[180:183], v[164:167]
	ds_read_b128 v[100:103], v207 offset:4096
	ds_read_b128 v[104:107], v207 offset:12288
	ds_read_b128 v[108:111], v207 offset:20480
	ds_read_b128 v[112:115], v207 offset:28672
	ds_read_b128 v[116:119], v207 offset:36864
	ds_read_b128 v[120:123], v207 offset:45056
	ds_read_b128 v[124:127], v207 offset:53248
	ds_read_b128 v[128:131], v207 offset:61440
	s_waitcnt lgkmcnt(4)
	v_mfma_f32_16x16x32_bf16 v[68:71], v[100:103], v[16:19], v[68:71]
	v_mfma_f32_16x16x32_bf16 v[132:135], v[100:103], v[184:187], v[132:135]
	v_mfma_f32_16x16x32_bf16 v[72:75], v[104:107], v[16:19], v[72:75]
	v_mfma_f32_16x16x32_bf16 v[136:139], v[104:107], v[184:187], v[136:139]
	v_mfma_f32_16x16x32_bf16 v[76:79], v[108:111], v[16:19], v[76:79]
	v_mfma_f32_16x16x32_bf16 v[144:147], v[108:111], v[184:187], v[144:147]
	v_mfma_f32_16x16x32_bf16 v[80:83], v[112:115], v[16:19], v[80:83]
	v_mfma_f32_16x16x32_bf16 v[148:151], v[112:115], v[184:187], v[148:151]
	s_waitcnt lgkmcnt(0)
	v_mfma_f32_16x16x32_bf16 v[84:87], v[116:119], v[16:19], v[84:87]
	v_mfma_f32_16x16x32_bf16 v[152:155], v[116:119], v[184:187], v[152:155]
	v_mfma_f32_16x16x32_bf16 v[88:91], v[120:123], v[16:19], v[88:91]
	v_mfma_f32_16x16x32_bf16 v[156:159], v[120:123], v[184:187], v[156:159]
	v_mfma_f32_16x16x32_bf16 v[92:95], v[124:127], v[16:19], v[92:95]
	v_mfma_f32_16x16x32_bf16 v[160:163], v[124:127], v[184:187], v[160:163]
	v_mfma_f32_16x16x32_bf16 v[96:99], v[128:131], v[16:19], v[96:99]
	v_mfma_f32_16x16x32_bf16 v[164:167], v[128:131], v[184:187], v[164:167]
	ds_read_b128 v[100:103], v207 offset:5120
	ds_read_b128 v[104:107], v207 offset:13312
	ds_read_b128 v[108:111], v207 offset:21504
	ds_read_b128 v[112:115], v207 offset:29696
	ds_read_b128 v[116:119], v207 offset:37888
	ds_read_b128 v[120:123], v207 offset:46080
	ds_read_b128 v[124:127], v207 offset:54272
	ds_read_b128 v[128:131], v207 offset:62464
	s_waitcnt lgkmcnt(4)
	v_mfma_f32_16x16x32_bf16 v[68:71], v[100:103], v[20:23], v[68:71]
	v_mfma_f32_16x16x32_bf16 v[132:135], v[100:103], v[188:191], v[132:135]
	v_mfma_f32_16x16x32_bf16 v[72:75], v[104:107], v[20:23], v[72:75]
	v_mfma_f32_16x16x32_bf16 v[136:139], v[104:107], v[188:191], v[136:139]
	v_mfma_f32_16x16x32_bf16 v[76:79], v[108:111], v[20:23], v[76:79]
	v_mfma_f32_16x16x32_bf16 v[144:147], v[108:111], v[188:191], v[144:147]
	v_mfma_f32_16x16x32_bf16 v[80:83], v[112:115], v[20:23], v[80:83]
	v_mfma_f32_16x16x32_bf16 v[148:151], v[112:115], v[188:191], v[148:151]
	s_waitcnt lgkmcnt(0)
	v_mfma_f32_16x16x32_bf16 v[84:87], v[116:119], v[20:23], v[84:87]
	v_mfma_f32_16x16x32_bf16 v[152:155], v[116:119], v[188:191], v[152:155]
	v_mfma_f32_16x16x32_bf16 v[88:91], v[120:123], v[20:23], v[88:91]
	v_mfma_f32_16x16x32_bf16 v[156:159], v[120:123], v[188:191], v[156:159]
	v_mfma_f32_16x16x32_bf16 v[92:95], v[124:127], v[20:23], v[92:95]
	v_mfma_f32_16x16x32_bf16 v[160:163], v[124:127], v[188:191], v[160:163]
	v_mfma_f32_16x16x32_bf16 v[96:99], v[128:131], v[20:23], v[96:99]
	v_mfma_f32_16x16x32_bf16 v[164:167], v[128:131], v[188:191], v[164:167]
	ds_read_b128 v[100:103], v207 offset:6144
	ds_read_b128 v[104:107], v207 offset:14336
	ds_read_b128 v[108:111], v207 offset:22528
	ds_read_b128 v[112:115], v207 offset:30720
	ds_read_b128 v[116:119], v207 offset:38912
	ds_read_b128 v[120:123], v207 offset:47104
	ds_read_b128 v[124:127], v207 offset:55296
	ds_read_b128 v[128:131], v207 offset:63488
	s_waitcnt lgkmcnt(4)
	v_mfma_f32_16x16x32_bf16 v[68:71], v[100:103], v[24:27], v[68:71]
	v_mfma_f32_16x16x32_bf16 v[132:135], v[100:103], v[192:195], v[132:135]
	v_mfma_f32_16x16x32_bf16 v[72:75], v[104:107], v[24:27], v[72:75]
	v_mfma_f32_16x16x32_bf16 v[136:139], v[104:107], v[192:195], v[136:139]
	v_mfma_f32_16x16x32_bf16 v[76:79], v[108:111], v[24:27], v[76:79]
	v_mfma_f32_16x16x32_bf16 v[144:147], v[108:111], v[192:195], v[144:147]
	v_mfma_f32_16x16x32_bf16 v[80:83], v[112:115], v[24:27], v[80:83]
	v_mfma_f32_16x16x32_bf16 v[148:151], v[112:115], v[192:195], v[148:151]
	s_waitcnt lgkmcnt(0)
	v_mfma_f32_16x16x32_bf16 v[84:87], v[116:119], v[24:27], v[84:87]
	v_mfma_f32_16x16x32_bf16 v[152:155], v[116:119], v[192:195], v[152:155]
	v_mfma_f32_16x16x32_bf16 v[88:91], v[120:123], v[24:27], v[88:91]
	v_mfma_f32_16x16x32_bf16 v[156:159], v[120:123], v[192:195], v[156:159]
	v_mfma_f32_16x16x32_bf16 v[92:95], v[124:127], v[24:27], v[92:95]
	v_mfma_f32_16x16x32_bf16 v[160:163], v[124:127], v[192:195], v[160:163]
	v_mfma_f32_16x16x32_bf16 v[96:99], v[128:131], v[24:27], v[96:99]
	v_mfma_f32_16x16x32_bf16 v[164:167], v[128:131], v[192:195], v[164:167]
	ds_read_b128 v[100:103], v207 offset:7168
	ds_read_b128 v[104:107], v207 offset:15360
	ds_read_b128 v[108:111], v207 offset:23552
	ds_read_b128 v[112:115], v207 offset:31744
	ds_read_b128 v[116:119], v207 offset:39936
	ds_read_b128 v[120:123], v207 offset:48128
	ds_read_b128 v[124:127], v207 offset:56320
	ds_read_b128 v[128:131], v207 offset:64512
	s_waitcnt lgkmcnt(4)
	v_mfma_f32_16x16x32_bf16 v[68:71], v[100:103], v[28:31], v[68:71]
	v_mfma_f32_16x16x32_bf16 v[132:135], v[100:103], v[196:199], v[132:135]
	v_mfma_f32_16x16x32_bf16 v[72:75], v[104:107], v[28:31], v[72:75]
	v_mfma_f32_16x16x32_bf16 v[136:139], v[104:107], v[196:199], v[136:139]
	v_mfma_f32_16x16x32_bf16 v[76:79], v[108:111], v[28:31], v[76:79]
	v_mfma_f32_16x16x32_bf16 v[144:147], v[108:111], v[196:199], v[144:147]
	v_mfma_f32_16x16x32_bf16 v[80:83], v[112:115], v[28:31], v[80:83]
	v_mfma_f32_16x16x32_bf16 v[148:151], v[112:115], v[196:199], v[148:151]
	s_waitcnt lgkmcnt(0)
	v_mfma_f32_16x16x32_bf16 v[84:87], v[116:119], v[28:31], v[84:87]
	v_mfma_f32_16x16x32_bf16 v[152:155], v[116:119], v[196:199], v[152:155]
	v_mfma_f32_16x16x32_bf16 v[88:91], v[120:123], v[28:31], v[88:91]
	v_mfma_f32_16x16x32_bf16 v[156:159], v[120:123], v[196:199], v[156:159]
	v_mfma_f32_16x16x32_bf16 v[92:95], v[124:127], v[28:31], v[92:95]
	v_mfma_f32_16x16x32_bf16 v[160:163], v[124:127], v[196:199], v[160:163]
	v_mfma_f32_16x16x32_bf16 v[96:99], v[128:131], v[28:31], v[96:99]
	v_mfma_f32_16x16x32_bf16 v[164:167], v[128:131], v[196:199], v[164:167]
	s_waitcnt vmcnt(0)
	s_barrier
	s_cmp_lt_i32 s10, 3
	s_cbranch_scc0 .Lintra_nodma
	s_add_i32 s0, s10, 1
	s_lshl_b32 s0, s0, 16
	s_mov_b32 s1, 0
	s_add_u32 s34, s18, s0
	s_addc_u32 s35, s19, 0
	s_add_u32 s34, s34, s11
	s_addc_u32 s35, s35, 0
	s_add_i32 s1, s1, s11
	s_add_i32 m0, s1, 0
	s_nop 0
	global_load_lds_dwordx4 v200, s[34:35]
	s_add_i32 m0, s1, 1024
	s_add_u32 s34, s34, 0x400
	s_addc_u32 s35, s35, 0
	global_load_lds_dwordx4 v200, s[34:35]
	s_add_i32 m0, s1, 2048
	s_add_u32 s34, s34, 0x400
	s_addc_u32 s35, s35, 0
	global_load_lds_dwordx4 v200, s[34:35]
	s_add_i32 m0, s1, 3072
	s_add_u32 s34, s34, 0x400
	s_addc_u32 s35, s35, 0
	global_load_lds_dwordx4 v200, s[34:35]
	s_add_i32 m0, s1, 4096
	s_add_u32 s34, s34, 0x400
	s_addc_u32 s35, s35, 0
	global_load_lds_dwordx4 v200, s[34:35]
	s_add_i32 m0, s1, 5120
	s_add_u32 s34, s34, 0x400
	s_addc_u32 s35, s35, 0
	global_load_lds_dwordx4 v200, s[34:35]
	s_add_i32 m0, s1, 6144
	s_add_u32 s34, s34, 0x400
	s_addc_u32 s35, s35, 0
	global_load_lds_dwordx4 v200, s[34:35]
	s_add_i32 m0, s1, 7168
	s_add_u32 s34, s34, 0x400
	s_addc_u32 s35, s35, 0
	global_load_lds_dwordx4 v200, s[34:35]
.Lintra_nodma:
	ds_read_b128 v[100:103], v230 offset:0
	ds_read_b128 v[104:107], v230 offset:1024
	ds_read_b128 v[108:111], v230 offset:2048
	ds_read_b128 v[112:115], v230 offset:3072
	ds_read_b128 v[116:119], v230 offset:4096
	ds_read_b128 v[120:123], v230 offset:5120
	ds_read_b128 v[124:127], v230 offset:6144
	ds_read_b128 v[128:131], v230 offset:7168
	s_cmp_ge_i32 s6, 1
	s_cbranch_scc0 .Lintra_v0_u1
	s_waitcnt lgkmcnt(4)
	v_mfma_f32_16x16x32_bf16 v[68:71], v[100:103], v[32:35], v[68:71]
	v_mfma_f32_16x16x32_bf16 v[72:75], v[104:107], v[32:35], v[72:75]
	v_mfma_f32_16x16x32_bf16 v[76:79], v[108:111], v[32:35], v[76:79]
	v_mfma_f32_16x16x32_bf16 v[80:83], v[112:115], v[32:35], v[80:83]
	s_waitcnt lgkmcnt(0)
	v_mfma_f32_16x16x32_bf16 v[84:87], v[116:119], v[32:35], v[84:87]
	v_mfma_f32_16x16x32_bf16 v[88:91], v[120:123], v[32:35], v[88:91]
	v_mfma_f32_16x16x32_bf16 v[92:95], v[124:127], v[32:35], v[92:95]
	v_mfma_f32_16x16x32_bf16 v[96:99], v[128:131], v[32:35], v[96:99]
.Lintra_v0_u1:
	s_waitcnt lgkmcnt(4)
	v_mfma_f32_16x16x32_bf16 v[132:135], v[100:103], v[240:243], v[132:135]
	v_mfma_f32_16x16x32_bf16 v[136:139], v[104:107], v[240:243], v[136:139]
	v_mfma_f32_16x16x32_bf16 v[144:147], v[108:111], v[240:243], v[144:147]
	v_mfma_f32_16x16x32_bf16 v[148:151], v[112:115], v[240:243], v[148:151]
	s_waitcnt lgkmcnt(0)
	v_mfma_f32_16x16x32_bf16 v[152:155], v[116:119], v[240:243], v[152:155]
	v_mfma_f32_16x16x32_bf16 v[156:159], v[120:123], v[240:243], v[156:159]
	v_mfma_f32_16x16x32_bf16 v[160:163], v[124:127], v[240:243], v[160:163]
	v_mfma_f32_16x16x32_bf16 v[164:167], v[128:131], v[240:243], v[164:167]
	s_cmp_ge_i32 s7, 2
	s_cbranch_scc0 .Lintra_hfend
	ds_read_b128 v[100:103], v230 offset:8192
	ds_read_b128 v[104:107], v230 offset:9216
	ds_read_b128 v[108:111], v230 offset:10240
	ds_read_b128 v[112:115], v230 offset:11264
	ds_read_b128 v[116:119], v230 offset:12288
	ds_read_b128 v[120:123], v230 offset:13312
	ds_read_b128 v[124:127], v230 offset:14336
	ds_read_b128 v[128:131], v230 offset:15360
	s_cmp_ge_i32 s6, 2
	s_cbranch_scc0 .Lintra_v1_u1
	s_waitcnt lgkmcnt(4)
	v_mfma_f32_16x16x32_bf16 v[68:71], v[100:103], v[36:39], v[68:71]
	v_mfma_f32_16x16x32_bf16 v[72:75], v[104:107], v[36:39], v[72:75]
	v_mfma_f32_16x16x32_bf16 v[76:79], v[108:111], v[36:39], v[76:79]
	v_mfma_f32_16x16x32_bf16 v[80:83], v[112:115], v[36:39], v[80:83]
	s_waitcnt lgkmcnt(0)
	v_mfma_f32_16x16x32_bf16 v[84:87], v[116:119], v[36:39], v[84:87]
	v_mfma_f32_16x16x32_bf16 v[88:91], v[120:123], v[36:39], v[88:91]
	v_mfma_f32_16x16x32_bf16 v[92:95], v[124:127], v[36:39], v[92:95]
	v_mfma_f32_16x16x32_bf16 v[96:99], v[128:131], v[36:39], v[96:99]
.Lintra_v1_u1:
	s_waitcnt lgkmcnt(4)
	v_mfma_f32_16x16x32_bf16 v[132:135], v[100:103], v[60:63], v[132:135]
	v_mfma_f32_16x16x32_bf16 v[136:139], v[104:107], v[60:63], v[136:139]
	v_mfma_f32_16x16x32_bf16 v[144:147], v[108:111], v[60:63], v[144:147]
	v_mfma_f32_16x16x32_bf16 v[148:151], v[112:115], v[60:63], v[148:151]
	s_waitcnt lgkmcnt(0)
	v_mfma_f32_16x16x32_bf16 v[152:155], v[116:119], v[60:63], v[152:155]
	v_mfma_f32_16x16x32_bf16 v[156:159], v[120:123], v[60:63], v[156:159]
	v_mfma_f32_16x16x32_bf16 v[160:163], v[124:127], v[60:63], v[160:163]
	v_mfma_f32_16x16x32_bf16 v[164:167], v[128:131], v[60:63], v[164:167]
	s_cmp_ge_i32 s7, 3
	s_cbranch_scc0 .Lintra_hfend
	ds_read_b128 v[100:103], v230 offset:16384
	ds_read_b128 v[104:107], v230 offset:17408
	ds_read_b128 v[108:111], v230 offset:18432
	ds_read_b128 v[112:115], v230 offset:19456
	ds_read_b128 v[116:119], v230 offset:20480
	ds_read_b128 v[120:123], v230 offset:21504
	ds_read_b128 v[124:127], v230 offset:22528
	ds_read_b128 v[128:131], v230 offset:23552
	s_cmp_ge_i32 s6, 3
	s_cbranch_scc0 .Lintra_v2_u1
	s_waitcnt lgkmcnt(4)
	v_mfma_f32_16x16x32_bf16 v[68:71], v[100:103], v[40:43], v[68:71]
	v_mfma_f32_16x16x32_bf16 v[72:75], v[104:107], v[40:43], v[72:75]
	v_mfma_f32_16x16x32_bf16 v[76:79], v[108:111], v[40:43], v[76:79]
	v_mfma_f32_16x16x32_bf16 v[80:83], v[112:115], v[40:43], v[80:83]
	s_waitcnt lgkmcnt(0)
	v_mfma_f32_16x16x32_bf16 v[84:87], v[116:119], v[40:43], v[84:87]
	v_mfma_f32_16x16x32_bf16 v[88:91], v[120:123], v[40:43], v[88:91]
	v_mfma_f32_16x16x32_bf16 v[92:95], v[124:127], v[40:43], v[92:95]
	v_mfma_f32_16x16x32_bf16 v[96:99], v[128:131], v[40:43], v[96:99]
.Lintra_v2_u1:
	s_waitcnt lgkmcnt(4)
	v_mfma_f32_16x16x32_bf16 v[132:135], v[100:103], v[56:59], v[132:135]
	v_mfma_f32_16x16x32_bf16 v[136:139], v[104:107], v[56:59], v[136:139]
	v_mfma_f32_16x16x32_bf16 v[144:147], v[108:111], v[56:59], v[144:147]
	v_mfma_f32_16x16x32_bf16 v[148:151], v[112:115], v[56:59], v[148:151]
	s_waitcnt lgkmcnt(0)
	v_mfma_f32_16x16x32_bf16 v[152:155], v[116:119], v[56:59], v[152:155]
	v_mfma_f32_16x16x32_bf16 v[156:159], v[120:123], v[56:59], v[156:159]
	v_mfma_f32_16x16x32_bf16 v[160:163], v[124:127], v[56:59], v[160:163]
	v_mfma_f32_16x16x32_bf16 v[164:167], v[128:131], v[56:59], v[164:167]
	s_cmp_ge_i32 s7, 4
	s_cbranch_scc0 .Lintra_hfend
	ds_read_b128 v[100:103], v230 offset:24576
	ds_read_b128 v[104:107], v230 offset:25600
	ds_read_b128 v[108:111], v230 offset:26624
	ds_read_b128 v[112:115], v230 offset:27648
	ds_read_b128 v[116:119], v230 offset:28672
	ds_read_b128 v[120:123], v230 offset:29696
	ds_read_b128 v[124:127], v230 offset:30720
	ds_read_b128 v[128:131], v230 offset:31744
	s_cmp_ge_i32 s6, 4
	s_cbranch_scc0 .Lintra_v3_u1
	s_waitcnt lgkmcnt(4)
	v_mfma_f32_16x16x32_bf16 v[68:71], v[100:103], v[44:47], v[68:71]
	v_mfma_f32_16x16x32_bf16 v[72:75], v[104:107], v[44:47], v[72:75]
	v_mfma_f32_16x16x32_bf16 v[76:79], v[108:111], v[44:47], v[76:79]
	v_mfma_f32_16x16x32_bf16 v[80:83], v[112:115], v[44:47], v[80:83]
	s_waitcnt lgkmcnt(0)
	v_mfma_f32_16x16x32_bf16 v[84:87], v[116:119], v[44:47], v[84:87]
	v_mfma_f32_16x16x32_bf16 v[88:91], v[120:123], v[44:47], v[88:91]
	v_mfma_f32_16x16x32_bf16 v[92:95], v[124:127], v[44:47], v[92:95]
	v_mfma_f32_16x16x32_bf16 v[96:99], v[128:131], v[44:47], v[96:99]
.Lintra_v3_u1:
	s_waitcnt lgkmcnt(4)
	v_mfma_f32_16x16x32_bf16 v[132:135], v[100:103], v[52:55], v[132:135]
	v_mfma_f32_16x16x32_bf16 v[136:139], v[104:107], v[52:55], v[136:139]
	v_mfma_f32_16x16x32_bf16 v[144:147], v[108:111], v[52:55], v[144:147]
	v_mfma_f32_16x16x32_bf16 v[148:151], v[112:115], v[52:55], v[148:151]
	s_waitcnt lgkmcnt(0)
	v_mfma_f32_16x16x32_bf16 v[152:155], v[116:119], v[52:55], v[152:155]
	v_mfma_f32_16x16x32_bf16 v[156:159], v[120:123], v[52:55], v[156:159]
	v_mfma_f32_16x16x32_bf16 v[160:163], v[124:127], v[52:55], v[160:163]
	v_mfma_f32_16x16x32_bf16 v[164:167], v[128:131], v[52:55], v[164:167]
	s_cmp_ge_i32 s7, 5
	s_cbranch_scc0 .Lintra_hfend
	ds_read_b128 v[100:103], v230 offset:32768
	ds_read_b128 v[104:107], v230 offset:33792
	ds_read_b128 v[108:111], v230 offset:34816
	ds_read_b128 v[112:115], v230 offset:35840
	ds_read_b128 v[116:119], v230 offset:36864
	ds_read_b128 v[120:123], v230 offset:37888
	ds_read_b128 v[124:127], v230 offset:38912
	ds_read_b128 v[128:131], v230 offset:39936
	s_cmp_ge_i32 s6, 5
	s_cbranch_scc0 .Lintra_v4_u1
	s_waitcnt lgkmcnt(4)
	v_mfma_f32_16x16x32_bf16 v[68:71], v[100:103], v[48:51], v[68:71]
	v_mfma_f32_16x16x32_bf16 v[72:75], v[104:107], v[48:51], v[72:75]
	v_mfma_f32_16x16x32_bf16 v[76:79], v[108:111], v[48:51], v[76:79]
	v_mfma_f32_16x16x32_bf16 v[80:83], v[112:115], v[48:51], v[80:83]
	s_waitcnt lgkmcnt(0)
	v_mfma_f32_16x16x32_bf16 v[84:87], v[116:119], v[48:51], v[84:87]
	v_mfma_f32_16x16x32_bf16 v[88:91], v[120:123], v[48:51], v[88:91]
	v_mfma_f32_16x16x32_bf16 v[92:95], v[124:127], v[48:51], v[92:95]
	v_mfma_f32_16x16x32_bf16 v[96:99], v[128:131], v[48:51], v[96:99]
.Lintra_v4_u1:
	s_waitcnt lgkmcnt(4)
	v_mfma_f32_16x16x32_bf16 v[132:135], v[100:103], v[48:51], v[132:135]
	v_mfma_f32_16x16x32_bf16 v[136:139], v[104:107], v[48:51], v[136:139]
	v_mfma_f32_16x16x32_bf16 v[144:147], v[108:111], v[48:51], v[144:147]
	v_mfma_f32_16x16x32_bf16 v[148:151], v[112:115], v[48:51], v[148:151]
	s_waitcnt lgkmcnt(0)
	v_mfma_f32_16x16x32_bf16 v[152:155], v[116:119], v[48:51], v[152:155]
	v_mfma_f32_16x16x32_bf16 v[156:159], v[120:123], v[48:51], v[156:159]
	v_mfma_f32_16x16x32_bf16 v[160:163], v[124:127], v[48:51], v[160:163]
	v_mfma_f32_16x16x32_bf16 v[164:167], v[128:131], v[48:51], v[164:167]
	s_cmp_ge_i32 s7, 6
	s_cbranch_scc0 .Lintra_hfend
	ds_read_b128 v[100:103], v230 offset:40960
	ds_read_b128 v[104:107], v230 offset:41984
	ds_read_b128 v[108:111], v230 offset:43008
	ds_read_b128 v[112:115], v230 offset:44032
	ds_read_b128 v[116:119], v230 offset:45056
	ds_read_b128 v[120:123], v230 offset:46080
	ds_read_b128 v[124:127], v230 offset:47104
	ds_read_b128 v[128:131], v230 offset:48128
	s_cmp_ge_i32 s6, 6
	s_cbranch_scc0 .Lintra_v5_u1
	s_waitcnt lgkmcnt(4)
	v_mfma_f32_16x16x32_bf16 v[68:71], v[100:103], v[52:55], v[68:71]
	v_mfma_f32_16x16x32_bf16 v[72:75], v[104:107], v[52:55], v[72:75]
	v_mfma_f32_16x16x32_bf16 v[76:79], v[108:111], v[52:55], v[76:79]
	v_mfma_f32_16x16x32_bf16 v[80:83], v[112:115], v[52:55], v[80:83]
	s_waitcnt lgkmcnt(0)
	v_mfma_f32_16x16x32_bf16 v[84:87], v[116:119], v[52:55], v[84:87]
	v_mfma_f32_16x16x32_bf16 v[88:91], v[120:123], v[52:55], v[88:91]
	v_mfma_f32_16x16x32_bf16 v[92:95], v[124:127], v[52:55], v[92:95]
	v_mfma_f32_16x16x32_bf16 v[96:99], v[128:131], v[52:55], v[96:99]
.Lintra_v5_u1:
	s_waitcnt lgkmcnt(4)
	v_mfma_f32_16x16x32_bf16 v[132:135], v[100:103], v[44:47], v[132:135]
	v_mfma_f32_16x16x32_bf16 v[136:139], v[104:107], v[44:47], v[136:139]
	v_mfma_f32_16x16x32_bf16 v[144:147], v[108:111], v[44:47], v[144:147]
	v_mfma_f32_16x16x32_bf16 v[148:151], v[112:115], v[44:47], v[148:151]
	s_waitcnt lgkmcnt(0)
	v_mfma_f32_16x16x32_bf16 v[152:155], v[116:119], v[44:47], v[152:155]
	v_mfma_f32_16x16x32_bf16 v[156:159], v[120:123], v[44:47], v[156:159]
	v_mfma_f32_16x16x32_bf16 v[160:163], v[124:127], v[44:47], v[160:163]
	v_mfma_f32_16x16x32_bf16 v[164:167], v[128:131], v[44:47], v[164:167]
	s_cmp_ge_i32 s7, 7
	s_cbranch_scc0 .Lintra_hfend
	ds_read_b128 v[100:103], v230 offset:49152
	ds_read_b128 v[104:107], v230 offset:50176
	ds_read_b128 v[108:111], v230 offset:51200
	ds_read_b128 v[112:115], v230 offset:52224
	ds_read_b128 v[116:119], v230 offset:53248
	ds_read_b128 v[120:123], v230 offset:54272
	ds_read_b128 v[124:127], v230 offset:55296
	ds_read_b128 v[128:131], v230 offset:56320
	s_cmp_ge_i32 s6, 7
	s_cbranch_scc0 .Lintra_v6_u1
	s_waitcnt lgkmcnt(4)
	v_mfma_f32_16x16x32_bf16 v[68:71], v[100:103], v[56:59], v[68:71]
	v_mfma_f32_16x16x32_bf16 v[72:75], v[104:107], v[56:59], v[72:75]
	v_mfma_f32_16x16x32_bf16 v[76:79], v[108:111], v[56:59], v[76:79]
	v_mfma_f32_16x16x32_bf16 v[80:83], v[112:115], v[56:59], v[80:83]
	s_waitcnt lgkmcnt(0)
	v_mfma_f32_16x16x32_bf16 v[84:87], v[116:119], v[56:59], v[84:87]
	v_mfma_f32_16x16x32_bf16 v[88:91], v[120:123], v[56:59], v[88:91]
	v_mfma_f32_16x16x32_bf16 v[92:95], v[124:127], v[56:59], v[92:95]
	v_mfma_f32_16x16x32_bf16 v[96:99], v[128:131], v[56:59], v[96:99]
.Lintra_v6_u1:
	s_waitcnt lgkmcnt(4)
	v_mfma_f32_16x16x32_bf16 v[132:135], v[100:103], v[40:43], v[132:135]
	v_mfma_f32_16x16x32_bf16 v[136:139], v[104:107], v[40:43], v[136:139]
	v_mfma_f32_16x16x32_bf16 v[144:147], v[108:111], v[40:43], v[144:147]
	v_mfma_f32_16x16x32_bf16 v[148:151], v[112:115], v[40:43], v[148:151]
	s_waitcnt lgkmcnt(0)
	v_mfma_f32_16x16x32_bf16 v[152:155], v[116:119], v[40:43], v[152:155]
	v_mfma_f32_16x16x32_bf16 v[156:159], v[120:123], v[40:43], v[156:159]
	v_mfma_f32_16x16x32_bf16 v[160:163], v[124:127], v[40:43], v[160:163]
	v_mfma_f32_16x16x32_bf16 v[164:167], v[128:131], v[40:43], v[164:167]
	s_cmp_ge_i32 s7, 8
	s_cbranch_scc0 .Lintra_hfend
	ds_read_b128 v[100:103], v230 offset:57344
	ds_read_b128 v[104:107], v230 offset:58368
	ds_read_b128 v[108:111], v230 offset:59392
	ds_read_b128 v[112:115], v230 offset:60416
	ds_read_b128 v[116:119], v230 offset:61440
	ds_read_b128 v[120:123], v230 offset:62464
	ds_read_b128 v[124:127], v230 offset:63488
	ds_read_b128 v[128:131], v230 offset:64512
	s_cmp_ge_i32 s6, 8
	s_cbranch_scc0 .Lintra_v7_u1
	s_waitcnt lgkmcnt(4)
	v_mfma_f32_16x16x32_bf16 v[68:71], v[100:103], v[60:63], v[68:71]
	v_mfma_f32_16x16x32_bf16 v[72:75], v[104:107], v[60:63], v[72:75]
	v_mfma_f32_16x16x32_bf16 v[76:79], v[108:111], v[60:63], v[76:79]
	v_mfma_f32_16x16x32_bf16 v[80:83], v[112:115], v[60:63], v[80:83]
	s_waitcnt lgkmcnt(0)
	v_mfma_f32_16x16x32_bf16 v[84:87], v[116:119], v[60:63], v[84:87]
	v_mfma_f32_16x16x32_bf16 v[88:91], v[120:123], v[60:63], v[88:91]
	v_mfma_f32_16x16x32_bf16 v[92:95], v[124:127], v[60:63], v[92:95]
	v_mfma_f32_16x16x32_bf16 v[96:99], v[128:131], v[60:63], v[96:99]
.Lintra_v7_u1:
	s_waitcnt lgkmcnt(4)
	v_mfma_f32_16x16x32_bf16 v[132:135], v[100:103], v[36:39], v[132:135]
	v_mfma_f32_16x16x32_bf16 v[136:139], v[104:107], v[36:39], v[136:139]
	v_mfma_f32_16x16x32_bf16 v[144:147], v[108:111], v[36:39], v[144:147]
	v_mfma_f32_16x16x32_bf16 v[148:151], v[112:115], v[36:39], v[148:151]
	s_waitcnt lgkmcnt(0)
	v_mfma_f32_16x16x32_bf16 v[152:155], v[116:119], v[36:39], v[152:155]
	v_mfma_f32_16x16x32_bf16 v[156:159], v[120:123], v[36:39], v[156:159]
	v_mfma_f32_16x16x32_bf16 v[160:163], v[124:127], v[36:39], v[160:163]
	v_mfma_f32_16x16x32_bf16 v[164:167], v[128:131], v[36:39], v[164:167]
.Lintra_hfend:
	s_nop 7
	s_nop 3
	s_mul_i32 s0, s8, 0x1800
	s_lshl_b32 s1, s10, 8
	s_add_i32 s0, s0, s1
	s_add_u32 s30, s20, s0
	s_addc_u32 s31, s21, 0
	v_add_f32_e32 v221, v68, v69
	v_add_f32_e32 v222, v70, v71
	v_add_f32_e32 v221, v221, v222
	v_add_f32_e32 v202, v202, v221
	v_mul_f32_e32 v221, v68, v68
	v_fmac_f32_e32 v221, v69, v69
	v_mul_f32_e32 v222, v70, v70
	v_fmac_f32_e32 v222, v71, v71
	v_add_f32_e32 v221, v221, v222
	v_add_f32_e32 v203, v203, v221
	v_cvt_pk_bf16_f32 v224, v68, v69
	v_cvt_pk_bf16_f32 v225, v70, v71
	global_store_dwordx2 v204, v[224:225], s[30:31] offset:0
	v_add_f32_e32 v221, v72, v73
	v_add_f32_e32 v222, v74, v75
	v_add_f32_e32 v221, v221, v222
	v_add_f32_e32 v202, v202, v221
	v_mul_f32_e32 v221, v72, v72
	v_fmac_f32_e32 v221, v73, v73
	v_mul_f32_e32 v222, v74, v74
	v_fmac_f32_e32 v222, v75, v75
	v_add_f32_e32 v221, v221, v222
	v_add_f32_e32 v203, v203, v221
	v_cvt_pk_bf16_f32 v224, v72, v73
	v_cvt_pk_bf16_f32 v225, v74, v75
	global_store_dwordx2 v204, v[224:225], s[30:31] offset:32
	v_add_f32_e32 v221, v76, v77
	v_add_f32_e32 v222, v78, v79
	v_add_f32_e32 v221, v221, v222
	v_add_f32_e32 v202, v202, v221
	v_mul_f32_e32 v221, v76, v76
	v_fmac_f32_e32 v221, v77, v77
	v_mul_f32_e32 v222, v78, v78
	v_fmac_f32_e32 v222, v79, v79
	v_add_f32_e32 v221, v221, v222
	v_add_f32_e32 v203, v203, v221
	v_cvt_pk_bf16_f32 v224, v76, v77
	v_cvt_pk_bf16_f32 v225, v78, v79
	global_store_dwordx2 v204, v[224:225], s[30:31] offset:64
	v_add_f32_e32 v221, v80, v81
	v_add_f32_e32 v222, v82, v83
	v_add_f32_e32 v221, v221, v222
	v_add_f32_e32 v202, v202, v221
	v_mul_f32_e32 v221, v80, v80
	v_fmac_f32_e32 v221, v81, v81
	v_mul_f32_e32 v222, v82, v82
	v_fmac_f32_e32 v222, v83, v83
	v_add_f32_e32 v221, v221, v222
	v_add_f32_e32 v203, v203, v221
	v_cvt_pk_bf16_f32 v224, v80, v81
	v_cvt_pk_bf16_f32 v225, v82, v83
	global_store_dwordx2 v204, v[224:225], s[30:31] offset:96
	v_add_f32_e32 v221, v84, v85
	v_add_f32_e32 v222, v86, v87
	v_add_f32_e32 v221, v221, v222
	v_add_f32_e32 v202, v202, v221
	v_mul_f32_e32 v221, v84, v84
	v_fmac_f32_e32 v221, v85, v85
	v_mul_f32_e32 v222, v86, v86
	v_fmac_f32_e32 v222, v87, v87
	v_add_f32_e32 v221, v221, v222
	v_add_f32_e32 v203, v203, v221
	v_cvt_pk_bf16_f32 v224, v84, v85
	v_cvt_pk_bf16_f32 v225, v86, v87
	global_store_dwordx2 v204, v[224:225], s[30:31] offset:128
	v_add_f32_e32 v221, v88, v89
	v_add_f32_e32 v222, v90, v91
	v_add_f32_e32 v221, v221, v222
	v_add_f32_e32 v202, v202, v221
	v_mul_f32_e32 v221, v88, v88
	v_fmac_f32_e32 v221, v89, v89
	v_mul_f32_e32 v222, v90, v90
	v_fmac_f32_e32 v222, v91, v91
	v_add_f32_e32 v221, v221, v222
	v_add_f32_e32 v203, v203, v221
	v_cvt_pk_bf16_f32 v224, v88, v89
	v_cvt_pk_bf16_f32 v225, v90, v91
	global_store_dwordx2 v204, v[224:225], s[30:31] offset:160
	v_add_f32_e32 v221, v92, v93
	v_add_f32_e32 v222, v94, v95
	v_add_f32_e32 v221, v221, v222
	v_add_f32_e32 v202, v202, v221
	v_mul_f32_e32 v221, v92, v92
	v_fmac_f32_e32 v221, v93, v93
	v_mul_f32_e32 v222, v94, v94
	v_fmac_f32_e32 v222, v95, v95
	v_add_f32_e32 v221, v221, v222
	v_add_f32_e32 v203, v203, v221
	v_cvt_pk_bf16_f32 v224, v92, v93
	v_cvt_pk_bf16_f32 v225, v94, v95
	global_store_dwordx2 v204, v[224:225], s[30:31] offset:192
	v_add_f32_e32 v221, v96, v97
	v_add_f32_e32 v222, v98, v99
	v_add_f32_e32 v221, v221, v222
	v_add_f32_e32 v202, v202, v221
	v_mul_f32_e32 v221, v96, v96
	v_fmac_f32_e32 v221, v97, v97
	v_mul_f32_e32 v222, v98, v98
	v_fmac_f32_e32 v222, v99, v99
	v_add_f32_e32 v221, v221, v222
	v_add_f32_e32 v203, v203, v221
	v_cvt_pk_bf16_f32 v224, v96, v97
	v_cvt_pk_bf16_f32 v225, v98, v99
	global_store_dwordx2 v204, v[224:225], s[30:31] offset:224
	s_mul_i32 s0, s9, 0x1800
	s_lshl_b32 s1, s10, 8
	s_add_i32 s0, s0, s1
	s_add_u32 s30, s20, s0
	s_addc_u32 s31, s21, 0
	v_add_f32_e32 v221, v132, v133
	v_add_f32_e32 v222, v134, v135
	v_add_f32_e32 v221, v221, v222
	v_add_f32_e32 v245, v245, v221
	v_mul_f32_e32 v221, v132, v132
	v_fmac_f32_e32 v221, v133, v133
	v_mul_f32_e32 v222, v134, v134
	v_fmac_f32_e32 v222, v135, v135
	v_add_f32_e32 v221, v221, v222
	v_add_f32_e32 v246, v246, v221
	v_cvt_pk_bf16_f32 v224, v132, v133
	v_cvt_pk_bf16_f32 v225, v134, v135
	global_store_dwordx2 v204, v[224:225], s[30:31] offset:0
	v_add_f32_e32 v221, v136, v137
	v_add_f32_e32 v222, v138, v139
	v_add_f32_e32 v221, v221, v222
	v_add_f32_e32 v245, v245, v221
	v_mul_f32_e32 v221, v136, v136
	v_fmac_f32_e32 v221, v137, v137
	v_mul_f32_e32 v222, v138, v138
	v_fmac_f32_e32 v222, v139, v139
	v_add_f32_e32 v221, v221, v222
	v_add_f32_e32 v246, v246, v221
	v_cvt_pk_bf16_f32 v224, v136, v137
	v_cvt_pk_bf16_f32 v225, v138, v139
	global_store_dwordx2 v204, v[224:225], s[30:31] offset:32
	v_add_f32_e32 v221, v144, v145
	v_add_f32_e32 v222, v146, v147
	v_add_f32_e32 v221, v221, v222
	v_add_f32_e32 v245, v245, v221
	v_mul_f32_e32 v221, v144, v144
	v_fmac_f32_e32 v221, v145, v145
	v_mul_f32_e32 v222, v146, v146
	v_fmac_f32_e32 v222, v147, v147
	v_add_f32_e32 v221, v221, v222
	v_add_f32_e32 v246, v246, v221
	v_cvt_pk_bf16_f32 v224, v144, v145
	v_cvt_pk_bf16_f32 v225, v146, v147
	global_store_dwordx2 v204, v[224:225], s[30:31] offset:64
	v_add_f32_e32 v221, v148, v149
	v_add_f32_e32 v222, v150, v151
	v_add_f32_e32 v221, v221, v222
	v_add_f32_e32 v245, v245, v221
	v_mul_f32_e32 v221, v148, v148
	v_fmac_f32_e32 v221, v149, v149
	v_mul_f32_e32 v222, v150, v150
	v_fmac_f32_e32 v222, v151, v151
	v_add_f32_e32 v221, v221, v222
	v_add_f32_e32 v246, v246, v221
	v_cvt_pk_bf16_f32 v224, v148, v149
	v_cvt_pk_bf16_f32 v225, v150, v151
	global_store_dwordx2 v204, v[224:225], s[30:31] offset:96
	v_add_f32_e32 v221, v152, v153
	v_add_f32_e32 v222, v154, v155
	v_add_f32_e32 v221, v221, v222
	v_add_f32_e32 v245, v245, v221
	v_mul_f32_e32 v221, v152, v152
	v_fmac_f32_e32 v221, v153, v153
	v_mul_f32_e32 v222, v154, v154
	v_fmac_f32_e32 v222, v155, v155
	v_add_f32_e32 v221, v221, v222
	v_add_f32_e32 v246, v246, v221
	v_cvt_pk_bf16_f32 v224, v152, v153
	v_cvt_pk_bf16_f32 v225, v154, v155
	global_store_dwordx2 v204, v[224:225], s[30:31] offset:128
	v_add_f32_e32 v221, v156, v157
	v_add_f32_e32 v222, v158, v159
	v_add_f32_e32 v221, v221, v222
	v_add_f32_e32 v245, v245, v221
	v_mul_f32_e32 v221, v156, v156
	v_fmac_f32_e32 v221, v157, v157
	v_mul_f32_e32 v222, v158, v158
	v_fmac_f32_e32 v222, v159, v159
	v_add_f32_e32 v221, v221, v222
	v_add_f32_e32 v246, v246, v221
	v_cvt_pk_bf16_f32 v224, v156, v157
	v_cvt_pk_bf16_f32 v225, v158, v159
	global_store_dwordx2 v204, v[224:225], s[30:31] offset:160
	v_add_f32_e32 v221, v160, v161
	v_add_f32_e32 v222, v162, v163
	v_add_f32_e32 v221, v221, v222
	v_add_f32_e32 v245, v245, v221
	v_mul_f32_e32 v221, v160, v160
	v_fmac_f32_e32 v221, v161, v161
	v_mul_f32_e32 v222, v162, v162
	v_fmac_f32_e32 v222, v163, v163
	v_add_f32_e32 v221, v221, v222
	v_add_f32_e32 v246, v246, v221
	v_cvt_pk_bf16_f32 v224, v160, v161
	v_cvt_pk_bf16_f32 v225, v162, v163
	global_store_dwordx2 v204, v[224:225], s[30:31] offset:192
	v_add_f32_e32 v221, v164, v165
	v_add_f32_e32 v222, v166, v167
	v_add_f32_e32 v221, v221, v222
	v_add_f32_e32 v245, v245, v221
	v_mul_f32_e32 v221, v164, v164
	v_fmac_f32_e32 v221, v165, v165
	v_mul_f32_e32 v222, v166, v166
	v_fmac_f32_e32 v222, v167, v167
	v_add_f32_e32 v221, v221, v222
	v_add_f32_e32 v246, v246, v221
	v_cvt_pk_bf16_f32 v224, v164, v165
	v_cvt_pk_bf16_f32 v225, v166, v167
	global_store_dwordx2 v204, v[224:225], s[30:31] offset:224
	s_add_i32 s10, s10, 1
	s_cmp_lt_i32 s10, 4
	s_cbranch_scc1 .Lintra_hf
	s_mov_b32 s6, 0
.Lintra_unit:
	s_cmp_eq_u32 s6, 0
	s_cbranch_scc1 .Lintra_c_go
	s_mov_b32 s8, s9
	v_mov_b32_e32 v202, v245
	v_mov_b32_e32 v203, v246
.Lintra_c_go:
	v_mov_b32_e32 v221, v208
	v_and_b32_e32 v221, 63, v221
	v_lshlrev_b32_e32 v221, 2, v221
	v_xor_b32_e32 v222, 64, v221
	v_xor_b32_e32 v221, 0x80, v221
	ds_bpermute_b32 v223, v222, v202
	ds_bpermute_b32 v224, v222, v203
	s_waitcnt lgkmcnt(0)
	v_add_f32_e32 v202, v202, v223
	v_add_f32_e32 v203, v203, v224
	ds_bpermute_b32 v223, v221, v202
	ds_bpermute_b32 v224, v221, v203
	s_waitcnt lgkmcnt(0)
	v_add_f32_e32 v202, v202, v223
	v_add_f32_e32 v203, v203, v224
	v_mul_f32_e32 v227, 0x3b000000, v202
	v_mul_f32_e32 v228, 0x3b000000, v203
	v_fma_f32 v228, -v227, v227, v228
	v_max_f32_e32 v228, 0, v228
	v_add_f32_e32 v228, 0x3727c5ac, v228
	v_rsq_f32_e32 v228, v228
	s_mul_i32 s0, s8, 0x1800
	s_add_u32 s30, s20, s0
	s_addc_u32 s31, s21, 0
	s_lshl_b32 s0, s8, 12
	s_add_u32 s34, s22, s0
	s_addc_u32 s35, s23, 0
	s_waitcnt vmcnt(0)
	global_load_dwordx2 v[24:25], v205, s[34:35] offset:0
	global_load_dwordx2 v[100:101], v204, s[30:31] offset:0
	global_load_dwordx4 v[68:71], v206, s[28:29] offset:0
	global_load_dwordx2 v[26:27], v205, s[34:35] offset:32
	global_load_dwordx2 v[102:103], v204, s[30:31] offset:32
	global_load_dwordx4 v[72:75], v206, s[28:29] offset:64
	global_load_dwordx2 v[28:29], v205, s[34:35] offset:64
	global_load_dwordx2 v[104:105], v204, s[30:31] offset:64
	global_load_dwordx4 v[76:79], v206, s[28:29] offset:128
	global_load_dwordx2 v[30:31], v205, s[34:35] offset:96
	global_load_dwordx2 v[106:107], v204, s[30:31] offset:96
	global_load_dwordx4 v[80:83], v206, s[28:29] offset:192
	global_load_dwordx2 v[32:33], v205, s[34:35] offset:128
	global_load_dwordx2 v[108:109], v204, s[30:31] offset:128
	global_load_dwordx4 v[84:87], v206, s[28:29] offset:256
	global_load_dwordx2 v[34:35], v205, s[34:35] offset:160
	global_load_dwordx2 v[110:111], v204, s[30:31] offset:160
	global_load_dwordx4 v[88:91], v206, s[28:29] offset:320
	global_load_dwordx2 v[36:37], v205, s[34:35] offset:192
	global_load_dwordx2 v[112:113], v204, s[30:31] offset:192
	global_load_dwordx4 v[92:95], v206, s[28:29] offset:384
	global_load_dwordx2 v[38:39], v205, s[34:35] offset:224
	global_load_dwordx2 v[114:115], v204, s[30:31] offset:224
	global_load_dwordx4 v[96:99], v206, s[28:29] offset:448
	s_waitcnt vmcnt(21)
	v_lshlrev_b32_e32 v12, 16, v24
	v_and_b32_e32 v13, 0xffff0000, v24
	v_lshlrev_b32_e32 v14, 16, v25
	v_and_b32_e32 v15, 0xffff0000, v25
	v_mul_f32_e32 v16, 0xbfb8aa3b, v12
	v_mul_f32_e32 v17, 0xbfb8aa3b, v13
	v_mul_f32_e32 v18, 0xbfb8aa3b, v14
	v_mul_f32_e32 v19, 0xbfb8aa3b, v15
	v_exp_f32_e32 v16, v16
	v_exp_f32_e32 v17, v17
	v_exp_f32_e32 v18, v18
	v_exp_f32_e32 v19, v19
	v_lshlrev_b32_e32 v20, 16, v100
	v_and_b32_e32 v21, 0xffff0000, v100
	v_lshlrev_b32_e32 v22, 16, v101
	v_and_b32_e32 v23, 0xffff0000, v101
	v_add_f32_e32 v16, 1.0, v16
	v_add_f32_e32 v17, 1.0, v17
	v_add_f32_e32 v18, 1.0, v18
	v_add_f32_e32 v19, 1.0, v19
	v_rcp_f32_e32 v16, v16
	v_rcp_f32_e32 v17, v17
	v_rcp_f32_e32 v18, v18
	v_rcp_f32_e32 v19, v19
	v_sub_f32_e32 v20, v20, v227
	v_sub_f32_e32 v21, v21, v227
	v_sub_f32_e32 v22, v22, v227
	v_sub_f32_e32 v23, v23, v227
	v_mul_f32_e32 v20, v20, v228
	v_mul_f32_e32 v21, v21, v228
	v_mul_f32_e32 v22, v22, v228
	v_mul_f32_e32 v23, v23, v228
	v_mul_f32_e32 v12, v12, v16
	v_mul_f32_e32 v13, v13, v17
	v_mul_f32_e32 v14, v14, v18
	v_mul_f32_e32 v15, v15, v19
	v_mul_f32_e32 v20, v20, v68
	v_mul_f32_e32 v21, v21, v69
	v_mul_f32_e32 v22, v22, v70
	v_mul_f32_e32 v23, v23, v71
	v_mul_f32_e32 v20, v20, v12
	v_mul_f32_e32 v21, v21, v13
	v_mul_f32_e32 v22, v22, v14
	v_mul_f32_e32 v23, v23, v15
	v_cvt_pk_bf16_f32 v20, v20, v21
	v_cvt_pk_bf16_f32 v21, v22, v23
	global_store_dwordx2 v204, v[20:21], s[30:31] offset:0
	s_waitcnt vmcnt(19)
	v_lshlrev_b32_e32 v12, 16, v26
	v_and_b32_e32 v13, 0xffff0000, v26
	v_lshlrev_b32_e32 v14, 16, v27
	v_and_b32_e32 v15, 0xffff0000, v27
	v_mul_f32_e32 v16, 0xbfb8aa3b, v12
	v_mul_f32_e32 v17, 0xbfb8aa3b, v13
	v_mul_f32_e32 v18, 0xbfb8aa3b, v14
	v_mul_f32_e32 v19, 0xbfb8aa3b, v15
	v_exp_f32_e32 v16, v16
	v_exp_f32_e32 v17, v17
	v_exp_f32_e32 v18, v18
	v_exp_f32_e32 v19, v19
	v_lshlrev_b32_e32 v20, 16, v102
	v_and_b32_e32 v21, 0xffff0000, v102
	v_lshlrev_b32_e32 v22, 16, v103
	v_and_b32_e32 v23, 0xffff0000, v103
	v_add_f32_e32 v16, 1.0, v16
	v_add_f32_e32 v17, 1.0, v17
	v_add_f32_e32 v18, 1.0, v18
	v_add_f32_e32 v19, 1.0, v19
	v_rcp_f32_e32 v16, v16
	v_rcp_f32_e32 v17, v17
	v_rcp_f32_e32 v18, v18
	v_rcp_f32_e32 v19, v19
	v_sub_f32_e32 v20, v20, v227
	v_sub_f32_e32 v21, v21, v227
	v_sub_f32_e32 v22, v22, v227
	v_sub_f32_e32 v23, v23, v227
	v_mul_f32_e32 v20, v20, v228
	v_mul_f32_e32 v21, v21, v228
	v_mul_f32_e32 v22, v22, v228
	v_mul_f32_e32 v23, v23, v228
	v_mul_f32_e32 v12, v12, v16
	v_mul_f32_e32 v13, v13, v17
	v_mul_f32_e32 v14, v14, v18
	v_mul_f32_e32 v15, v15, v19
	v_mul_f32_e32 v20, v20, v72
	v_mul_f32_e32 v21, v21, v73
	v_mul_f32_e32 v22, v22, v74
	v_mul_f32_e32 v23, v23, v75
	v_mul_f32_e32 v20, v20, v12
	v_mul_f32_e32 v21, v21, v13
	v_mul_f32_e32 v22, v22, v14
	v_mul_f32_e32 v23, v23, v15
	v_cvt_pk_bf16_f32 v20, v20, v21
	v_cvt_pk_bf16_f32 v21, v22, v23
	global_store_dwordx2 v204, v[20:21], s[30:31] offset:32
	s_waitcnt vmcnt(17)
	v_lshlrev_b32_e32 v12, 16, v28
	v_and_b32_e32 v13, 0xffff0000, v28
	v_lshlrev_b32_e32 v14, 16, v29
	v_and_b32_e32 v15, 0xffff0000, v29
	v_mul_f32_e32 v16, 0xbfb8aa3b, v12
	v_mul_f32_e32 v17, 0xbfb8aa3b, v13
	v_mul_f32_e32 v18, 0xbfb8aa3b, v14
	v_mul_f32_e32 v19, 0xbfb8aa3b, v15
	v_exp_f32_e32 v16, v16
	v_exp_f32_e32 v17, v17
	v_exp_f32_e32 v18, v18
	v_exp_f32_e32 v19, v19
	v_lshlrev_b32_e32 v20, 16, v104
	v_and_b32_e32 v21, 0xffff0000, v104
	v_lshlrev_b32_e32 v22, 16, v105
	v_and_b32_e32 v23, 0xffff0000, v105
	v_add_f32_e32 v16, 1.0, v16
	v_add_f32_e32 v17, 1.0, v17
	v_add_f32_e32 v18, 1.0, v18
	v_add_f32_e32 v19, 1.0, v19
	v_rcp_f32_e32 v16, v16
	v_rcp_f32_e32 v17, v17
	v_rcp_f32_e32 v18, v18
	v_rcp_f32_e32 v19, v19
	v_sub_f32_e32 v20, v20, v227
	v_sub_f32_e32 v21, v21, v227
	v_sub_f32_e32 v22, v22, v227
	v_sub_f32_e32 v23, v23, v227
	v_mul_f32_e32 v20, v20, v228
	v_mul_f32_e32 v21, v21, v228
	v_mul_f32_e32 v22, v22, v228
	v_mul_f32_e32 v23, v23, v228
	v_mul_f32_e32 v12, v12, v16
	v_mul_f32_e32 v13, v13, v17
	v_mul_f32_e32 v14, v14, v18
	v_mul_f32_e32 v15, v15, v19
	v_mul_f32_e32 v20, v20, v76
	v_mul_f32_e32 v21, v21, v77
	v_mul_f32_e32 v22, v22, v78
	v_mul_f32_e32 v23, v23, v79
	v_mul_f32_e32 v20, v20, v12
	v_mul_f32_e32 v21, v21, v13
	v_mul_f32_e32 v22, v22, v14
	v_mul_f32_e32 v23, v23, v15
	v_cvt_pk_bf16_f32 v20, v20, v21
	v_cvt_pk_bf16_f32 v21, v22, v23
	global_store_dwordx2 v204, v[20:21], s[30:31] offset:64
	s_waitcnt vmcnt(15)
	v_lshlrev_b32_e32 v12, 16, v30
	v_and_b32_e32 v13, 0xffff0000, v30
	v_lshlrev_b32_e32 v14, 16, v31
	v_and_b32_e32 v15, 0xffff0000, v31
	v_mul_f32_e32 v16, 0xbfb8aa3b, v12
	v_mul_f32_e32 v17, 0xbfb8aa3b, v13
	v_mul_f32_e32 v18, 0xbfb8aa3b, v14
	v_mul_f32_e32 v19, 0xbfb8aa3b, v15
	v_exp_f32_e32 v16, v16
	v_exp_f32_e32 v17, v17
	v_exp_f32_e32 v18, v18
	v_exp_f32_e32 v19, v19
	v_lshlrev_b32_e32 v20, 16, v106
	v_and_b32_e32 v21, 0xffff0000, v106
	v_lshlrev_b32_e32 v22, 16, v107
	v_and_b32_e32 v23, 0xffff0000, v107
	v_add_f32_e32 v16, 1.0, v16
	v_add_f32_e32 v17, 1.0, v17
	v_add_f32_e32 v18, 1.0, v18
	v_add_f32_e32 v19, 1.0, v19
	v_rcp_f32_e32 v16, v16
	v_rcp_f32_e32 v17, v17
	v_rcp_f32_e32 v18, v18
	v_rcp_f32_e32 v19, v19
	v_sub_f32_e32 v20, v20, v227
	v_sub_f32_e32 v21, v21, v227
	v_sub_f32_e32 v22, v22, v227
	v_sub_f32_e32 v23, v23, v227
	v_mul_f32_e32 v20, v20, v228
	v_mul_f32_e32 v21, v21, v228
	v_mul_f32_e32 v22, v22, v228
	v_mul_f32_e32 v23, v23, v228
	v_mul_f32_e32 v12, v12, v16
	v_mul_f32_e32 v13, v13, v17
	v_mul_f32_e32 v14, v14, v18
	v_mul_f32_e32 v15, v15, v19
	v_mul_f32_e32 v20, v20, v80
	v_mul_f32_e32 v21, v21, v81
	v_mul_f32_e32 v22, v22, v82
	v_mul_f32_e32 v23, v23, v83
	v_mul_f32_e32 v20, v20, v12
	v_mul_f32_e32 v21, v21, v13
	v_mul_f32_e32 v22, v22, v14
	v_mul_f32_e32 v23, v23, v15
	v_cvt_pk_bf16_f32 v20, v20, v21
	v_cvt_pk_bf16_f32 v21, v22, v23
	global_store_dwordx2 v204, v[20:21], s[30:31] offset:96
	s_waitcnt vmcnt(13)
	v_lshlrev_b32_e32 v12, 16, v32
	v_and_b32_e32 v13, 0xffff0000, v32
	v_lshlrev_b32_e32 v14, 16, v33
	v_and_b32_e32 v15, 0xffff0000, v33
	v_mul_f32_e32 v16, 0xbfb8aa3b, v12
	v_mul_f32_e32 v17, 0xbfb8aa3b, v13
	v_mul_f32_e32 v18, 0xbfb8aa3b, v14
	v_mul_f32_e32 v19, 0xbfb8aa3b, v15
	v_exp_f32_e32 v16, v16
	v_exp_f32_e32 v17, v17
	v_exp_f32_e32 v18, v18
	v_exp_f32_e32 v19, v19
	v_lshlrev_b32_e32 v20, 16, v108
	v_and_b32_e32 v21, 0xffff0000, v108
	v_lshlrev_b32_e32 v22, 16, v109
	v_and_b32_e32 v23, 0xffff0000, v109
	v_add_f32_e32 v16, 1.0, v16
	v_add_f32_e32 v17, 1.0, v17
	v_add_f32_e32 v18, 1.0, v18
	v_add_f32_e32 v19, 1.0, v19
	v_rcp_f32_e32 v16, v16
	v_rcp_f32_e32 v17, v17
	v_rcp_f32_e32 v18, v18
	v_rcp_f32_e32 v19, v19
	v_sub_f32_e32 v20, v20, v227
	v_sub_f32_e32 v21, v21, v227
	v_sub_f32_e32 v22, v22, v227
	v_sub_f32_e32 v23, v23, v227
	v_mul_f32_e32 v20, v20, v228
	v_mul_f32_e32 v21, v21, v228
	v_mul_f32_e32 v22, v22, v228
	v_mul_f32_e32 v23, v23, v228
	v_mul_f32_e32 v12, v12, v16
	v_mul_f32_e32 v13, v13, v17
	v_mul_f32_e32 v14, v14, v18
	v_mul_f32_e32 v15, v15, v19
	v_mul_f32_e32 v20, v20, v84
	v_mul_f32_e32 v21, v21, v85
	v_mul_f32_e32 v22, v22, v86
	v_mul_f32_e32 v23, v23, v87
	v_mul_f32_e32 v20, v20, v12
	v_mul_f32_e32 v21, v21, v13
	v_mul_f32_e32 v22, v22, v14
	v_mul_f32_e32 v23, v23, v15
	v_cvt_pk_bf16_f32 v20, v20, v21
	v_cvt_pk_bf16_f32 v21, v22, v23
	global_store_dwordx2 v204, v[20:21], s[30:31] offset:128
	s_waitcnt vmcnt(11)
	v_lshlrev_b32_e32 v12, 16, v34
	v_and_b32_e32 v13, 0xffff0000, v34
	v_lshlrev_b32_e32 v14, 16, v35
	v_and_b32_e32 v15, 0xffff0000, v35
	v_mul_f32_e32 v16, 0xbfb8aa3b, v12
	v_mul_f32_e32 v17, 0xbfb8aa3b, v13
	v_mul_f32_e32 v18, 0xbfb8aa3b, v14
	v_mul_f32_e32 v19, 0xbfb8aa3b, v15
	v_exp_f32_e32 v16, v16
	v_exp_f32_e32 v17, v17
	v_exp_f32_e32 v18, v18
	v_exp_f32_e32 v19, v19
	v_lshlrev_b32_e32 v20, 16, v110
	v_and_b32_e32 v21, 0xffff0000, v110
	v_lshlrev_b32_e32 v22, 16, v111
	v_and_b32_e32 v23, 0xffff0000, v111
	v_add_f32_e32 v16, 1.0, v16
	v_add_f32_e32 v17, 1.0, v17
	v_add_f32_e32 v18, 1.0, v18
	v_add_f32_e32 v19, 1.0, v19
	v_rcp_f32_e32 v16, v16
	v_rcp_f32_e32 v17, v17
	v_rcp_f32_e32 v18, v18
	v_rcp_f32_e32 v19, v19
	v_sub_f32_e32 v20, v20, v227
	v_sub_f32_e32 v21, v21, v227
	v_sub_f32_e32 v22, v22, v227
	v_sub_f32_e32 v23, v23, v227
	v_mul_f32_e32 v20, v20, v228
	v_mul_f32_e32 v21, v21, v228
	v_mul_f32_e32 v22, v22, v228
	v_mul_f32_e32 v23, v23, v228
	v_mul_f32_e32 v12, v12, v16
	v_mul_f32_e32 v13, v13, v17
	v_mul_f32_e32 v14, v14, v18
	v_mul_f32_e32 v15, v15, v19
	v_mul_f32_e32 v20, v20, v88
	v_mul_f32_e32 v21, v21, v89
	v_mul_f32_e32 v22, v22, v90
	v_mul_f32_e32 v23, v23, v91
	v_mul_f32_e32 v20, v20, v12
	v_mul_f32_e32 v21, v21, v13
	v_mul_f32_e32 v22, v22, v14
	v_mul_f32_e32 v23, v23, v15
	v_cvt_pk_bf16_f32 v20, v20, v21
	v_cvt_pk_bf16_f32 v21, v22, v23
	global_store_dwordx2 v204, v[20:21], s[30:31] offset:160
	s_waitcnt vmcnt(9)
	v_lshlrev_b32_e32 v12, 16, v36
	v_and_b32_e32 v13, 0xffff0000, v36
	v_lshlrev_b32_e32 v14, 16, v37
	v_and_b32_e32 v15, 0xffff0000, v37
	v_mul_f32_e32 v16, 0xbfb8aa3b, v12
	v_mul_f32_e32 v17, 0xbfb8aa3b, v13
	v_mul_f32_e32 v18, 0xbfb8aa3b, v14
	v_mul_f32_e32 v19, 0xbfb8aa3b, v15
	v_exp_f32_e32 v16, v16
	v_exp_f32_e32 v17, v17
	v_exp_f32_e32 v18, v18
	v_exp_f32_e32 v19, v19
	v_lshlrev_b32_e32 v20, 16, v112
	v_and_b32_e32 v21, 0xffff0000, v112
	v_lshlrev_b32_e32 v22, 16, v113
	v_and_b32_e32 v23, 0xffff0000, v113
	v_add_f32_e32 v16, 1.0, v16
	v_add_f32_e32 v17, 1.0, v17
	v_add_f32_e32 v18, 1.0, v18
	v_add_f32_e32 v19, 1.0, v19
	v_rcp_f32_e32 v16, v16
	v_rcp_f32_e32 v17, v17
	v_rcp_f32_e32 v18, v18
	v_rcp_f32_e32 v19, v19
	v_sub_f32_e32 v20, v20, v227
	v_sub_f32_e32 v21, v21, v227
	v_sub_f32_e32 v22, v22, v227
	v_sub_f32_e32 v23, v23, v227
	v_mul_f32_e32 v20, v20, v228
	v_mul_f32_e32 v21, v21, v228
	v_mul_f32_e32 v22, v22, v228
	v_mul_f32_e32 v23, v23, v228
	v_mul_f32_e32 v12, v12, v16
	v_mul_f32_e32 v13, v13, v17
	v_mul_f32_e32 v14, v14, v18
	v_mul_f32_e32 v15, v15, v19
	v_mul_f32_e32 v20, v20, v92
	v_mul_f32_e32 v21, v21, v93
	v_mul_f32_e32 v22, v22, v94
	v_mul_f32_e32 v23, v23, v95
	v_mul_f32_e32 v20, v20, v12
	v_mul_f32_e32 v21, v21, v13
	v_mul_f32_e32 v22, v22, v14
	v_mul_f32_e32 v23, v23, v15
	v_cvt_pk_bf16_f32 v20, v20, v21
	v_cvt_pk_bf16_f32 v21, v22, v23
	global_store_dwordx2 v204, v[20:21], s[30:31] offset:192
	s_waitcnt vmcnt(7)
	v_lshlrev_b32_e32 v12, 16, v38
	v_and_b32_e32 v13, 0xffff0000, v38
	v_lshlrev_b32_e32 v14, 16, v39
	v_and_b32_e32 v15, 0xffff0000, v39
	v_mul_f32_e32 v16, 0xbfb8aa3b, v12
	v_mul_f32_e32 v17, 0xbfb8aa3b, v13
	v_mul_f32_e32 v18, 0xbfb8aa3b, v14
	v_mul_f32_e32 v19, 0xbfb8aa3b, v15
	v_exp_f32_e32 v16, v16
	v_exp_f32_e32 v17, v17
	v_exp_f32_e32 v18, v18
	v_exp_f32_e32 v19, v19
	v_lshlrev_b32_e32 v20, 16, v114
	v_and_b32_e32 v21, 0xffff0000, v114
	v_lshlrev_b32_e32 v22, 16, v115
	v_and_b32_e32 v23, 0xffff0000, v115
	v_add_f32_e32 v16, 1.0, v16
	v_add_f32_e32 v17, 1.0, v17
	v_add_f32_e32 v18, 1.0, v18
	v_add_f32_e32 v19, 1.0, v19
	v_rcp_f32_e32 v16, v16
	v_rcp_f32_e32 v17, v17
	v_rcp_f32_e32 v18, v18
	v_rcp_f32_e32 v19, v19
	v_sub_f32_e32 v20, v20, v227
	v_sub_f32_e32 v21, v21, v227
	v_sub_f32_e32 v22, v22, v227
	v_sub_f32_e32 v23, v23, v227
	v_mul_f32_e32 v20, v20, v228
	v_mul_f32_e32 v21, v21, v228
	v_mul_f32_e32 v22, v22, v228
	v_mul_f32_e32 v23, v23, v228
	v_mul_f32_e32 v12, v12, v16
	v_mul_f32_e32 v13, v13, v17
	v_mul_f32_e32 v14, v14, v18
	v_mul_f32_e32 v15, v15, v19
	v_mul_f32_e32 v20, v20, v96
	v_mul_f32_e32 v21, v21, v97
	v_mul_f32_e32 v22, v22, v98
	v_mul_f32_e32 v23, v23, v99
	v_mul_f32_e32 v20, v20, v12
	v_mul_f32_e32 v21, v21, v13
	v_mul_f32_e32 v22, v22, v14
	v_mul_f32_e32 v23, v23, v15
	v_cvt_pk_bf16_f32 v20, v20, v21
	v_cvt_pk_bf16_f32 v21, v22, v23
	global_store_dwordx2 v204, v[20:21], s[30:31] offset:224
	global_load_dwordx2 v[24:25], v205, s[34:35] offset:256
	global_load_dwordx2 v[100:101], v204, s[30:31] offset:256
	global_load_dwordx4 v[68:71], v206, s[28:29] offset:512
	global_load_dwordx2 v[26:27], v205, s[34:35] offset:288
	global_load_dwordx2 v[102:103], v204, s[30:31] offset:288
	global_load_dwordx4 v[72:75], v206, s[28:29] offset:576
	global_load_dwordx2 v[28:29], v205, s[34:35] offset:320
	global_load_dwordx2 v[104:105], v204, s[30:31] offset:320
	global_load_dwordx4 v[76:79], v206, s[28:29] offset:640
	global_load_dwordx2 v[30:31], v205, s[34:35] offset:352
	global_load_dwordx2 v[106:107], v204, s[30:31] offset:352
	global_load_dwordx4 v[80:83], v206, s[28:29] offset:704
	global_load_dwordx2 v[32:33], v205, s[34:35] offset:384
	global_load_dwordx2 v[108:109], v204, s[30:31] offset:384
	global_load_dwordx4 v[84:87], v206, s[28:29] offset:768
	global_load_dwordx2 v[34:35], v205, s[34:35] offset:416
	global_load_dwordx2 v[110:111], v204, s[30:31] offset:416
	global_load_dwordx4 v[88:91], v206, s[28:29] offset:832
	global_load_dwordx2 v[36:37], v205, s[34:35] offset:448
	global_load_dwordx2 v[112:113], v204, s[30:31] offset:448
	global_load_dwordx4 v[92:95], v206, s[28:29] offset:896
	global_load_dwordx2 v[38:39], v205, s[34:35] offset:480
	global_load_dwordx2 v[114:115], v204, s[30:31] offset:480
	global_load_dwordx4 v[96:99], v206, s[28:29] offset:960
	s_waitcnt vmcnt(21)
	v_lshlrev_b32_e32 v12, 16, v24
	v_and_b32_e32 v13, 0xffff0000, v24
	v_lshlrev_b32_e32 v14, 16, v25
	v_and_b32_e32 v15, 0xffff0000, v25
	v_mul_f32_e32 v16, 0xbfb8aa3b, v12
	v_mul_f32_e32 v17, 0xbfb8aa3b, v13
	v_mul_f32_e32 v18, 0xbfb8aa3b, v14
	v_mul_f32_e32 v19, 0xbfb8aa3b, v15
	v_exp_f32_e32 v16, v16
	v_exp_f32_e32 v17, v17
	v_exp_f32_e32 v18, v18
	v_exp_f32_e32 v19, v19
	v_lshlrev_b32_e32 v20, 16, v100
	v_and_b32_e32 v21, 0xffff0000, v100
	v_lshlrev_b32_e32 v22, 16, v101
	v_and_b32_e32 v23, 0xffff0000, v101
	v_add_f32_e32 v16, 1.0, v16
	v_add_f32_e32 v17, 1.0, v17
	v_add_f32_e32 v18, 1.0, v18
	v_add_f32_e32 v19, 1.0, v19
	v_rcp_f32_e32 v16, v16
	v_rcp_f32_e32 v17, v17
	v_rcp_f32_e32 v18, v18
	v_rcp_f32_e32 v19, v19
	v_sub_f32_e32 v20, v20, v227
	v_sub_f32_e32 v21, v21, v227
	v_sub_f32_e32 v22, v22, v227
	v_sub_f32_e32 v23, v23, v227
	v_mul_f32_e32 v20, v20, v228
	v_mul_f32_e32 v21, v21, v228
	v_mul_f32_e32 v22, v22, v228
	v_mul_f32_e32 v23, v23, v228
	v_mul_f32_e32 v12, v12, v16
	v_mul_f32_e32 v13, v13, v17
	v_mul_f32_e32 v14, v14, v18
	v_mul_f32_e32 v15, v15, v19
	v_mul_f32_e32 v20, v20, v68
	v_mul_f32_e32 v21, v21, v69
	v_mul_f32_e32 v22, v22, v70
	v_mul_f32_e32 v23, v23, v71
	v_mul_f32_e32 v20, v20, v12
	v_mul_f32_e32 v21, v21, v13
	v_mul_f32_e32 v22, v22, v14
	v_mul_f32_e32 v23, v23, v15
	v_cvt_pk_bf16_f32 v20, v20, v21
	v_cvt_pk_bf16_f32 v21, v22, v23
	global_store_dwordx2 v204, v[20:21], s[30:31] offset:256
	s_waitcnt vmcnt(19)
	v_lshlrev_b32_e32 v12, 16, v26
	v_and_b32_e32 v13, 0xffff0000, v26
	v_lshlrev_b32_e32 v14, 16, v27
	v_and_b32_e32 v15, 0xffff0000, v27
	v_mul_f32_e32 v16, 0xbfb8aa3b, v12
	v_mul_f32_e32 v17, 0xbfb8aa3b, v13
	v_mul_f32_e32 v18, 0xbfb8aa3b, v14
	v_mul_f32_e32 v19, 0xbfb8aa3b, v15
	v_exp_f32_e32 v16, v16
	v_exp_f32_e32 v17, v17
	v_exp_f32_e32 v18, v18
	v_exp_f32_e32 v19, v19
	v_lshlrev_b32_e32 v20, 16, v102
	v_and_b32_e32 v21, 0xffff0000, v102
	v_lshlrev_b32_e32 v22, 16, v103
	v_and_b32_e32 v23, 0xffff0000, v103
	v_add_f32_e32 v16, 1.0, v16
	v_add_f32_e32 v17, 1.0, v17
	v_add_f32_e32 v18, 1.0, v18
	v_add_f32_e32 v19, 1.0, v19
	v_rcp_f32_e32 v16, v16
	v_rcp_f32_e32 v17, v17
	v_rcp_f32_e32 v18, v18
	v_rcp_f32_e32 v19, v19
	v_sub_f32_e32 v20, v20, v227
	v_sub_f32_e32 v21, v21, v227
	v_sub_f32_e32 v22, v22, v227
	v_sub_f32_e32 v23, v23, v227
	v_mul_f32_e32 v20, v20, v228
	v_mul_f32_e32 v21, v21, v228
	v_mul_f32_e32 v22, v22, v228
	v_mul_f32_e32 v23, v23, v228
	v_mul_f32_e32 v12, v12, v16
	v_mul_f32_e32 v13, v13, v17
	v_mul_f32_e32 v14, v14, v18
	v_mul_f32_e32 v15, v15, v19
	v_mul_f32_e32 v20, v20, v72
	v_mul_f32_e32 v21, v21, v73
	v_mul_f32_e32 v22, v22, v74
	v_mul_f32_e32 v23, v23, v75
	v_mul_f32_e32 v20, v20, v12
	v_mul_f32_e32 v21, v21, v13
	v_mul_f32_e32 v22, v22, v14
	v_mul_f32_e32 v23, v23, v15
	v_cvt_pk_bf16_f32 v20, v20, v21
	v_cvt_pk_bf16_f32 v21, v22, v23
	global_store_dwordx2 v204, v[20:21], s[30:31] offset:288
	s_waitcnt vmcnt(17)
	v_lshlrev_b32_e32 v12, 16, v28
	v_and_b32_e32 v13, 0xffff0000, v28
	v_lshlrev_b32_e32 v14, 16, v29
	v_and_b32_e32 v15, 0xffff0000, v29
	v_mul_f32_e32 v16, 0xbfb8aa3b, v12
	v_mul_f32_e32 v17, 0xbfb8aa3b, v13
	v_mul_f32_e32 v18, 0xbfb8aa3b, v14
	v_mul_f32_e32 v19, 0xbfb8aa3b, v15
	v_exp_f32_e32 v16, v16
	v_exp_f32_e32 v17, v17
	v_exp_f32_e32 v18, v18
	v_exp_f32_e32 v19, v19
	v_lshlrev_b32_e32 v20, 16, v104
	v_and_b32_e32 v21, 0xffff0000, v104
	v_lshlrev_b32_e32 v22, 16, v105
	v_and_b32_e32 v23, 0xffff0000, v105
	v_add_f32_e32 v16, 1.0, v16
	v_add_f32_e32 v17, 1.0, v17
	v_add_f32_e32 v18, 1.0, v18
	v_add_f32_e32 v19, 1.0, v19
	v_rcp_f32_e32 v16, v16
	v_rcp_f32_e32 v17, v17
	v_rcp_f32_e32 v18, v18
	v_rcp_f32_e32 v19, v19
	v_sub_f32_e32 v20, v20, v227
	v_sub_f32_e32 v21, v21, v227
	v_sub_f32_e32 v22, v22, v227
	v_sub_f32_e32 v23, v23, v227
	v_mul_f32_e32 v20, v20, v228
	v_mul_f32_e32 v21, v21, v228
	v_mul_f32_e32 v22, v22, v228
	v_mul_f32_e32 v23, v23, v228
	v_mul_f32_e32 v12, v12, v16
	v_mul_f32_e32 v13, v13, v17
	v_mul_f32_e32 v14, v14, v18
	v_mul_f32_e32 v15, v15, v19
	v_mul_f32_e32 v20, v20, v76
	v_mul_f32_e32 v21, v21, v77
	v_mul_f32_e32 v22, v22, v78
	v_mul_f32_e32 v23, v23, v79
	v_mul_f32_e32 v20, v20, v12
	v_mul_f32_e32 v21, v21, v13
	v_mul_f32_e32 v22, v22, v14
	v_mul_f32_e32 v23, v23, v15
	v_cvt_pk_bf16_f32 v20, v20, v21
	v_cvt_pk_bf16_f32 v21, v22, v23
	global_store_dwordx2 v204, v[20:21], s[30:31] offset:320
	s_waitcnt vmcnt(15)
	v_lshlrev_b32_e32 v12, 16, v30
	v_and_b32_e32 v13, 0xffff0000, v30
	v_lshlrev_b32_e32 v14, 16, v31
	v_and_b32_e32 v15, 0xffff0000, v31
	v_mul_f32_e32 v16, 0xbfb8aa3b, v12
	v_mul_f32_e32 v17, 0xbfb8aa3b, v13
	v_mul_f32_e32 v18, 0xbfb8aa3b, v14
	v_mul_f32_e32 v19, 0xbfb8aa3b, v15
	v_exp_f32_e32 v16, v16
	v_exp_f32_e32 v17, v17
	v_exp_f32_e32 v18, v18
	v_exp_f32_e32 v19, v19
	v_lshlrev_b32_e32 v20, 16, v106
	v_and_b32_e32 v21, 0xffff0000, v106
	v_lshlrev_b32_e32 v22, 16, v107
	v_and_b32_e32 v23, 0xffff0000, v107
	v_add_f32_e32 v16, 1.0, v16
	v_add_f32_e32 v17, 1.0, v17
	v_add_f32_e32 v18, 1.0, v18
	v_add_f32_e32 v19, 1.0, v19
	v_rcp_f32_e32 v16, v16
	v_rcp_f32_e32 v17, v17
	v_rcp_f32_e32 v18, v18
	v_rcp_f32_e32 v19, v19
	v_sub_f32_e32 v20, v20, v227
	v_sub_f32_e32 v21, v21, v227
	v_sub_f32_e32 v22, v22, v227
	v_sub_f32_e32 v23, v23, v227
	v_mul_f32_e32 v20, v20, v228
	v_mul_f32_e32 v21, v21, v228
	v_mul_f32_e32 v22, v22, v228
	v_mul_f32_e32 v23, v23, v228
	v_mul_f32_e32 v12, v12, v16
	v_mul_f32_e32 v13, v13, v17
	v_mul_f32_e32 v14, v14, v18
	v_mul_f32_e32 v15, v15, v19
	v_mul_f32_e32 v20, v20, v80
	v_mul_f32_e32 v21, v21, v81
	v_mul_f32_e32 v22, v22, v82
	v_mul_f32_e32 v23, v23, v83
	v_mul_f32_e32 v20, v20, v12
	v_mul_f32_e32 v21, v21, v13
	v_mul_f32_e32 v22, v22, v14
	v_mul_f32_e32 v23, v23, v15
	v_cvt_pk_bf16_f32 v20, v20, v21
	v_cvt_pk_bf16_f32 v21, v22, v23
	global_store_dwordx2 v204, v[20:21], s[30:31] offset:352
	s_waitcnt vmcnt(13)
	v_lshlrev_b32_e32 v12, 16, v32
	v_and_b32_e32 v13, 0xffff0000, v32
	v_lshlrev_b32_e32 v14, 16, v33
	v_and_b32_e32 v15, 0xffff0000, v33
	v_mul_f32_e32 v16, 0xbfb8aa3b, v12
	v_mul_f32_e32 v17, 0xbfb8aa3b, v13
	v_mul_f32_e32 v18, 0xbfb8aa3b, v14
	v_mul_f32_e32 v19, 0xbfb8aa3b, v15
	v_exp_f32_e32 v16, v16
	v_exp_f32_e32 v17, v17
	v_exp_f32_e32 v18, v18
	v_exp_f32_e32 v19, v19
	v_lshlrev_b32_e32 v20, 16, v108
	v_and_b32_e32 v21, 0xffff0000, v108
	v_lshlrev_b32_e32 v22, 16, v109
	v_and_b32_e32 v23, 0xffff0000, v109
	v_add_f32_e32 v16, 1.0, v16
	v_add_f32_e32 v17, 1.0, v17
	v_add_f32_e32 v18, 1.0, v18
	v_add_f32_e32 v19, 1.0, v19
	v_rcp_f32_e32 v16, v16
	v_rcp_f32_e32 v17, v17
	v_rcp_f32_e32 v18, v18
	v_rcp_f32_e32 v19, v19
	v_sub_f32_e32 v20, v20, v227
	v_sub_f32_e32 v21, v21, v227
	v_sub_f32_e32 v22, v22, v227
	v_sub_f32_e32 v23, v23, v227
	v_mul_f32_e32 v20, v20, v228
	v_mul_f32_e32 v21, v21, v228
	v_mul_f32_e32 v22, v22, v228
	v_mul_f32_e32 v23, v23, v228
	v_mul_f32_e32 v12, v12, v16
	v_mul_f32_e32 v13, v13, v17
	v_mul_f32_e32 v14, v14, v18
	v_mul_f32_e32 v15, v15, v19
	v_mul_f32_e32 v20, v20, v84
	v_mul_f32_e32 v21, v21, v85
	v_mul_f32_e32 v22, v22, v86
	v_mul_f32_e32 v23, v23, v87
	v_mul_f32_e32 v20, v20, v12
	v_mul_f32_e32 v21, v21, v13
	v_mul_f32_e32 v22, v22, v14
	v_mul_f32_e32 v23, v23, v15
	v_cvt_pk_bf16_f32 v20, v20, v21
	v_cvt_pk_bf16_f32 v21, v22, v23
	global_store_dwordx2 v204, v[20:21], s[30:31] offset:384
	s_waitcnt vmcnt(11)
	v_lshlrev_b32_e32 v12, 16, v34
	v_and_b32_e32 v13, 0xffff0000, v34
	v_lshlrev_b32_e32 v14, 16, v35
	v_and_b32_e32 v15, 0xffff0000, v35
	v_mul_f32_e32 v16, 0xbfb8aa3b, v12
	v_mul_f32_e32 v17, 0xbfb8aa3b, v13
	v_mul_f32_e32 v18, 0xbfb8aa3b, v14
	v_mul_f32_e32 v19, 0xbfb8aa3b, v15
	v_exp_f32_e32 v16, v16
	v_exp_f32_e32 v17, v17
	v_exp_f32_e32 v18, v18
	v_exp_f32_e32 v19, v19
	v_lshlrev_b32_e32 v20, 16, v110
	v_and_b32_e32 v21, 0xffff0000, v110
	v_lshlrev_b32_e32 v22, 16, v111
	v_and_b32_e32 v23, 0xffff0000, v111
	v_add_f32_e32 v16, 1.0, v16
	v_add_f32_e32 v17, 1.0, v17
	v_add_f32_e32 v18, 1.0, v18
	v_add_f32_e32 v19, 1.0, v19
	v_rcp_f32_e32 v16, v16
	v_rcp_f32_e32 v17, v17
	v_rcp_f32_e32 v18, v18
	v_rcp_f32_e32 v19, v19
	v_sub_f32_e32 v20, v20, v227
	v_sub_f32_e32 v21, v21, v227
	v_sub_f32_e32 v22, v22, v227
	v_sub_f32_e32 v23, v23, v227
	v_mul_f32_e32 v20, v20, v228
	v_mul_f32_e32 v21, v21, v228
	v_mul_f32_e32 v22, v22, v228
	v_mul_f32_e32 v23, v23, v228
	v_mul_f32_e32 v12, v12, v16
	v_mul_f32_e32 v13, v13, v17
	v_mul_f32_e32 v14, v14, v18
	v_mul_f32_e32 v15, v15, v19
	v_mul_f32_e32 v20, v20, v88
	v_mul_f32_e32 v21, v21, v89
	v_mul_f32_e32 v22, v22, v90
	v_mul_f32_e32 v23, v23, v91
	v_mul_f32_e32 v20, v20, v12
	v_mul_f32_e32 v21, v21, v13
	v_mul_f32_e32 v22, v22, v14
	v_mul_f32_e32 v23, v23, v15
	v_cvt_pk_bf16_f32 v20, v20, v21
	v_cvt_pk_bf16_f32 v21, v22, v23
	global_store_dwordx2 v204, v[20:21], s[30:31] offset:416
	s_waitcnt vmcnt(9)
	v_lshlrev_b32_e32 v12, 16, v36
	v_and_b32_e32 v13, 0xffff0000, v36
	v_lshlrev_b32_e32 v14, 16, v37
	v_and_b32_e32 v15, 0xffff0000, v37
	v_mul_f32_e32 v16, 0xbfb8aa3b, v12
	v_mul_f32_e32 v17, 0xbfb8aa3b, v13
	v_mul_f32_e32 v18, 0xbfb8aa3b, v14
	v_mul_f32_e32 v19, 0xbfb8aa3b, v15
	v_exp_f32_e32 v16, v16
	v_exp_f32_e32 v17, v17
	v_exp_f32_e32 v18, v18
	v_exp_f32_e32 v19, v19
	v_lshlrev_b32_e32 v20, 16, v112
	v_and_b32_e32 v21, 0xffff0000, v112
	v_lshlrev_b32_e32 v22, 16, v113
	v_and_b32_e32 v23, 0xffff0000, v113
	v_add_f32_e32 v16, 1.0, v16
	v_add_f32_e32 v17, 1.0, v17
	v_add_f32_e32 v18, 1.0, v18
	v_add_f32_e32 v19, 1.0, v19
	v_rcp_f32_e32 v16, v16
	v_rcp_f32_e32 v17, v17
	v_rcp_f32_e32 v18, v18
	v_rcp_f32_e32 v19, v19
	v_sub_f32_e32 v20, v20, v227
	v_sub_f32_e32 v21, v21, v227
	v_sub_f32_e32 v22, v22, v227
	v_sub_f32_e32 v23, v23, v227
	v_mul_f32_e32 v20, v20, v228
	v_mul_f32_e32 v21, v21, v228
	v_mul_f32_e32 v22, v22, v228
	v_mul_f32_e32 v23, v23, v228
	v_mul_f32_e32 v12, v12, v16
	v_mul_f32_e32 v13, v13, v17
	v_mul_f32_e32 v14, v14, v18
	v_mul_f32_e32 v15, v15, v19
	v_mul_f32_e32 v20, v20, v92
	v_mul_f32_e32 v21, v21, v93
	v_mul_f32_e32 v22, v22, v94
	v_mul_f32_e32 v23, v23, v95
	v_mul_f32_e32 v20, v20, v12
	v_mul_f32_e32 v21, v21, v13
	v_mul_f32_e32 v22, v22, v14
	v_mul_f32_e32 v23, v23, v15
	v_cvt_pk_bf16_f32 v20, v20, v21
	v_cvt_pk_bf16_f32 v21, v22, v23
	global_store_dwordx2 v204, v[20:21], s[30:31] offset:448
	s_waitcnt vmcnt(7)
	v_lshlrev_b32_e32 v12, 16, v38
	v_and_b32_e32 v13, 0xffff0000, v38
	v_lshlrev_b32_e32 v14, 16, v39
	v_and_b32_e32 v15, 0xffff0000, v39
	v_mul_f32_e32 v16, 0xbfb8aa3b, v12
	v_mul_f32_e32 v17, 0xbfb8aa3b, v13
	v_mul_f32_e32 v18, 0xbfb8aa3b, v14
	v_mul_f32_e32 v19, 0xbfb8aa3b, v15
	v_exp_f32_e32 v16, v16
	v_exp_f32_e32 v17, v17
	v_exp_f32_e32 v18, v18
	v_exp_f32_e32 v19, v19
	v_lshlrev_b32_e32 v20, 16, v114
	v_and_b32_e32 v21, 0xffff0000, v114
	v_lshlrev_b32_e32 v22, 16, v115
	v_and_b32_e32 v23, 0xffff0000, v115
	v_add_f32_e32 v16, 1.0, v16
	v_add_f32_e32 v17, 1.0, v17
	v_add_f32_e32 v18, 1.0, v18
	v_add_f32_e32 v19, 1.0, v19
	v_rcp_f32_e32 v16, v16
	v_rcp_f32_e32 v17, v17
	v_rcp_f32_e32 v18, v18
	v_rcp_f32_e32 v19, v19
	v_sub_f32_e32 v20, v20, v227
	v_sub_f32_e32 v21, v21, v227
	v_sub_f32_e32 v22, v22, v227
	v_sub_f32_e32 v23, v23, v227
	v_mul_f32_e32 v20, v20, v228
	v_mul_f32_e32 v21, v21, v228
	v_mul_f32_e32 v22, v22, v228
	v_mul_f32_e32 v23, v23, v228
	v_mul_f32_e32 v12, v12, v16
	v_mul_f32_e32 v13, v13, v17
	v_mul_f32_e32 v14, v14, v18
	v_mul_f32_e32 v15, v15, v19
	v_mul_f32_e32 v20, v20, v96
	v_mul_f32_e32 v21, v21, v97
	v_mul_f32_e32 v22, v22, v98
	v_mul_f32_e32 v23, v23, v99
	v_mul_f32_e32 v20, v20, v12
	v_mul_f32_e32 v21, v21, v13
	v_mul_f32_e32 v22, v22, v14
	v_mul_f32_e32 v23, v23, v15
	v_cvt_pk_bf16_f32 v20, v20, v21
	v_cvt_pk_bf16_f32 v21, v22, v23
	global_store_dwordx2 v204, v[20:21], s[30:31] offset:480
	global_load_dwordx2 v[24:25], v205, s[34:35] offset:512
	global_load_dwordx2 v[100:101], v204, s[30:31] offset:512
	global_load_dwordx4 v[68:71], v206, s[28:29] offset:1024
	global_load_dwordx2 v[26:27], v205, s[34:35] offset:544
	global_load_dwordx2 v[102:103], v204, s[30:31] offset:544
	global_load_dwordx4 v[72:75], v206, s[28:29] offset:1088
	global_load_dwordx2 v[28:29], v205, s[34:35] offset:576
	global_load_dwordx2 v[104:105], v204, s[30:31] offset:576
	global_load_dwordx4 v[76:79], v206, s[28:29] offset:1152
	global_load_dwordx2 v[30:31], v205, s[34:35] offset:608
	global_load_dwordx2 v[106:107], v204, s[30:31] offset:608
	global_load_dwordx4 v[80:83], v206, s[28:29] offset:1216
	global_load_dwordx2 v[32:33], v205, s[34:35] offset:640
	global_load_dwordx2 v[108:109], v204, s[30:31] offset:640
	global_load_dwordx4 v[84:87], v206, s[28:29] offset:1280
	global_load_dwordx2 v[34:35], v205, s[34:35] offset:672
	global_load_dwordx2 v[110:111], v204, s[30:31] offset:672
	global_load_dwordx4 v[88:91], v206, s[28:29] offset:1344
	global_load_dwordx2 v[36:37], v205, s[34:35] offset:704
	global_load_dwordx2 v[112:113], v204, s[30:31] offset:704
	global_load_dwordx4 v[92:95], v206, s[28:29] offset:1408
	global_load_dwordx2 v[38:39], v205, s[34:35] offset:736
	global_load_dwordx2 v[114:115], v204, s[30:31] offset:736
	global_load_dwordx4 v[96:99], v206, s[28:29] offset:1472
	s_waitcnt vmcnt(21)
	v_lshlrev_b32_e32 v12, 16, v24
	v_and_b32_e32 v13, 0xffff0000, v24
	v_lshlrev_b32_e32 v14, 16, v25
	v_and_b32_e32 v15, 0xffff0000, v25
	v_mul_f32_e32 v16, 0xbfb8aa3b, v12
	v_mul_f32_e32 v17, 0xbfb8aa3b, v13
	v_mul_f32_e32 v18, 0xbfb8aa3b, v14
	v_mul_f32_e32 v19, 0xbfb8aa3b, v15
	v_exp_f32_e32 v16, v16
	v_exp_f32_e32 v17, v17
	v_exp_f32_e32 v18, v18
	v_exp_f32_e32 v19, v19
	v_lshlrev_b32_e32 v20, 16, v100
	v_and_b32_e32 v21, 0xffff0000, v100
	v_lshlrev_b32_e32 v22, 16, v101
	v_and_b32_e32 v23, 0xffff0000, v101
	v_add_f32_e32 v16, 1.0, v16
	v_add_f32_e32 v17, 1.0, v17
	v_add_f32_e32 v18, 1.0, v18
	v_add_f32_e32 v19, 1.0, v19
	v_rcp_f32_e32 v16, v16
	v_rcp_f32_e32 v17, v17
	v_rcp_f32_e32 v18, v18
	v_rcp_f32_e32 v19, v19
	v_sub_f32_e32 v20, v20, v227
	v_sub_f32_e32 v21, v21, v227
	v_sub_f32_e32 v22, v22, v227
	v_sub_f32_e32 v23, v23, v227
	v_mul_f32_e32 v20, v20, v228
	v_mul_f32_e32 v21, v21, v228
	v_mul_f32_e32 v22, v22, v228
	v_mul_f32_e32 v23, v23, v228
	v_mul_f32_e32 v12, v12, v16
	v_mul_f32_e32 v13, v13, v17
	v_mul_f32_e32 v14, v14, v18
	v_mul_f32_e32 v15, v15, v19
	v_mul_f32_e32 v20, v20, v68
	v_mul_f32_e32 v21, v21, v69
	v_mul_f32_e32 v22, v22, v70
	v_mul_f32_e32 v23, v23, v71
	v_mul_f32_e32 v20, v20, v12
	v_mul_f32_e32 v21, v21, v13
	v_mul_f32_e32 v22, v22, v14
	v_mul_f32_e32 v23, v23, v15
	v_cvt_pk_bf16_f32 v20, v20, v21
	v_cvt_pk_bf16_f32 v21, v22, v23
	global_store_dwordx2 v204, v[20:21], s[30:31] offset:512
	s_waitcnt vmcnt(19)
	v_lshlrev_b32_e32 v12, 16, v26
	v_and_b32_e32 v13, 0xffff0000, v26
	v_lshlrev_b32_e32 v14, 16, v27
	v_and_b32_e32 v15, 0xffff0000, v27
	v_mul_f32_e32 v16, 0xbfb8aa3b, v12
	v_mul_f32_e32 v17, 0xbfb8aa3b, v13
	v_mul_f32_e32 v18, 0xbfb8aa3b, v14
	v_mul_f32_e32 v19, 0xbfb8aa3b, v15
	v_exp_f32_e32 v16, v16
	v_exp_f32_e32 v17, v17
	v_exp_f32_e32 v18, v18
	v_exp_f32_e32 v19, v19
	v_lshlrev_b32_e32 v20, 16, v102
	v_and_b32_e32 v21, 0xffff0000, v102
	v_lshlrev_b32_e32 v22, 16, v103
	v_and_b32_e32 v23, 0xffff0000, v103
	v_add_f32_e32 v16, 1.0, v16
	v_add_f32_e32 v17, 1.0, v17
	v_add_f32_e32 v18, 1.0, v18
	v_add_f32_e32 v19, 1.0, v19
	v_rcp_f32_e32 v16, v16
	v_rcp_f32_e32 v17, v17
	v_rcp_f32_e32 v18, v18
	v_rcp_f32_e32 v19, v19
	v_sub_f32_e32 v20, v20, v227
	v_sub_f32_e32 v21, v21, v227
	v_sub_f32_e32 v22, v22, v227
	v_sub_f32_e32 v23, v23, v227
	v_mul_f32_e32 v20, v20, v228
	v_mul_f32_e32 v21, v21, v228
	v_mul_f32_e32 v22, v22, v228
	v_mul_f32_e32 v23, v23, v228
	v_mul_f32_e32 v12, v12, v16
	v_mul_f32_e32 v13, v13, v17
	v_mul_f32_e32 v14, v14, v18
	v_mul_f32_e32 v15, v15, v19
	v_mul_f32_e32 v20, v20, v72
	v_mul_f32_e32 v21, v21, v73
	v_mul_f32_e32 v22, v22, v74
	v_mul_f32_e32 v23, v23, v75
	v_mul_f32_e32 v20, v20, v12
	v_mul_f32_e32 v21, v21, v13
	v_mul_f32_e32 v22, v22, v14
	v_mul_f32_e32 v23, v23, v15
	v_cvt_pk_bf16_f32 v20, v20, v21
	v_cvt_pk_bf16_f32 v21, v22, v23
	global_store_dwordx2 v204, v[20:21], s[30:31] offset:544
	s_waitcnt vmcnt(17)
	v_lshlrev_b32_e32 v12, 16, v28
	v_and_b32_e32 v13, 0xffff0000, v28
	v_lshlrev_b32_e32 v14, 16, v29
	v_and_b32_e32 v15, 0xffff0000, v29
	v_mul_f32_e32 v16, 0xbfb8aa3b, v12
	v_mul_f32_e32 v17, 0xbfb8aa3b, v13
	v_mul_f32_e32 v18, 0xbfb8aa3b, v14
	v_mul_f32_e32 v19, 0xbfb8aa3b, v15
	v_exp_f32_e32 v16, v16
	v_exp_f32_e32 v17, v17
	v_exp_f32_e32 v18, v18
	v_exp_f32_e32 v19, v19
	v_lshlrev_b32_e32 v20, 16, v104
	v_and_b32_e32 v21, 0xffff0000, v104
	v_lshlrev_b32_e32 v22, 16, v105
	v_and_b32_e32 v23, 0xffff0000, v105
	v_add_f32_e32 v16, 1.0, v16
	v_add_f32_e32 v17, 1.0, v17
	v_add_f32_e32 v18, 1.0, v18
	v_add_f32_e32 v19, 1.0, v19
	v_rcp_f32_e32 v16, v16
	v_rcp_f32_e32 v17, v17
	v_rcp_f32_e32 v18, v18
	v_rcp_f32_e32 v19, v19
	v_sub_f32_e32 v20, v20, v227
	v_sub_f32_e32 v21, v21, v227
	v_sub_f32_e32 v22, v22, v227
	v_sub_f32_e32 v23, v23, v227
	v_mul_f32_e32 v20, v20, v228
	v_mul_f32_e32 v21, v21, v228
	v_mul_f32_e32 v22, v22, v228
	v_mul_f32_e32 v23, v23, v228
	v_mul_f32_e32 v12, v12, v16
	v_mul_f32_e32 v13, v13, v17
	v_mul_f32_e32 v14, v14, v18
	v_mul_f32_e32 v15, v15, v19
	v_mul_f32_e32 v20, v20, v76
	v_mul_f32_e32 v21, v21, v77
	v_mul_f32_e32 v22, v22, v78
	v_mul_f32_e32 v23, v23, v79
	v_mul_f32_e32 v20, v20, v12
	v_mul_f32_e32 v21, v21, v13
	v_mul_f32_e32 v22, v22, v14
	v_mul_f32_e32 v23, v23, v15
	v_cvt_pk_bf16_f32 v20, v20, v21
	v_cvt_pk_bf16_f32 v21, v22, v23
	global_store_dwordx2 v204, v[20:21], s[30:31] offset:576
	s_waitcnt vmcnt(15)
	v_lshlrev_b32_e32 v12, 16, v30
	v_and_b32_e32 v13, 0xffff0000, v30
	v_lshlrev_b32_e32 v14, 16, v31
	v_and_b32_e32 v15, 0xffff0000, v31
	v_mul_f32_e32 v16, 0xbfb8aa3b, v12
	v_mul_f32_e32 v17, 0xbfb8aa3b, v13
	v_mul_f32_e32 v18, 0xbfb8aa3b, v14
	v_mul_f32_e32 v19, 0xbfb8aa3b, v15
	v_exp_f32_e32 v16, v16
	v_exp_f32_e32 v17, v17
	v_exp_f32_e32 v18, v18
	v_exp_f32_e32 v19, v19
	v_lshlrev_b32_e32 v20, 16, v106
	v_and_b32_e32 v21, 0xffff0000, v106
	v_lshlrev_b32_e32 v22, 16, v107
	v_and_b32_e32 v23, 0xffff0000, v107
	v_add_f32_e32 v16, 1.0, v16
	v_add_f32_e32 v17, 1.0, v17
	v_add_f32_e32 v18, 1.0, v18
	v_add_f32_e32 v19, 1.0, v19
	v_rcp_f32_e32 v16, v16
	v_rcp_f32_e32 v17, v17
	v_rcp_f32_e32 v18, v18
	v_rcp_f32_e32 v19, v19
	v_sub_f32_e32 v20, v20, v227
	v_sub_f32_e32 v21, v21, v227
	v_sub_f32_e32 v22, v22, v227
	v_sub_f32_e32 v23, v23, v227
	v_mul_f32_e32 v20, v20, v228
	v_mul_f32_e32 v21, v21, v228
	v_mul_f32_e32 v22, v22, v228
	v_mul_f32_e32 v23, v23, v228
	v_mul_f32_e32 v12, v12, v16
	v_mul_f32_e32 v13, v13, v17
	v_mul_f32_e32 v14, v14, v18
	v_mul_f32_e32 v15, v15, v19
	v_mul_f32_e32 v20, v20, v80
	v_mul_f32_e32 v21, v21, v81
	v_mul_f32_e32 v22, v22, v82
	v_mul_f32_e32 v23, v23, v83
	v_mul_f32_e32 v20, v20, v12
	v_mul_f32_e32 v21, v21, v13
	v_mul_f32_e32 v22, v22, v14
	v_mul_f32_e32 v23, v23, v15
	v_cvt_pk_bf16_f32 v20, v20, v21
	v_cvt_pk_bf16_f32 v21, v22, v23
	global_store_dwordx2 v204, v[20:21], s[30:31] offset:608
	s_waitcnt vmcnt(13)
	v_lshlrev_b32_e32 v12, 16, v32
	v_and_b32_e32 v13, 0xffff0000, v32
	v_lshlrev_b32_e32 v14, 16, v33
	v_and_b32_e32 v15, 0xffff0000, v33
	v_mul_f32_e32 v16, 0xbfb8aa3b, v12
	v_mul_f32_e32 v17, 0xbfb8aa3b, v13
	v_mul_f32_e32 v18, 0xbfb8aa3b, v14
	v_mul_f32_e32 v19, 0xbfb8aa3b, v15
	v_exp_f32_e32 v16, v16
	v_exp_f32_e32 v17, v17
	v_exp_f32_e32 v18, v18
	v_exp_f32_e32 v19, v19
	v_lshlrev_b32_e32 v20, 16, v108
	v_and_b32_e32 v21, 0xffff0000, v108
	v_lshlrev_b32_e32 v22, 16, v109
	v_and_b32_e32 v23, 0xffff0000, v109
	v_add_f32_e32 v16, 1.0, v16
	v_add_f32_e32 v17, 1.0, v17
	v_add_f32_e32 v18, 1.0, v18
	v_add_f32_e32 v19, 1.0, v19
	v_rcp_f32_e32 v16, v16
	v_rcp_f32_e32 v17, v17
	v_rcp_f32_e32 v18, v18
	v_rcp_f32_e32 v19, v19
	v_sub_f32_e32 v20, v20, v227
	v_sub_f32_e32 v21, v21, v227
	v_sub_f32_e32 v22, v22, v227
	v_sub_f32_e32 v23, v23, v227
	v_mul_f32_e32 v20, v20, v228
	v_mul_f32_e32 v21, v21, v228
	v_mul_f32_e32 v22, v22, v228
	v_mul_f32_e32 v23, v23, v228
	v_mul_f32_e32 v12, v12, v16
	v_mul_f32_e32 v13, v13, v17
	v_mul_f32_e32 v14, v14, v18
	v_mul_f32_e32 v15, v15, v19
	v_mul_f32_e32 v20, v20, v84
	v_mul_f32_e32 v21, v21, v85
	v_mul_f32_e32 v22, v22, v86
	v_mul_f32_e32 v23, v23, v87
	v_mul_f32_e32 v20, v20, v12
	v_mul_f32_e32 v21, v21, v13
	v_mul_f32_e32 v22, v22, v14
	v_mul_f32_e32 v23, v23, v15
	v_cvt_pk_bf16_f32 v20, v20, v21
	v_cvt_pk_bf16_f32 v21, v22, v23
	global_store_dwordx2 v204, v[20:21], s[30:31] offset:640
	s_waitcnt vmcnt(11)
	v_lshlrev_b32_e32 v12, 16, v34
	v_and_b32_e32 v13, 0xffff0000, v34
	v_lshlrev_b32_e32 v14, 16, v35
	v_and_b32_e32 v15, 0xffff0000, v35
	v_mul_f32_e32 v16, 0xbfb8aa3b, v12
	v_mul_f32_e32 v17, 0xbfb8aa3b, v13
	v_mul_f32_e32 v18, 0xbfb8aa3b, v14
	v_mul_f32_e32 v19, 0xbfb8aa3b, v15
	v_exp_f32_e32 v16, v16
	v_exp_f32_e32 v17, v17
	v_exp_f32_e32 v18, v18
	v_exp_f32_e32 v19, v19
	v_lshlrev_b32_e32 v20, 16, v110
	v_and_b32_e32 v21, 0xffff0000, v110
	v_lshlrev_b32_e32 v22, 16, v111
	v_and_b32_e32 v23, 0xffff0000, v111
	v_add_f32_e32 v16, 1.0, v16
	v_add_f32_e32 v17, 1.0, v17
	v_add_f32_e32 v18, 1.0, v18
	v_add_f32_e32 v19, 1.0, v19
	v_rcp_f32_e32 v16, v16
	v_rcp_f32_e32 v17, v17
	v_rcp_f32_e32 v18, v18
	v_rcp_f32_e32 v19, v19
	v_sub_f32_e32 v20, v20, v227
	v_sub_f32_e32 v21, v21, v227
	v_sub_f32_e32 v22, v22, v227
	v_sub_f32_e32 v23, v23, v227
	v_mul_f32_e32 v20, v20, v228
	v_mul_f32_e32 v21, v21, v228
	v_mul_f32_e32 v22, v22, v228
	v_mul_f32_e32 v23, v23, v228
	v_mul_f32_e32 v12, v12, v16
	v_mul_f32_e32 v13, v13, v17
	v_mul_f32_e32 v14, v14, v18
	v_mul_f32_e32 v15, v15, v19
	v_mul_f32_e32 v20, v20, v88
	v_mul_f32_e32 v21, v21, v89
	v_mul_f32_e32 v22, v22, v90
	v_mul_f32_e32 v23, v23, v91
	v_mul_f32_e32 v20, v20, v12
	v_mul_f32_e32 v21, v21, v13
	v_mul_f32_e32 v22, v22, v14
	v_mul_f32_e32 v23, v23, v15
	v_cvt_pk_bf16_f32 v20, v20, v21
	v_cvt_pk_bf16_f32 v21, v22, v23
	global_store_dwordx2 v204, v[20:21], s[30:31] offset:672
	s_waitcnt vmcnt(9)
	v_lshlrev_b32_e32 v12, 16, v36
	v_and_b32_e32 v13, 0xffff0000, v36
	v_lshlrev_b32_e32 v14, 16, v37
	v_and_b32_e32 v15, 0xffff0000, v37
	v_mul_f32_e32 v16, 0xbfb8aa3b, v12
	v_mul_f32_e32 v17, 0xbfb8aa3b, v13
	v_mul_f32_e32 v18, 0xbfb8aa3b, v14
	v_mul_f32_e32 v19, 0xbfb8aa3b, v15
	v_exp_f32_e32 v16, v16
	v_exp_f32_e32 v17, v17
	v_exp_f32_e32 v18, v18
	v_exp_f32_e32 v19, v19
	v_lshlrev_b32_e32 v20, 16, v112
	v_and_b32_e32 v21, 0xffff0000, v112
	v_lshlrev_b32_e32 v22, 16, v113
	v_and_b32_e32 v23, 0xffff0000, v113
	v_add_f32_e32 v16, 1.0, v16
	v_add_f32_e32 v17, 1.0, v17
	v_add_f32_e32 v18, 1.0, v18
	v_add_f32_e32 v19, 1.0, v19
	v_rcp_f32_e32 v16, v16
	v_rcp_f32_e32 v17, v17
	v_rcp_f32_e32 v18, v18
	v_rcp_f32_e32 v19, v19
	v_sub_f32_e32 v20, v20, v227
	v_sub_f32_e32 v21, v21, v227
	v_sub_f32_e32 v22, v22, v227
	v_sub_f32_e32 v23, v23, v227
	v_mul_f32_e32 v20, v20, v228
	v_mul_f32_e32 v21, v21, v228
	v_mul_f32_e32 v22, v22, v228
	v_mul_f32_e32 v23, v23, v228
	v_mul_f32_e32 v12, v12, v16
	v_mul_f32_e32 v13, v13, v17
	v_mul_f32_e32 v14, v14, v18
	v_mul_f32_e32 v15, v15, v19
	v_mul_f32_e32 v20, v20, v92
	v_mul_f32_e32 v21, v21, v93
	v_mul_f32_e32 v22, v22, v94
	v_mul_f32_e32 v23, v23, v95
	v_mul_f32_e32 v20, v20, v12
	v_mul_f32_e32 v21, v21, v13
	v_mul_f32_e32 v22, v22, v14
	v_mul_f32_e32 v23, v23, v15
	v_cvt_pk_bf16_f32 v20, v20, v21
	v_cvt_pk_bf16_f32 v21, v22, v23
	global_store_dwordx2 v204, v[20:21], s[30:31] offset:704
	s_waitcnt vmcnt(7)
	v_lshlrev_b32_e32 v12, 16, v38
	v_and_b32_e32 v13, 0xffff0000, v38
	v_lshlrev_b32_e32 v14, 16, v39
	v_and_b32_e32 v15, 0xffff0000, v39
	v_mul_f32_e32 v16, 0xbfb8aa3b, v12
	v_mul_f32_e32 v17, 0xbfb8aa3b, v13
	v_mul_f32_e32 v18, 0xbfb8aa3b, v14
	v_mul_f32_e32 v19, 0xbfb8aa3b, v15
	v_exp_f32_e32 v16, v16
	v_exp_f32_e32 v17, v17
	v_exp_f32_e32 v18, v18
	v_exp_f32_e32 v19, v19
	v_lshlrev_b32_e32 v20, 16, v114
	v_and_b32_e32 v21, 0xffff0000, v114
	v_lshlrev_b32_e32 v22, 16, v115
	v_and_b32_e32 v23, 0xffff0000, v115
	v_add_f32_e32 v16, 1.0, v16
	v_add_f32_e32 v17, 1.0, v17
	v_add_f32_e32 v18, 1.0, v18
	v_add_f32_e32 v19, 1.0, v19
	v_rcp_f32_e32 v16, v16
	v_rcp_f32_e32 v17, v17
	v_rcp_f32_e32 v18, v18
	v_rcp_f32_e32 v19, v19
	v_sub_f32_e32 v20, v20, v227
	v_sub_f32_e32 v21, v21, v227
	v_sub_f32_e32 v22, v22, v227
	v_sub_f32_e32 v23, v23, v227
	v_mul_f32_e32 v20, v20, v228
	v_mul_f32_e32 v21, v21, v228
	v_mul_f32_e32 v22, v22, v228
	v_mul_f32_e32 v23, v23, v228
	v_mul_f32_e32 v12, v12, v16
	v_mul_f32_e32 v13, v13, v17
	v_mul_f32_e32 v14, v14, v18
	v_mul_f32_e32 v15, v15, v19
	v_mul_f32_e32 v20, v20, v96
	v_mul_f32_e32 v21, v21, v97
	v_mul_f32_e32 v22, v22, v98
	v_mul_f32_e32 v23, v23, v99
	v_mul_f32_e32 v20, v20, v12
	v_mul_f32_e32 v21, v21, v13
	v_mul_f32_e32 v22, v22, v14
	v_mul_f32_e32 v23, v23, v15
	v_cvt_pk_bf16_f32 v20, v20, v21
	v_cvt_pk_bf16_f32 v21, v22, v23
	global_store_dwordx2 v204, v[20:21], s[30:31] offset:736
	global_load_dwordx2 v[24:25], v205, s[34:35] offset:768
	global_load_dwordx2 v[100:101], v204, s[30:31] offset:768
	global_load_dwordx4 v[68:71], v206, s[28:29] offset:1536
	global_load_dwordx2 v[26:27], v205, s[34:35] offset:800
	global_load_dwordx2 v[102:103], v204, s[30:31] offset:800
	global_load_dwordx4 v[72:75], v206, s[28:29] offset:1600
	global_load_dwordx2 v[28:29], v205, s[34:35] offset:832
	global_load_dwordx2 v[104:105], v204, s[30:31] offset:832
	global_load_dwordx4 v[76:79], v206, s[28:29] offset:1664
	global_load_dwordx2 v[30:31], v205, s[34:35] offset:864
	global_load_dwordx2 v[106:107], v204, s[30:31] offset:864
	global_load_dwordx4 v[80:83], v206, s[28:29] offset:1728
	global_load_dwordx2 v[32:33], v205, s[34:35] offset:896
	global_load_dwordx2 v[108:109], v204, s[30:31] offset:896
	global_load_dwordx4 v[84:87], v206, s[28:29] offset:1792
	global_load_dwordx2 v[34:35], v205, s[34:35] offset:928
	global_load_dwordx2 v[110:111], v204, s[30:31] offset:928
	global_load_dwordx4 v[88:91], v206, s[28:29] offset:1856
	global_load_dwordx2 v[36:37], v205, s[34:35] offset:960
	global_load_dwordx2 v[112:113], v204, s[30:31] offset:960
	global_load_dwordx4 v[92:95], v206, s[28:29] offset:1920
	global_load_dwordx2 v[38:39], v205, s[34:35] offset:992
	global_load_dwordx2 v[114:115], v204, s[30:31] offset:992
	global_load_dwordx4 v[96:99], v206, s[28:29] offset:1984
	s_waitcnt vmcnt(21)
	v_lshlrev_b32_e32 v12, 16, v24
	v_and_b32_e32 v13, 0xffff0000, v24
	v_lshlrev_b32_e32 v14, 16, v25
	v_and_b32_e32 v15, 0xffff0000, v25
	v_mul_f32_e32 v16, 0xbfb8aa3b, v12
	v_mul_f32_e32 v17, 0xbfb8aa3b, v13
	v_mul_f32_e32 v18, 0xbfb8aa3b, v14
	v_mul_f32_e32 v19, 0xbfb8aa3b, v15
	v_exp_f32_e32 v16, v16
	v_exp_f32_e32 v17, v17
	v_exp_f32_e32 v18, v18
	v_exp_f32_e32 v19, v19
	v_lshlrev_b32_e32 v20, 16, v100
	v_and_b32_e32 v21, 0xffff0000, v100
	v_lshlrev_b32_e32 v22, 16, v101
	v_and_b32_e32 v23, 0xffff0000, v101
	v_add_f32_e32 v16, 1.0, v16
	v_add_f32_e32 v17, 1.0, v17
	v_add_f32_e32 v18, 1.0, v18
	v_add_f32_e32 v19, 1.0, v19
	v_rcp_f32_e32 v16, v16
	v_rcp_f32_e32 v17, v17
	v_rcp_f32_e32 v18, v18
	v_rcp_f32_e32 v19, v19
	v_sub_f32_e32 v20, v20, v227
	v_sub_f32_e32 v21, v21, v227
	v_sub_f32_e32 v22, v22, v227
	v_sub_f32_e32 v23, v23, v227
	v_mul_f32_e32 v20, v20, v228
	v_mul_f32_e32 v21, v21, v228
	v_mul_f32_e32 v22, v22, v228
	v_mul_f32_e32 v23, v23, v228
	v_mul_f32_e32 v12, v12, v16
	v_mul_f32_e32 v13, v13, v17
	v_mul_f32_e32 v14, v14, v18
	v_mul_f32_e32 v15, v15, v19
	v_mul_f32_e32 v20, v20, v68
	v_mul_f32_e32 v21, v21, v69
	v_mul_f32_e32 v22, v22, v70
	v_mul_f32_e32 v23, v23, v71
	v_mul_f32_e32 v20, v20, v12
	v_mul_f32_e32 v21, v21, v13
	v_mul_f32_e32 v22, v22, v14
	v_mul_f32_e32 v23, v23, v15
	v_cvt_pk_bf16_f32 v20, v20, v21
	v_cvt_pk_bf16_f32 v21, v22, v23
	global_store_dwordx2 v204, v[20:21], s[30:31] offset:768
	s_waitcnt vmcnt(19)
	v_lshlrev_b32_e32 v12, 16, v26
	v_and_b32_e32 v13, 0xffff0000, v26
	v_lshlrev_b32_e32 v14, 16, v27
	v_and_b32_e32 v15, 0xffff0000, v27
	v_mul_f32_e32 v16, 0xbfb8aa3b, v12
	v_mul_f32_e32 v17, 0xbfb8aa3b, v13
	v_mul_f32_e32 v18, 0xbfb8aa3b, v14
	v_mul_f32_e32 v19, 0xbfb8aa3b, v15
	v_exp_f32_e32 v16, v16
	v_exp_f32_e32 v17, v17
	v_exp_f32_e32 v18, v18
	v_exp_f32_e32 v19, v19
	v_lshlrev_b32_e32 v20, 16, v102
	v_and_b32_e32 v21, 0xffff0000, v102
	v_lshlrev_b32_e32 v22, 16, v103
	v_and_b32_e32 v23, 0xffff0000, v103
	v_add_f32_e32 v16, 1.0, v16
	v_add_f32_e32 v17, 1.0, v17
	v_add_f32_e32 v18, 1.0, v18
	v_add_f32_e32 v19, 1.0, v19
	v_rcp_f32_e32 v16, v16
	v_rcp_f32_e32 v17, v17
	v_rcp_f32_e32 v18, v18
	v_rcp_f32_e32 v19, v19
	v_sub_f32_e32 v20, v20, v227
	v_sub_f32_e32 v21, v21, v227
	v_sub_f32_e32 v22, v22, v227
	v_sub_f32_e32 v23, v23, v227
	v_mul_f32_e32 v20, v20, v228
	v_mul_f32_e32 v21, v21, v228
	v_mul_f32_e32 v22, v22, v228
	v_mul_f32_e32 v23, v23, v228
	v_mul_f32_e32 v12, v12, v16
	v_mul_f32_e32 v13, v13, v17
	v_mul_f32_e32 v14, v14, v18
	v_mul_f32_e32 v15, v15, v19
	v_mul_f32_e32 v20, v20, v72
	v_mul_f32_e32 v21, v21, v73
	v_mul_f32_e32 v22, v22, v74
	v_mul_f32_e32 v23, v23, v75
	v_mul_f32_e32 v20, v20, v12
	v_mul_f32_e32 v21, v21, v13
	v_mul_f32_e32 v22, v22, v14
	v_mul_f32_e32 v23, v23, v15
	v_cvt_pk_bf16_f32 v20, v20, v21
	v_cvt_pk_bf16_f32 v21, v22, v23
	global_store_dwordx2 v204, v[20:21], s[30:31] offset:800
	s_waitcnt vmcnt(17)
	v_lshlrev_b32_e32 v12, 16, v28
	v_and_b32_e32 v13, 0xffff0000, v28
	v_lshlrev_b32_e32 v14, 16, v29
	v_and_b32_e32 v15, 0xffff0000, v29
	v_mul_f32_e32 v16, 0xbfb8aa3b, v12
	v_mul_f32_e32 v17, 0xbfb8aa3b, v13
	v_mul_f32_e32 v18, 0xbfb8aa3b, v14
	v_mul_f32_e32 v19, 0xbfb8aa3b, v15
	v_exp_f32_e32 v16, v16
	v_exp_f32_e32 v17, v17
	v_exp_f32_e32 v18, v18
	v_exp_f32_e32 v19, v19
	v_lshlrev_b32_e32 v20, 16, v104
	v_and_b32_e32 v21, 0xffff0000, v104
	v_lshlrev_b32_e32 v22, 16, v105
	v_and_b32_e32 v23, 0xffff0000, v105
	v_add_f32_e32 v16, 1.0, v16
	v_add_f32_e32 v17, 1.0, v17
	v_add_f32_e32 v18, 1.0, v18
	v_add_f32_e32 v19, 1.0, v19
	v_rcp_f32_e32 v16, v16
	v_rcp_f32_e32 v17, v17
	v_rcp_f32_e32 v18, v18
	v_rcp_f32_e32 v19, v19
	v_sub_f32_e32 v20, v20, v227
	v_sub_f32_e32 v21, v21, v227
	v_sub_f32_e32 v22, v22, v227
	v_sub_f32_e32 v23, v23, v227
	v_mul_f32_e32 v20, v20, v228
	v_mul_f32_e32 v21, v21, v228
	v_mul_f32_e32 v22, v22, v228
	v_mul_f32_e32 v23, v23, v228
	v_mul_f32_e32 v12, v12, v16
	v_mul_f32_e32 v13, v13, v17
	v_mul_f32_e32 v14, v14, v18
	v_mul_f32_e32 v15, v15, v19
	v_mul_f32_e32 v20, v20, v76
	v_mul_f32_e32 v21, v21, v77
	v_mul_f32_e32 v22, v22, v78
	v_mul_f32_e32 v23, v23, v79
	v_mul_f32_e32 v20, v20, v12
	v_mul_f32_e32 v21, v21, v13
	v_mul_f32_e32 v22, v22, v14
	v_mul_f32_e32 v23, v23, v15
	v_cvt_pk_bf16_f32 v20, v20, v21
	v_cvt_pk_bf16_f32 v21, v22, v23
	global_store_dwordx2 v204, v[20:21], s[30:31] offset:832
	s_waitcnt vmcnt(15)
	v_lshlrev_b32_e32 v12, 16, v30
	v_and_b32_e32 v13, 0xffff0000, v30
	v_lshlrev_b32_e32 v14, 16, v31
	v_and_b32_e32 v15, 0xffff0000, v31
	v_mul_f32_e32 v16, 0xbfb8aa3b, v12
	v_mul_f32_e32 v17, 0xbfb8aa3b, v13
	v_mul_f32_e32 v18, 0xbfb8aa3b, v14
	v_mul_f32_e32 v19, 0xbfb8aa3b, v15
	v_exp_f32_e32 v16, v16
	v_exp_f32_e32 v17, v17
	v_exp_f32_e32 v18, v18
	v_exp_f32_e32 v19, v19
	v_lshlrev_b32_e32 v20, 16, v106
	v_and_b32_e32 v21, 0xffff0000, v106
	v_lshlrev_b32_e32 v22, 16, v107
	v_and_b32_e32 v23, 0xffff0000, v107
	v_add_f32_e32 v16, 1.0, v16
	v_add_f32_e32 v17, 1.0, v17
	v_add_f32_e32 v18, 1.0, v18
	v_add_f32_e32 v19, 1.0, v19
	v_rcp_f32_e32 v16, v16
	v_rcp_f32_e32 v17, v17
	v_rcp_f32_e32 v18, v18
	v_rcp_f32_e32 v19, v19
	v_sub_f32_e32 v20, v20, v227
	v_sub_f32_e32 v21, v21, v227
	v_sub_f32_e32 v22, v22, v227
	v_sub_f32_e32 v23, v23, v227
	v_mul_f32_e32 v20, v20, v228
	v_mul_f32_e32 v21, v21, v228
	v_mul_f32_e32 v22, v22, v228
	v_mul_f32_e32 v23, v23, v228
	v_mul_f32_e32 v12, v12, v16
	v_mul_f32_e32 v13, v13, v17
	v_mul_f32_e32 v14, v14, v18
	v_mul_f32_e32 v15, v15, v19
	v_mul_f32_e32 v20, v20, v80
	v_mul_f32_e32 v21, v21, v81
	v_mul_f32_e32 v22, v22, v82
	v_mul_f32_e32 v23, v23, v83
	v_mul_f32_e32 v20, v20, v12
	v_mul_f32_e32 v21, v21, v13
	v_mul_f32_e32 v22, v22, v14
	v_mul_f32_e32 v23, v23, v15
	v_cvt_pk_bf16_f32 v20, v20, v21
	v_cvt_pk_bf16_f32 v21, v22, v23
	global_store_dwordx2 v204, v[20:21], s[30:31] offset:864
	s_waitcnt vmcnt(13)
	v_lshlrev_b32_e32 v12, 16, v32
	v_and_b32_e32 v13, 0xffff0000, v32
	v_lshlrev_b32_e32 v14, 16, v33
	v_and_b32_e32 v15, 0xffff0000, v33
	v_mul_f32_e32 v16, 0xbfb8aa3b, v12
	v_mul_f32_e32 v17, 0xbfb8aa3b, v13
	v_mul_f32_e32 v18, 0xbfb8aa3b, v14
	v_mul_f32_e32 v19, 0xbfb8aa3b, v15
	v_exp_f32_e32 v16, v16
	v_exp_f32_e32 v17, v17
	v_exp_f32_e32 v18, v18
	v_exp_f32_e32 v19, v19
	v_lshlrev_b32_e32 v20, 16, v108
	v_and_b32_e32 v21, 0xffff0000, v108
	v_lshlrev_b32_e32 v22, 16, v109
	v_and_b32_e32 v23, 0xffff0000, v109
	v_add_f32_e32 v16, 1.0, v16
	v_add_f32_e32 v17, 1.0, v17
	v_add_f32_e32 v18, 1.0, v18
	v_add_f32_e32 v19, 1.0, v19
	v_rcp_f32_e32 v16, v16
	v_rcp_f32_e32 v17, v17
	v_rcp_f32_e32 v18, v18
	v_rcp_f32_e32 v19, v19
	v_sub_f32_e32 v20, v20, v227
	v_sub_f32_e32 v21, v21, v227
	v_sub_f32_e32 v22, v22, v227
	v_sub_f32_e32 v23, v23, v227
	v_mul_f32_e32 v20, v20, v228
	v_mul_f32_e32 v21, v21, v228
	v_mul_f32_e32 v22, v22, v228
	v_mul_f32_e32 v23, v23, v228
	v_mul_f32_e32 v12, v12, v16
	v_mul_f32_e32 v13, v13, v17
	v_mul_f32_e32 v14, v14, v18
	v_mul_f32_e32 v15, v15, v19
	v_mul_f32_e32 v20, v20, v84
	v_mul_f32_e32 v21, v21, v85
	v_mul_f32_e32 v22, v22, v86
	v_mul_f32_e32 v23, v23, v87
	v_mul_f32_e32 v20, v20, v12
	v_mul_f32_e32 v21, v21, v13
	v_mul_f32_e32 v22, v22, v14
	v_mul_f32_e32 v23, v23, v15
	v_cvt_pk_bf16_f32 v20, v20, v21
	v_cvt_pk_bf16_f32 v21, v22, v23
	global_store_dwordx2 v204, v[20:21], s[30:31] offset:896
	s_waitcnt vmcnt(11)
	v_lshlrev_b32_e32 v12, 16, v34
	v_and_b32_e32 v13, 0xffff0000, v34
	v_lshlrev_b32_e32 v14, 16, v35
	v_and_b32_e32 v15, 0xffff0000, v35
	v_mul_f32_e32 v16, 0xbfb8aa3b, v12
	v_mul_f32_e32 v17, 0xbfb8aa3b, v13
	v_mul_f32_e32 v18, 0xbfb8aa3b, v14
	v_mul_f32_e32 v19, 0xbfb8aa3b, v15
	v_exp_f32_e32 v16, v16
	v_exp_f32_e32 v17, v17
	v_exp_f32_e32 v18, v18
	v_exp_f32_e32 v19, v19
	v_lshlrev_b32_e32 v20, 16, v110
	v_and_b32_e32 v21, 0xffff0000, v110
	v_lshlrev_b32_e32 v22, 16, v111
	v_and_b32_e32 v23, 0xffff0000, v111
	v_add_f32_e32 v16, 1.0, v16
	v_add_f32_e32 v17, 1.0, v17
	v_add_f32_e32 v18, 1.0, v18
	v_add_f32_e32 v19, 1.0, v19
	v_rcp_f32_e32 v16, v16
	v_rcp_f32_e32 v17, v17
	v_rcp_f32_e32 v18, v18
	v_rcp_f32_e32 v19, v19
	v_sub_f32_e32 v20, v20, v227
	v_sub_f32_e32 v21, v21, v227
	v_sub_f32_e32 v22, v22, v227
	v_sub_f32_e32 v23, v23, v227
	v_mul_f32_e32 v20, v20, v228
	v_mul_f32_e32 v21, v21, v228
	v_mul_f32_e32 v22, v22, v228
	v_mul_f32_e32 v23, v23, v228
	v_mul_f32_e32 v12, v12, v16
	v_mul_f32_e32 v13, v13, v17
	v_mul_f32_e32 v14, v14, v18
	v_mul_f32_e32 v15, v15, v19
	v_mul_f32_e32 v20, v20, v88
	v_mul_f32_e32 v21, v21, v89
	v_mul_f32_e32 v22, v22, v90
	v_mul_f32_e32 v23, v23, v91
	v_mul_f32_e32 v20, v20, v12
	v_mul_f32_e32 v21, v21, v13
	v_mul_f32_e32 v22, v22, v14
	v_mul_f32_e32 v23, v23, v15
	v_cvt_pk_bf16_f32 v20, v20, v21
	v_cvt_pk_bf16_f32 v21, v22, v23
	global_store_dwordx2 v204, v[20:21], s[30:31] offset:928
	s_waitcnt vmcnt(9)
	v_lshlrev_b32_e32 v12, 16, v36
	v_and_b32_e32 v13, 0xffff0000, v36
	v_lshlrev_b32_e32 v14, 16, v37
	v_and_b32_e32 v15, 0xffff0000, v37
	v_mul_f32_e32 v16, 0xbfb8aa3b, v12
	v_mul_f32_e32 v17, 0xbfb8aa3b, v13
	v_mul_f32_e32 v18, 0xbfb8aa3b, v14
	v_mul_f32_e32 v19, 0xbfb8aa3b, v15
	v_exp_f32_e32 v16, v16
	v_exp_f32_e32 v17, v17
	v_exp_f32_e32 v18, v18
	v_exp_f32_e32 v19, v19
	v_lshlrev_b32_e32 v20, 16, v112
	v_and_b32_e32 v21, 0xffff0000, v112
	v_lshlrev_b32_e32 v22, 16, v113
	v_and_b32_e32 v23, 0xffff0000, v113
	v_add_f32_e32 v16, 1.0, v16
	v_add_f32_e32 v17, 1.0, v17
	v_add_f32_e32 v18, 1.0, v18
	v_add_f32_e32 v19, 1.0, v19
	v_rcp_f32_e32 v16, v16
	v_rcp_f32_e32 v17, v17
	v_rcp_f32_e32 v18, v18
	v_rcp_f32_e32 v19, v19
	v_sub_f32_e32 v20, v20, v227
	v_sub_f32_e32 v21, v21, v227
	v_sub_f32_e32 v22, v22, v227
	v_sub_f32_e32 v23, v23, v227
	v_mul_f32_e32 v20, v20, v228
	v_mul_f32_e32 v21, v21, v228
	v_mul_f32_e32 v22, v22, v228
	v_mul_f32_e32 v23, v23, v228
	v_mul_f32_e32 v12, v12, v16
	v_mul_f32_e32 v13, v13, v17
	v_mul_f32_e32 v14, v14, v18
	v_mul_f32_e32 v15, v15, v19
	v_mul_f32_e32 v20, v20, v92
	v_mul_f32_e32 v21, v21, v93
	v_mul_f32_e32 v22, v22, v94
	v_mul_f32_e32 v23, v23, v95
	v_mul_f32_e32 v20, v20, v12
	v_mul_f32_e32 v21, v21, v13
	v_mul_f32_e32 v22, v22, v14
	v_mul_f32_e32 v23, v23, v15
	v_cvt_pk_bf16_f32 v20, v20, v21
	v_cvt_pk_bf16_f32 v21, v22, v23
	global_store_dwordx2 v204, v[20:21], s[30:31] offset:960
	s_waitcnt vmcnt(7)
	v_lshlrev_b32_e32 v12, 16, v38
	v_and_b32_e32 v13, 0xffff0000, v38
	v_lshlrev_b32_e32 v14, 16, v39
	v_and_b32_e32 v15, 0xffff0000, v39
	v_mul_f32_e32 v16, 0xbfb8aa3b, v12
	v_mul_f32_e32 v17, 0xbfb8aa3b, v13
	v_mul_f32_e32 v18, 0xbfb8aa3b, v14
	v_mul_f32_e32 v19, 0xbfb8aa3b, v15
	v_exp_f32_e32 v16, v16
	v_exp_f32_e32 v17, v17
	v_exp_f32_e32 v18, v18
	v_exp_f32_e32 v19, v19
	v_lshlrev_b32_e32 v20, 16, v114
	v_and_b32_e32 v21, 0xffff0000, v114
	v_lshlrev_b32_e32 v22, 16, v115
	v_and_b32_e32 v23, 0xffff0000, v115
	v_add_f32_e32 v16, 1.0, v16
	v_add_f32_e32 v17, 1.0, v17
	v_add_f32_e32 v18, 1.0, v18
	v_add_f32_e32 v19, 1.0, v19
	v_rcp_f32_e32 v16, v16
	v_rcp_f32_e32 v17, v17
	v_rcp_f32_e32 v18, v18
	v_rcp_f32_e32 v19, v19
	v_sub_f32_e32 v20, v20, v227
	v_sub_f32_e32 v21, v21, v227
	v_sub_f32_e32 v22, v22, v227
	v_sub_f32_e32 v23, v23, v227
	v_mul_f32_e32 v20, v20, v228
	v_mul_f32_e32 v21, v21, v228
	v_mul_f32_e32 v22, v22, v228
	v_mul_f32_e32 v23, v23, v228
	v_mul_f32_e32 v12, v12, v16
	v_mul_f32_e32 v13, v13, v17
	v_mul_f32_e32 v14, v14, v18
	v_mul_f32_e32 v15, v15, v19
	v_mul_f32_e32 v20, v20, v96
	v_mul_f32_e32 v21, v21, v97
	v_mul_f32_e32 v22, v22, v98
	v_mul_f32_e32 v23, v23, v99
	v_mul_f32_e32 v20, v20, v12
	v_mul_f32_e32 v21, v21, v13
	v_mul_f32_e32 v22, v22, v14
	v_mul_f32_e32 v23, v23, v15
	v_cvt_pk_bf16_f32 v20, v20, v21
	v_cvt_pk_bf16_f32 v21, v22, v23
	global_store_dwordx2 v204, v[20:21], s[30:31] offset:992
	s_waitcnt vmcnt(0)
	s_add_i32 s6, s6, 1
	s_cmp_lt_i32 s6, 2
	s_cbranch_scc1 .Lintra_unit
	s_branch .LBB0_748

.Lb_step:
	s_waitcnt vmcnt(0)
	ds_write_b128 v114, v[40:43] offset:0
	ds_write_b128 v114, v[44:47] offset:1152
	ds_write_b128 v114, v[48:51] offset:2304
	ds_write_b128 v114, v[52:55] offset:3456
	ds_read_b32 v100, v110 offset:76
	ds_read_b32 v101, v110 offset:72
	ds_read_b32 v102, v110 offset:68
	ds_read_b32 v103, v110 offset:64
	ds_read_b32 v104, v110 offset:12
	ds_read_b32 v105, v110 offset:8
	ds_read_b32 v106, v110 offset:4
	ds_read_b32 v107, v110 offset:0
	ds_read_b32 v124, v110 offset:140
	ds_read_b32 v125, v110 offset:136
	ds_read_b32 v126, v110 offset:132
	ds_read_b32 v127, v110 offset:128
	ds_read_b32 v128, v110 offset:76
	ds_read_b32 v129, v110 offset:72
	ds_read_b32 v130, v110 offset:68
	ds_read_b32 v131, v110 offset:64
	v_add_u32_e32 v110, 0xffffff80, v110
	v_mfma_f32_16x16x32_bf16 v[92:95], v[24:27], v[16:19], 0
	v_mfma_f32_16x16x32_bf16 v[96:99], v[32:35], v[16:19], 0
	v_mfma_f32_16x16x32_bf16 v[92:95], v[28:31], v[20:23], v[92:95]
	v_mfma_f32_16x16x32_bf16 v[96:99], v[36:39], v[20:23], v[96:99]
	v_mfma_f32_16x16x32_bf16 v[132:135], v[24:27], v[160:163], 0
	v_mfma_f32_16x16x32_bf16 v[136:139], v[32:35], v[160:163], 0
	v_mfma_f32_16x16x32_bf16 v[132:135], v[28:31], v[164:167], v[132:135]
	v_mfma_f32_16x16x32_bf16 v[136:139], v[36:39], v[164:167], v[136:139]
	s_add_i32 s1, s10, 1
	s_cmp_ge_i32 s1, s9
	s_cbranch_scc1 .Lb_last
	s_mov_b32 s49, 0
	s_add_i32 s3, s11, 2
	s_lshl_b32 s1, 0x12000, s13
	s_mul_i32 s0, s3, s1
	s_add_u32 s16, s24, s0
	s_addc_u32 s17, s25, 0
	s_add_u32 s20, s26, s0
	s_addc_u32 s21, s27, 0
	s_add_i32 s2, s3, 1
	s_cmp_gt_i32 s2, s12
	s_cselect_b32 s2, s3, s2
	s_mul_i32 s0, s2, s1
	s_add_u32 s18, s24, s0
	s_addc_u32 s19, s25, 0
	s_add_u32 s22, s26, s0
	s_addc_u32 s23, s27, 0
	global_load_dwordx4 v[24:27], v111, s[16:17]
	global_load_dwordx4 v[28:31], v111, s[16:17] offset:64
	global_load_dwordx4 v[32:35], v111, s[18:19]
	global_load_dwordx4 v[36:39], v111, s[18:19] offset:64
	global_load_dwordx4 v[40:43], v112, s[20:21]
	global_load_dwordx4 v[44:47], v113, s[20:21]
	global_load_dwordx4 v[48:51], v112, s[22:23]
	global_load_dwordx4 v[52:55], v113, s[22:23]
	s_branch .Lb_compute

.Lb_norescA:
	v_pk_add_f32 v[92:93], v[92:93], v[108:109] op_sel_hi:[1,0] neg_lo:[0,1] neg_hi:[0,1]
	v_pk_add_f32 v[94:95], v[94:95], v[108:109] op_sel_hi:[1,0] neg_lo:[0,1] neg_hi:[0,1]
	v_pk_add_f32 v[96:97], v[96:97], v[108:109] op_sel_hi:[1,0] neg_lo:[0,1] neg_hi:[0,1]
	v_pk_add_f32 v[98:99], v[98:99], v[108:109] op_sel_hi:[1,0] neg_lo:[0,1] neg_hi:[0,1]
	v_exp_f32_e32 v92, v92
	v_exp_f32_e32 v93, v93
	v_exp_f32_e32 v94, v94
	v_exp_f32_e32 v95, v95
	v_exp_f32_e32 v96, v96
	v_exp_f32_e32 v97, v97
	v_exp_f32_e32 v98, v98
	v_exp_f32_e32 v99, v99
	s_nop 0
	v_pk_add_f32 v[100:101], v[92:93], v[94:95]
	v_pk_add_f32 v[100:101], v[100:101], v[96:97]
	v_pk_add_f32 v[100:101], v[100:101], v[98:99]
	v_add_f32_e32 v100, v100, v101
	v_add_f32_e32 v109, v109, v100
	v_cvt_pk_bf16_f32 v92, v92, v93
	v_cvt_pk_bf16_f32 v93, v94, v95
	v_cvt_pk_bf16_f32 v94, v96, v97
	v_cvt_pk_bf16_f32 v95, v98, v99
	s_waitcnt lgkmcnt(0)
	v_lshl_or_b32 v56, v74, 16, v56
	v_lshl_or_b32 v57, v75, 16, v57
	v_lshl_or_b32 v58, v76, 16, v58
	v_lshl_or_b32 v59, v77, 16, v59
	v_lshl_or_b32 v60, v78, 16, v60
	v_lshl_or_b32 v61, v79, 16, v61
	v_lshl_or_b32 v62, v80, 16, v62
	v_lshl_or_b32 v63, v81, 16, v63
	v_lshl_or_b32 v66, v82, 16, v66
	v_lshl_or_b32 v67, v83, 16, v67
	v_lshl_or_b32 v68, v84, 16, v68
	v_lshl_or_b32 v69, v85, 16, v69
	v_lshl_or_b32 v70, v86, 16, v70
	v_lshl_or_b32 v71, v87, 16, v71
	v_lshl_or_b32 v72, v88, 16, v72
	v_lshl_or_b32 v73, v89, 16, v73
	s_nop 1
	v_mfma_f32_16x16x32_bf16 v[0:3], v[56:59], v[92:95], v[0:3]
	v_mfma_f32_16x16x32_bf16 v[4:7], v[60:63], v[92:95], v[4:7]
	v_mfma_f32_16x16x32_bf16 v[8:11], v[66:69], v[92:95], v[8:11]
	v_mfma_f32_16x16x32_bf16 v[12:15], v[70:73], v[92:95], v[12:15]
	v_pk_fma_f32 v[132:133], v[132:133], s[40:41], v[124:125] op_sel_hi:[1,0,1]
	v_pk_fma_f32 v[134:135], v[134:135], s[40:41], v[126:127] op_sel_hi:[1,0,1]
	v_pk_fma_f32 v[136:137], v[136:137], s[40:41], v[128:129] op_sel_hi:[1,0,1]
	v_pk_fma_f32 v[138:139], v[138:139], s[40:41], v[130:131] op_sel_hi:[1,0,1]
	v_max3_f32 v124, v132, v133, v134
	v_max3_f32 v125, v135, v136, v137
	v_max3_f32 v124, v124, v138, v139
	v_max_f32_e32 v124, v124, v125
	v_mov_b32_e32 v125, v124
	s_nop 1
	v_permlane16_swap_b32_e32 v125, v124
	v_max_f32_e32 v124, v124, v125
	v_mov_b32_e32 v125, v124
	s_nop 1
	v_permlane32_swap_b32_e32 v125, v124
	v_max_f32_e32 v126, v124, v125
	v_cmp_gt_f32_e32 vcc, v126, v168
	s_cbranch_vccz .Lb_norescB
	v_max_f32_e32 v126, v168, v126
	v_sub_f32_e32 v124, v168, v126
	v_exp_f32_e32 v124, v124
	v_mov_b32_e32 v168, v126
	s_nop 0
	v_pk_mul_f32 v[144:145], v[144:145], v[124:125] op_sel_hi:[1,0]
	v_pk_mul_f32 v[146:147], v[146:147], v[124:125] op_sel_hi:[1,0]
	v_pk_mul_f32 v[148:149], v[148:149], v[124:125] op_sel_hi:[1,0]
	v_pk_mul_f32 v[150:151], v[150:151], v[124:125] op_sel_hi:[1,0]
	v_pk_mul_f32 v[152:153], v[152:153], v[124:125] op_sel_hi:[1,0]
	v_pk_mul_f32 v[154:155], v[154:155], v[124:125] op_sel_hi:[1,0]
	v_pk_mul_f32 v[156:157], v[156:157], v[124:125] op_sel_hi:[1,0]
	v_pk_mul_f32 v[158:159], v[158:159], v[124:125] op_sel_hi:[1,0]
	v_mul_f32_e32 v169, v169, v124
.Lb_norescB:
	v_pk_add_f32 v[132:133], v[132:133], v[168:169] op_sel_hi:[1,0] neg_lo:[0,1] neg_hi:[0,1]
	v_pk_add_f32 v[134:135], v[134:135], v[168:169] op_sel_hi:[1,0] neg_lo:[0,1] neg_hi:[0,1]
	v_pk_add_f32 v[136:137], v[136:137], v[168:169] op_sel_hi:[1,0] neg_lo:[0,1] neg_hi:[0,1]
	v_pk_add_f32 v[138:139], v[138:139], v[168:169] op_sel_hi:[1,0] neg_lo:[0,1] neg_hi:[0,1]
	v_exp_f32_e32 v132, v132
	v_exp_f32_e32 v133, v133
	v_exp_f32_e32 v134, v134
	v_exp_f32_e32 v135, v135
	v_exp_f32_e32 v136, v136
	v_exp_f32_e32 v137, v137
	v_exp_f32_e32 v138, v138
	v_exp_f32_e32 v139, v139
	s_nop 0
	v_pk_add_f32 v[124:125], v[132:133], v[134:135]
	v_pk_add_f32 v[124:125], v[124:125], v[136:137]
	v_pk_add_f32 v[124:125], v[124:125], v[138:139]
	v_add_f32_e32 v124, v124, v125
	v_add_f32_e32 v169, v169, v124
	v_cvt_pk_bf16_f32 v132, v132, v133
	v_cvt_pk_bf16_f32 v133, v134, v135
	v_cvt_pk_bf16_f32 v134, v136, v137
	v_cvt_pk_bf16_f32 v135, v138, v139
	s_nop 1
	v_mfma_f32_16x16x32_bf16 v[144:147], v[56:59], v[132:135], v[144:147]
	v_mfma_f32_16x16x32_bf16 v[148:151], v[60:63], v[132:135], v[148:151]
	v_mfma_f32_16x16x32_bf16 v[152:155], v[66:69], v[132:135], v[152:155]
	v_mfma_f32_16x16x32_bf16 v[156:159], v[70:73], v[132:135], v[156:159]
	s_cmp_eq_u32 s49, 0
	s_cbranch_scc0 .Lb_epilogue
	s_add_i32 s10, s10, 1
	s_add_i32 s11, s11, 2
	s_branch .Lb_step
